# scan phase: h_loc / p_cum packed into one dword per element (one store instead of two 2-byte stores); fix-up reads the interleaved array
# speedup vs baseline: 1.0066x; 1.0066x over previous
; __device__ __forceinline__ void scan_phase(KP p, int l, LAS unsigned char* lds) {
;     ...
;         LDS_WAIT();
;         {
;             const int ch = hc0 + lane;
; #pragma unroll
;             for (int k = 0; k < 4; ++k) CST[k * 64 + lane] = p->in[14][(size_t)(l * 4 + k) * D + ch];
;             CST[4 * 64 + lane] = p->in[15][l * D + ch]; CST[5 * 64 + lane] = p->in[17][l * D + ch]; CST[6 * 64 + lane] = p->in[19][l * D + ch]; CST[7 * 64 + lane] = SP[ch];
;         }
;         bf16x8 Wa[4][2], Wx[4][2];
; #pragma unroll
;         for (int n = 0; n < 4; ++n)
; #pragma unroll
;             for (int s = 0; s < 2; ++s) { const size_t o = (size_t)head * 4096 + (16 * n + fr) * 64 + 32 * s + 8 * fq;
;                 Wa[n][s] = *(const bf16x8*)((const bf16_t*)(p->ws + WS_RGA) + o); Wx[n][s] = *(const bf16x8*)((const bf16_t*)(p->ws + WS_RGX) + o); }
;         if (ck < 128) {
;             const int b = ck >> 4, q = ck & 15, tile0 = b * 129 + 8 * q;
;             float Hc[4], Pc[4];
; #pragma unroll
;             for (int n = 0; n < 4; ++n) { Hc[n] = 0.f; Pc[n] = 1.f; }
;             for (int tt = 0; tt < 8; tt += 2) scan_tiles<2>(p, l, P, HLOC, PCUM, XC, CST, Wa, Wx, b, hc0, (tile0 + tt) * 16, lane, fr, fq, Hc, Pc);
;             if (q == 15) scan_tiles<1>(p, l, P, HLOC, PCUM, XC, CST, Wa, Wx, b, hc0, (tile0 + 8) * 16, lane, fr, fq, Hc, Pc);
;             if (fq == 0) {
; #pragma unroll
;                 for (int n = 0; n < 4; ++n) { const int ch = hc0 + 16 * n + fr; SUMM[(size_t)ck * 2 * D + ch] = Pc[n]; SUMM[(size_t)ck * 2 * D + D + ch] = Hc[n]; } }
;         } else {
;             const int m0 = (1032 + (ck - 128)) * 16;
;             LDS_WAIT();
;             {   const int rr = lane >> 2, cb = lane & 3, cl = cb * 16, m = m0 + rr, sb = m - MP;
;                 float xv[4][16];
;                 const float* st = p->in[3] + ((size_t)(l * MS + sb) * 3) * D + hc0 + cl;
; #pragma unroll
;                 for (int k = 0; k < 3; ++k)
; #pragma unroll
;                     for (int e = 0; e < 16; e += 4) { const f32x4 v = *(const f32x4*)(st + (size_t)k * D + e); xv[k][e] = v[0]; xv[k][e + 1] = v[1]; xv[k][e + 2] = v[2]; xv[k][e + 3] = v[3]; }
;                 const bf16_t* src = P + (size_t)m * DP + C_XR + hc0 + cl;
;                 float f0[8], f1[8]; unpack8(*(const u32x4*)src, f0); unpack8(*(const u32x4*)(src + 8), f1);
; #pragma unroll
.LBB0_331:
	s_and_b32 s16, s54, 15
	s_waitcnt lgkmcnt(0)
	s_lshl_b32 s75, s16, 6
	s_load_dwordx4 s[12:15], s[58:59], 0x70
	s_load_dwordx2 s[10:11], s[58:59], 0x88
	s_load_dwordx2 s[18:19], s[58:59], 0x98
	s_waitcnt vmcnt(1)
	v_or_b32_e32 v6, s75, v205
	v_lshlrev_b32_e32 v0, 2, v6
	s_waitcnt vmcnt(0) lgkmcnt(0)
	v_lshl_add_u64 v[2:3], s[12:13], 0, v[0:1]
	v_lshl_add_u64 v[2:3], v[2:3], 0, s[68:69]
	v_add_co_u32_e32 v4, vcc, s43, v2
	global_load_dword v7, v[2:3], off
	s_nop 0
	v_addc_co_u32_e32 v5, vcc, 0, v3, vcc
	global_load_dword v8, v[4:5], off offset:-4096
	v_add_co_u32_e32 v2, vcc, s23, v2
	global_load_dword v4, v[4:5], off
	s_nop 0
	v_addc_co_u32_e32 v3, vcc, 0, v3, vcc
	global_load_dword v2, v[2:3], off
	v_mov_b32_e32 v3, v1
	s_ashr_i32 s74, s54, 4
	s_cmpk_gt_i32 s74, 0x7f
	v_add_u32_e32 v241, v232, v231
	s_waitcnt vmcnt(2)
	ds_write2st64_b32 v225, v7, v8 offset0:34 offset1:35
	s_waitcnt vmcnt(0)
	ds_write2st64_b32 v225, v4, v2 offset0:36 offset1:37
	v_or_b32_e32 v2, s77, v6
	v_lshlrev_b64 v[2:3], 2, v[2:3]
	v_lshl_add_u64 v[4:5], s[14:15], 0, v[2:3]
	global_load_dword v6, v[4:5], off
	v_lshl_add_u64 v[4:5], s[10:11], 0, v[2:3]
	global_load_dword v4, v[4:5], off
	v_lshl_add_u64 v[2:3], s[18:19], 0, v[2:3]
	s_mov_b64 s[10:11], -1
	s_waitcnt vmcnt(0)
	ds_write2st64_b32 v225, v6, v4 offset0:38 offset1:39
	global_load_dword v2, v[2:3], off
	s_nop 0
	global_load_dword v0, v0, s[66:67]
	s_waitcnt vmcnt(0)
	ds_write2st64_b32 v225, v2, v0 offset0:40 offset1:41
	v_lshl_or_b32 v0, s16, 13, v238
	v_or_b32_e32 v2, 64, v0
	global_load_dwordx4 v[34:37], v0, s[70:71]
	global_load_dwordx4 v[38:41], v0, s[72:73]
	global_load_dwordx4 v[10:13], v2, s[70:71]
	global_load_dwordx4 v[14:17], v2, s[72:73]
	v_or_b32_e32 v2, 0x800, v0
	global_load_dwordx4 v[42:45], v2, s[70:71]
	global_load_dwordx4 v[46:49], v2, s[72:73]
	v_or_b32_e32 v2, 0x840, v0
	global_load_dwordx4 v[22:25], v2, s[70:71]
	global_load_dwordx4 v[26:29], v2, s[72:73]
	v_or_b32_e32 v2, 0x1000, v0
	global_load_dwordx4 v[50:53], v2, s[70:71]
	global_load_dwordx4 v[54:57], v2, s[72:73]
	v_or_b32_e32 v2, 0x1040, v0
	global_load_dwordx4 v[30:33], v2, s[70:71]
	global_load_dwordx4 v[18:21], v2, s[72:73]
	v_or_b32_e32 v2, 0x1800, v0
	v_or_b32_e32 v0, 0x1840, v0
	global_load_dwordx4 v[62:65], v2, s[70:71]
	global_load_dwordx4 v[58:61], v2, s[72:73]
	global_load_dwordx4 v[6:9], v0, s[70:71]
	s_nop 0
	global_load_dwordx4 v[2:5], v0, s[72:73]
	v_lshlrev_b32_e32 v0, 1, v206
	s_cbranch_scc0 .LBB0_333
	s_waitcnt lgkmcnt(0)
	s_load_dwordx4 s[12:15], s[58:59], 0x18
	s_and_b32 s10, s54, -16
	s_add_i32 s11, s10, 0x3880
	v_or_b32_e32 v106, s11, v226
	v_add_u32_e32 v126, s78, v106
	s_waitcnt lgkmcnt(0)
	v_mov_b64_e32 v[66:67], s[12:13]
	v_mad_i64_i32 v[66:67], s[12:13], v126, s23, v[66:67]
	s_lshl_b32 s16, s75, 2
	v_lshl_add_u64 v[66:67], v[66:67], 0, s[16:17]
	v_lshlrev_b32_e32 v122, 2, v206
	v_mov_b32_e32 v123, v1
	v_lshl_add_u64 v[70:71], v[66:67], 0, v[122:123]
	v_add_co_u32_e32 v78, vcc, s43, v70
	v_lshl_add_u64 v[72:73], v[70:71], 0, s[28:29]
	s_nop 0
	v_addc_co_u32_e32 v79, vcc, 0, v71, vcc
	global_load_dwordx4 v[66:69], v[70:71], off offset:48
	global_load_dwordx4 v[82:85], v[70:71], off offset:32
	global_load_dwordx4 v[94:97], v[70:71], off offset:16
	global_load_dwordx4 v[110:113], v[70:71], off
	global_load_dwordx4 v[114:117], v[78:79], off offset:-4096
	global_load_dwordx4 v[74:77], v[72:73], off offset:48
	global_load_dwordx4 v[90:93], v[72:73], off offset:32
	global_load_dwordx4 v[102:105], v[72:73], off offset:16
	v_lshl_add_u64 v[80:81], v[70:71], 0, s[30:31]
	global_load_dwordx4 v[118:121], v[78:79], off
	global_load_dwordx4 v[70:73], v[80:81], off offset:48
	global_load_dwordx4 v[86:89], v[80:81], off offset:32
	global_load_dwordx4 v[98:101], v[80:81], off offset:16
	v_mov_b64_e32 v[78:79], s[60:61]
	v_mad_u64_u32 v[78:79], s[12:13], v106, s33, v[78:79]
	s_lshl_b32 s12, s75, 1
	s_mov_b32 s13, s17
	v_lshl_add_u64 v[78:79], v[78:79], 0, s[12:13]
	v_lshl_add_u64 v[78:79], v[78:79], 0, v[0:1]
	v_lshl_add_u64 v[80:81], v[78:79], 0, s[28:29]
	v_add_co_u32_e32 v78, vcc, s38, v78
	s_nop 1
	v_addc_co_u32_e32 v79, vcc, 0, v79, vcc
	global_load_dwordx4 v[106:109], v[78:79], off
	s_nop 0
	global_load_dwordx4 v[78:81], v[80:81], off offset:16
	s_load_dwordx2 s[12:13], s[58:59], 0xe0
	s_waitcnt lgkmcnt(0)
	v_mov_b64_e32 v[124:125], s[12:13]
	v_mad_i64_i32 v[124:125], s[18:19], v126, s23, v[124:125]
	v_lshl_add_u64 v[124:125], v[124:125], 0, s[16:17]
	v_lshl_add_u64 v[146:147], v[124:125], 0, v[122:123]
	s_mov_b32 s16, 0x45f1000
	v_add_co_u32_e32 v124, vcc, s16, v146
	s_mov_b64 s[18:19], 0x45f0000
	s_nop 0
	v_addc_co_u32_e32 v125, vcc, 0, v147, vcc
	v_lshl_add_u64 v[122:123], v[146:147], 0, s[18:19]
	s_mov_b32 s16, 0x45f2000
	s_mov_b64 s[18:19], 0x4bf0000
	s_waitcnt vmcnt(9)
	global_store_dwordx4 v[124:125], v[114:117], off offset:-4096
	s_waitcnt vmcnt(7)
	global_store_dwordx4 v[122:123], v[102:105], off offset:16
	global_store_dwordx4 v[122:123], v[90:93], off offset:32
	global_store_dwordx4 v[122:123], v[74:77], off offset:48
	s_waitcnt vmcnt(9)
	global_store_dwordx4 v[124:125], v[118:121], off
	s_waitcnt vmcnt(7)
	global_store_dwordx4 v[124:125], v[98:101], off offset:16
	global_store_dwordx4 v[124:125], v[86:89], off offset:32
	global_store_dwordx4 v[124:125], v[70:73], off offset:48
	ds_read_b128 v[122:125], v227 offset:8704
	ds_read_b128 v[126:129], v227 offset:8960
	ds_read_b128 v[130:133], v227 offset:9216
	ds_read_b128 v[134:137], v227 offset:9472
	ds_read_b128 v[138:141], v227 offset:9728
	s_waitcnt lgkmcnt(3)
; #define LAS __attribute__((address_space(3)))
; __device__ __forceinline__ void scan_phase(KP p, int l, LAS unsigned char* lds) {
;     ...
;             {   const int rr = lane >> 2, cb = lane & 3, cl = cb * 16, m = m0 + rr, sb = m - MP;
;                 float xv[4][16];
;                 const float* st = p->in[3] + ((size_t)(l * MS + sb) * 3) * D + hc0 + cl;
; #pragma unroll
;                 for (int k = 0; k < 3; ++k)
; #pragma unroll
;                     for (int e = 0; e < 16; e += 4) { const f32x4 v = *(const f32x4*)(st + (size_t)k * D + e); xv[k][e] = v[0]; xv[k][e + 1] = v[1]; xv[k][e + 2] = v[2]; xv[k][e + 3] = v[3]; }
;                 const bf16_t* src = P + (size_t)m * DP + C_XR + hc0 + cl;
;                 float f0[8], f1[8]; unpack8(*(const u32x4*)src, f0); unpack8(*(const u32x4*)(src + 8), f1);
; #pragma unroll
;                 for (int e = 0; e < 8; ++e) { xv[3][e] = f0[e]; xv[3][8 + e] = f1[e]; }
;                 float* o = p->out + O_SCB + ((size_t)(l * MS + sb) * 3) * D + hc0 + cl;
; #pragma unroll
;                 for (int k = 0; k < 3; ++k)
; #pragma unroll
;                     for (int e = 0; e < 16; e += 4) *(f32x4*)(o + (size_t)k * D + e) = (f32x4){xv[k + 1][e], xv[k + 1][e + 1], xv[k + 1][e + 2], xv[k + 1][e + 3]};
; #pragma unroll
;                 for (int e = 0; e < 16; e += 4) {
;                     const f32x4 w0 = *(const LAS f32x4*)(CST + 0 * 64 + cl + e), w1 = *(const LAS f32x4*)(CST + 1 * 64 + cl + e), w2 = *(const LAS f32x4*)(CST + 2 * 64 + cl + e),
;                                 w3 = *(const LAS f32x4*)(CST + 3 * 64 + cl + e), bb = *(const LAS f32x4*)(CST + 4 * 64 + cl + e);
;                     f32x4 r;
; #pragma unroll
;                     for (int q = 0; q < 4; ++q) r[q] = w0[q] * xv[0][e + q] + w1[q] * xv[1][e + q] + w2[q] * xv[2][e + q] + w3[q] * xv[3][e + q] + bb[q];
;                     *(LAS f32x4*)(XC + rr * 68 + cl + e) = r;
;                 }
;             }
;             LDS_WAIT();
;             f32x4 ar[4], ai[4];
; #pragma unroll
;             for (int n = 0; n < 4; ++n) { ar[n] = (f32x4){0.f, 0.f, 0.f, 0.f}; ai[n] = (f32x4){0.f, 0.f, 0.f, 0.f}; }
; #pragma unroll
;             for (int s = 0; s < 2; ++s) {
;                 const f32x4 x0 = *(const LAS f32x4*)(XC + fr * 68 + 32 * s + 8 * fq), x1 = *(const LAS f32x4*)(XC + fr * 68 + 32 * s + 8 * fq + 4);
	v_pk_mul_f32 v[116:117], v[116:117], v[128:129]
	v_pk_mul_f32 v[114:115], v[114:115], v[126:127]
	v_pk_fma_f32 v[112:113], v[112:113], v[124:125], v[116:117]
	v_pk_fma_f32 v[110:111], v[110:111], v[122:123], v[114:115]
	s_waitcnt lgkmcnt(2)
	v_pk_fma_f32 v[112:113], v[120:121], v[132:133], v[112:113]
	v_pk_fma_f32 v[110:111], v[118:119], v[130:131], v[110:111]
	s_waitcnt vmcnt(9)
	v_lshlrev_b32_e32 v142, 16, v106
	v_and_b32_e32 v143, 0xffff0000, v106
	v_lshlrev_b32_e32 v144, 16, v107
	v_and_b32_e32 v145, 0xffff0000, v107
	v_add_co_u32_e32 v106, vcc, s16, v146
	s_waitcnt lgkmcnt(1)
	v_pk_fma_f32 v[112:113], v[136:137], v[144:145], v[112:113]
	v_pk_fma_f32 v[110:111], v[134:135], v[142:143], v[110:111]
	v_addc_co_u32_e32 v107, vcc, 0, v147, vcc
	s_waitcnt lgkmcnt(0)
	v_pk_add_f32 v[112:113], v[140:141], v[112:113]
	v_pk_add_f32 v[110:111], v[138:139], v[110:111]
	global_store_dwordx4 v[106:107], v[142:145], off
	ds_write_b128 v228, v[110:113]
	ds_read_b128 v[110:113], v227 offset:8720
	ds_read_b128 v[114:117], v227 offset:8976
	ds_read_b128 v[118:121], v227 offset:9232
	ds_read_b128 v[122:125], v227 offset:9488
	ds_read_b128 v[126:129], v227 offset:9744
	v_lshlrev_b32_e32 v130, 16, v108
	s_waitcnt lgkmcnt(3)
	v_pk_mul_f32 v[104:105], v[104:105], v[116:117]
	v_pk_mul_f32 v[102:103], v[102:103], v[114:115]
	v_pk_fma_f32 v[96:97], v[96:97], v[112:113], v[104:105]
	v_pk_fma_f32 v[94:95], v[94:95], v[110:111], v[102:103]
	v_and_b32_e32 v131, 0xffff0000, v108
	v_lshlrev_b32_e32 v132, 16, v109
	v_and_b32_e32 v133, 0xffff0000, v109
	s_waitcnt lgkmcnt(2)
	v_pk_fma_f32 v[96:97], v[100:101], v[120:121], v[96:97]
	v_pk_fma_f32 v[94:95], v[98:99], v[118:119], v[94:95]
	s_waitcnt lgkmcnt(1)
	v_pk_fma_f32 v[96:97], v[124:125], v[132:133], v[96:97]
	v_pk_fma_f32 v[94:95], v[122:123], v[130:131], v[94:95]
	s_waitcnt lgkmcnt(0)
	v_pk_add_f32 v[96:97], v[128:129], v[96:97]
	v_pk_add_f32 v[94:95], v[126:127], v[94:95]
	global_store_dwordx4 v[106:107], v[130:133], off offset:16
	ds_write_b128 v228, v[94:97] offset:16
	ds_read_b128 v[94:97], v227 offset:8736
	ds_read_b128 v[98:101], v227 offset:8992
	ds_read_b128 v[102:105], v227 offset:9248
	ds_read_b128 v[108:111], v227 offset:9504
	ds_read_b128 v[112:115], v227 offset:9760
	s_waitcnt vmcnt(10)
	v_lshlrev_b32_e32 v116, 16, v78
	v_and_b32_e32 v117, 0xffff0000, v78
	v_lshlrev_b32_e32 v118, 16, v79
	v_and_b32_e32 v119, 0xffff0000, v79
	s_waitcnt lgkmcnt(3)
	v_pk_mul_f32 v[78:79], v[92:93], v[100:101]
	v_pk_mul_f32 v[90:91], v[90:91], v[98:99]
	v_pk_fma_f32 v[78:79], v[84:85], v[96:97], v[78:79]
	v_pk_fma_f32 v[82:83], v[82:83], v[94:95], v[90:91]
	s_waitcnt lgkmcnt(2)
	v_pk_fma_f32 v[78:79], v[88:89], v[104:105], v[78:79]
	v_pk_fma_f32 v[82:83], v[86:87], v[102:103], v[82:83]
	s_waitcnt lgkmcnt(1)
	v_pk_fma_f32 v[78:79], v[110:111], v[118:119], v[78:79]
	v_pk_fma_f32 v[82:83], v[108:109], v[116:117], v[82:83]
	s_waitcnt lgkmcnt(0)
	v_pk_add_f32 v[84:85], v[114:115], v[78:79]
	v_pk_add_f32 v[82:83], v[112:113], v[82:83]
	global_store_dwordx4 v[106:107], v[116:119], off offset:32
	ds_write_b128 v228, v[82:85] offset:32
	ds_read_b128 v[82:85], v227 offset:8752
	ds_read_b128 v[86:89], v227 offset:9008
	ds_read_b128 v[90:93], v227 offset:9264
	ds_read_b128 v[94:97], v227 offset:9520
	ds_read_b128 v[98:101], v227 offset:9776
	v_lshlrev_b32_e32 v78, 16, v80
	s_waitcnt lgkmcnt(3)
	v_pk_mul_f32 v[76:77], v[76:77], v[88:89]
	v_pk_mul_f32 v[74:75], v[74:75], v[86:87]
	v_pk_fma_f32 v[68:69], v[68:69], v[84:85], v[76:77]
	v_pk_fma_f32 v[66:67], v[66:67], v[82:83], v[74:75]
	v_and_b32_e32 v79, 0xffff0000, v80
	v_lshlrev_b32_e32 v80, 16, v81
	v_and_b32_e32 v81, 0xffff0000, v81
	s_waitcnt lgkmcnt(2)
	v_pk_fma_f32 v[68:69], v[72:73], v[92:93], v[68:69]
	v_pk_fma_f32 v[66:67], v[70:71], v[90:91], v[66:67]
	s_waitcnt lgkmcnt(1)
	v_pk_fma_f32 v[68:69], v[96:97], v[80:81], v[68:69]
	v_pk_fma_f32 v[66:67], v[94:95], v[78:79], v[66:67]
	s_waitcnt lgkmcnt(0)
	v_pk_add_f32 v[68:69], v[100:101], v[68:69]
	v_pk_add_f32 v[66:67], v[98:99], v[66:67]
	global_store_dwordx4 v[106:107], v[78:81], off offset:48
	ds_write_b128 v228, v[66:69] offset:48
	s_waitcnt lgkmcnt(0)
	ds_read_b128 v[66:69], v239
	ds_read_b128 v[70:73], v239 offset:16
	s_waitcnt lgkmcnt(1)
	v_cvt_pk_bf16_f32 v66, v66, v67
	v_cvt_pk_bf16_f32 v67, v68, v69
	s_waitcnt lgkmcnt(0)
	v_cvt_pk_bf16_f32 v68, v70, v71
	v_cvt_pk_bf16_f32 v69, v72, v73
	ds_read_b128 v[86:89], v239 offset:128
	ds_read_b128 v[90:93], v239 offset:144
	v_mfma_f32_16x16x32_bf16 v[70:73], v[66:69], v[34:37], 0
	s_waitcnt lgkmcnt(1)
	v_cvt_pk_bf16_f32 v110, v86, v87
	v_cvt_pk_bf16_f32 v111, v88, v89
	s_waitcnt lgkmcnt(0)
	v_cvt_pk_bf16_f32 v112, v90, v91
	v_cvt_pk_bf16_f32 v113, v92, v93
	ds_read2st64_b32 v[120:121], v232 offset0:39 offset1:40
	ds_read_b32 v123, v232 offset:10496
	v_mfma_f32_16x16x32_bf16 v[94:97], v[110:113], v[10:13], v[70:73]
	v_or_b32_e32 v114, s11, v229
	v_or_b32_e32 v122, s75, v223
	v_lshlrev_b32_e32 v116, 2, v122
	v_mfma_f32_16x16x32_bf16 v[78:81], v[66:69], v[42:45], 0
	v_mov_b32_e32 v117, v1
	s_waitcnt lgkmcnt(1)
	s_nop 1
	v_add_f32_e32 v94, v94, v120
	v_mul_f32_e32 v94, 0xbfb8aa3b, v94
	v_exp_f32_e32 v94, v94
	v_mfma_f32_16x16x32_bf16 v[98:101], v[66:69], v[50:53], 0
	v_lshl_add_u64 v[118:119], s[14:15], 0, v[116:117]
	v_ashrrev_i32_e32 v115, 31, v114
	v_add_f32_e32 v94, 1.0, v94
	v_rcp_f32_e32 v94, v94
	v_mfma_f32_16x16x32_bf16 v[86:89], v[110:113], v[22:25], v[78:81]
	v_mul_f32_e32 v94, 0xc1000000, v94
	s_waitcnt lgkmcnt(0)
; #define LAS __attribute__((address_space(3)))
; __device__ __forceinline__ unsigned cvt_pk_bf16(float lo, float hi) { unsigned r; asm volatile("v_cvt_pk_bf16_f32 %0, %1, %2" : "=v"(r) : "v"(lo), "v"(hi)); return r; }
; __device__ __forceinline__ float sigmoidf_(float x) { return __builtin_amdgcn_rcpf(1.0f + __expf(-x)); }
; __device__ __forceinline__ void scan_phase(KP p, int l, LAS unsigned char* lds) {
;     ...
; #pragma unroll
;             for (int s = 0; s < 2; ++s) {
;                 const f32x4 x0 = *(const LAS f32x4*)(XC + fr * 68 + 32 * s + 8 * fq), x1 = *(const LAS f32x4*)(XC + fr * 68 + 32 * s + 8 * fq + 4);
;                 u32x4 aw; aw.x = cvt_pk_bf16(x0[0], x0[1]); aw.y = cvt_pk_bf16(x0[2], x0[3]); aw.z = cvt_pk_bf16(x1[0], x1[1]); aw.w = cvt_pk_bf16(x1[2], x1[3]);
;                 const bf16x8 af = __builtin_bit_cast(bf16x8, aw);
; #pragma unroll
;                 for (int n = 0; n < 4; ++n) { ar[n] = __builtin_amdgcn_mfma_f32_16x16x32_bf16(af, Wa[n][s], ar[n], 0, 0, 0); ai[n] = __builtin_amdgcn_mfma_f32_16x16x32_bf16(af, Wx[n][s], ai[n], 0, 0, 0); }
;             }
; #pragma unroll
;             for (int n = 0; n < 4; ++n) {
;                 const int cc = 16 * n + fr, ch = hc0 + cc;
;                 const float ba = CST[5 * 64 + cc], bx = CST[6 * 64 + cc], sp = CST[7 * 64 + cc];
; #pragma unroll
;                 for (int j = 0; j < 4; ++j) {
;                     const float xc = XC[(4 * fq + j) * 68 + cc];
;                     const float r = sigmoidf_(ar[n][j] + ba), ig = sigmoidf_(ai[n][j] + bx);
;                     const float a = __expf(-8.0f * r * sp);
;                     const float mult = sqrtf(fmaxf(1.0f - a * a, 0.f));
;                     const int sb = m0 - MP + 4 * fq + j;
;                     const float h0 = p->in[4][(size_t)(l * MS + sb) * D + ch];
;                     const float h = a * h0 + mult * ig * xc;
;                     const size_t o = (size_t)(m0 + 4 * fq + j) * D + ch; HLOC[o] = (bf16_t)(cvt_pk_bf16(h, 0.f) & 0xffffu); PCUM[o] = 0;
;                     p->out[O_SRG + (size_t)(l * MS + sb) * D + ch] = h; }
;             }
	v_mul_f32_e32 v94, v123, v94
	v_mul_f32_e32 v94, 0x3fb8aa3b, v94
	v_exp_f32_e32 v94, v94
	v_mfma_f32_16x16x32_bf16 v[78:81], v[110:113], v[30:33], v[98:101]
	s_nop 2
	v_fma_f32 v98, -v94, v94, 1.0
	v_max_f32_e32 v98, 0, v98
	s_nop 0
	s_nop 0
	v_mfma_f32_16x16x32_bf16 v[74:77], v[66:69], v[38:41], 0
	ds_read_b32 v100, v241
	v_mfma_f32_16x16x32_bf16 v[102:105], v[66:69], v[54:57], 0
	s_nop 0
	v_mfma_f32_16x16x32_bf16 v[82:85], v[66:69], v[46:49], 0
	v_mfma_f32_16x16x32_bf16 v[106:109], v[66:69], v[62:65], 0
	v_mfma_f32_16x16x32_bf16 v[66:69], v[66:69], v[58:61], 0
	v_mfma_f32_16x16x32_bf16 v[90:93], v[110:113], v[14:17], v[74:77]
	v_mfma_f32_16x16x32_bf16 v[74:77], v[110:113], v[18:21], v[102:105]
	s_nop 2
	s_nop 0
	v_mfma_f32_16x16x32_bf16 v[82:85], v[110:113], v[26:29], v[82:85]
	s_nop 1
	v_add_f32_e32 v90, v90, v121
	v_mul_f32_e32 v90, 0xbfb8aa3b, v90
	v_exp_f32_e32 v90, v90
	v_mfma_f32_16x16x32_bf16 v[70:73], v[110:113], v[6:9], v[106:109]
	v_add_f32_e32 v91, v91, v121
	v_mul_f32_e32 v91, 0xbfb8aa3b, v91
	v_add_f32_e32 v90, 1.0, v90
	v_mfma_f32_16x16x32_bf16 v[66:69], v[110:113], v[2:5], v[66:69]
	v_add_u32_e32 v110, s10, v230
	v_ashrrev_i32_e32 v111, 31, v110
	v_lshlrev_b64 v[106:107], 12, v[110:111]
	v_rcp_f32_e32 v90, v90
	v_lshlrev_b64 v[102:103], 10, v[114:115]
	v_exp_f32_e32 v91, v91
	v_sqrt_f32_e32 v101, v98
	s_nop 0
	v_lshl_add_u64 v[98:99], v[118:119], 0, v[106:107]
	global_load_dword v98, v[98:99], off
	v_mul_f32_e32 v90, v90, v101
	s_waitcnt lgkmcnt(0)
	v_mul_f32_e32 v90, v100, v90
	v_mov_b32_e32 v99, v103
	v_add_f32_e32 v91, 1.0, v91
	v_add_f32_e32 v92, v92, v121
	v_mul_f32_e32 v92, 0xbfb8aa3b, v92
	v_exp_f32_e32 v92, v92
	v_add_f32_e32 v93, v93, v121
	v_mul_f32_e32 v93, 0xbfb8aa3b, v93
	v_exp_f32_e32 v93, v93
	v_add_f32_e32 v92, 1.0, v92
	v_rcp_f32_e32 v92, v92
	v_add_f32_e32 v93, 1.0, v93
	s_waitcnt vmcnt(0)
	v_fmac_f32_e32 v90, v98, v94
	v_or_b32_e32 v98, v102, v122
	v_lshlrev_b64 v[98:99], 1, v[98:99]
	v_lshl_add_u64 v[100:101], v[98:99], 1, s[62:63]
	v_cvt_pk_bf16_f32 v94, v90, v1
	v_lshl_add_u64 v[98:99], s[12:13], 0, v[106:107]
	v_lshl_add_u64 v[98:99], v[98:99], 0, s[18:19]
	global_store_dword v[100:101], v94, off
	v_lshl_add_u64 v[100:101], v[98:99], 0, v[116:117]
	global_store_dword v[100:101], v90, off
	v_add_f32_e32 v90, v95, v120
	v_mul_f32_e32 v90, 0xbfb8aa3b, v90
	v_exp_f32_e32 v90, v90
	v_rcp_f32_e32 v95, v91
	ds_read_b32 v94, v241 offset:272
	v_add_f32_e32 v90, 1.0, v90
	v_rcp_f32_e32 v90, v90
	s_nop 0
	v_mul_f32_e32 v90, 0xc1000000, v90
	v_mul_f32_e32 v90, v123, v90
	v_mul_f32_e32 v90, 0x3fb8aa3b, v90
	v_exp_f32_e32 v100, v90
	s_nop 0
	v_fma_f32 v90, -v100, v100, 1.0
	v_max_f32_e32 v90, 0, v90
	s_nop 0
	s_nop 0
	s_nop 0
	s_nop 1
	s_nop 1
	v_sqrt_f32_e32 v101, v90
	s_nop 0
	v_or_b32_e32 v90, 1, v110
	v_ashrrev_i32_e32 v91, 31, v90
	v_lshlrev_b64 v[112:113], 12, v[90:91]
	v_lshl_add_u64 v[90:91], v[118:119], 0, v[112:113]
	global_load_dword v90, v[90:91], off
	v_mul_f32_e32 v91, v95, v101
	s_waitcnt lgkmcnt(0)
	v_mul_f32_e32 v104, v94, v91
	s_waitcnt vmcnt(0)
	v_fmac_f32_e32 v104, v100, v90
	v_or_b32_e32 v90, 1, v114
	v_ashrrev_i32_e32 v91, 31, v90
	v_lshlrev_b64 v[100:101], 10, v[90:91]
	v_or_b32_e32 v90, v100, v122
	v_mov_b32_e32 v91, v101
	v_lshlrev_b64 v[90:91], 1, v[90:91]
	v_lshl_add_u64 v[94:95], v[90:91], 1, s[62:63]
	v_cvt_pk_bf16_f32 v105, v104, v1
	v_lshl_add_u64 v[90:91], s[12:13], 0, v[112:113]
	v_lshl_add_u64 v[90:91], v[90:91], 0, s[18:19]
	global_store_dword v[94:95], v105, off
	v_lshl_add_u64 v[94:95], v[90:91], 0, v[116:117]
	global_store_dword v[94:95], v104, off
	v_add_f32_e32 v94, v96, v120
	v_mul_f32_e32 v94, 0xbfb8aa3b, v94
	v_exp_f32_e32 v94, v94
	ds_read_b32 v104, v241 offset:544
	v_add_f32_e32 v94, 1.0, v94
	v_rcp_f32_e32 v94, v94
	s_nop 0
	v_mul_f32_e32 v94, 0xc1000000, v94
	v_mul_f32_e32 v94, v123, v94
	v_mul_f32_e32 v94, 0x3fb8aa3b, v94
	v_exp_f32_e32 v96, v94
	s_nop 0
	v_fma_f32 v94, -v96, v96, 1.0
	v_max_f32_e32 v94, 0, v94
	s_nop 0
	s_nop 0
	s_nop 0
	s_nop 1
	s_nop 1
	v_sqrt_f32_e32 v105, v94
	s_nop 0
	v_or_b32_e32 v94, 2, v110
	v_ashrrev_i32_e32 v95, 31, v94
	v_lshlrev_b64 v[108:109], 12, v[94:95]
	v_lshl_add_u64 v[94:95], v[118:119], 0, v[108:109]
	global_load_dword v94, v[94:95], off
	v_mul_f32_e32 v92, v92, v105
	s_waitcnt vmcnt(0)
	v_mul_f32_e32 v96, v96, v94
	v_or_b32_e32 v94, 2, v114
	v_ashrrev_i32_e32 v95, 31, v94
	s_waitcnt lgkmcnt(0)
	v_fmac_f32_e32 v96, v92, v104
	v_lshlrev_b64 v[104:105], 10, v[94:95]
	v_or_b32_e32 v94, v104, v122
	v_mov_b32_e32 v95, v105
	v_lshlrev_b64 v[94:95], 1, v[94:95]
	v_cvt_pk_bf16_f32 v92, v96, v1
	v_lshl_add_u64 v[124:125], v[94:95], 1, s[62:63]
	global_store_dword v[124:125], v92, off
	v_add_f32_e32 v92, v97, v120
	v_mul_f32_e32 v92, 0xbfb8aa3b, v92
	v_exp_f32_e32 v92, v92
	v_rcp_f32_e32 v97, v93
	v_add_f32_e32 v92, 1.0, v92
	v_rcp_f32_e32 v92, v92
	v_lshl_add_u64 v[94:95], s[12:13], 0, v[108:109]
	v_lshl_add_u64 v[94:95], v[94:95], 0, s[18:19]
	v_lshl_add_u64 v[124:125], v[94:95], 0, v[116:117]
	v_mul_f32_e32 v92, 0xc1000000, v92
	v_mul_f32_e32 v92, v123, v92
	v_mul_f32_e32 v92, 0x3fb8aa3b, v92
	v_exp_f32_e32 v115, v92
	global_store_dword v[124:125], v96, off
	ds_read_b32 v96, v241 offset:816
	v_fma_f32 v92, -v115, v115, 1.0
	v_max_f32_e32 v92, 0, v92
	s_nop 0
	s_nop 0
	s_nop 0
	s_nop 1
	s_nop 1
	v_sqrt_f32_e32 v120, v92
	s_nop 0
	v_or_b32_e32 v92, 3, v110
	v_ashrrev_i32_e32 v93, 31, v92
	v_lshlrev_b64 v[110:111], 12, v[92:93]
	v_lshl_add_u64 v[92:93], v[118:119], 0, v[110:111]
	global_load_dword v92, v[92:93], off
	s_waitcnt vmcnt(0)
	v_mul_f32_e32 v118, v115, v92
	v_mul_f32_e32 v92, v97, v120
	s_waitcnt lgkmcnt(0)
; __device__ __forceinline__ unsigned cvt_pk_bf16(float lo, float hi) { unsigned r; asm volatile("v_cvt_pk_bf16_f32 %0, %1, %2" : "=v"(r) : "v"(lo), "v"(hi)); return r; }
; __device__ __forceinline__ float sigmoidf_(float x) { return __builtin_amdgcn_rcpf(1.0f + __expf(-x)); }
; __device__ __forceinline__ void scan_phase(KP p, int l, LAS unsigned char* lds) {
;     ...
; #pragma unroll
;             for (int n = 0; n < 4; ++n) {
;                 const int cc = 16 * n + fr, ch = hc0 + cc;
;                 const float ba = CST[5 * 64 + cc], bx = CST[6 * 64 + cc], sp = CST[7 * 64 + cc];
; #pragma unroll
;                 for (int j = 0; j < 4; ++j) {
;                     const float xc = XC[(4 * fq + j) * 68 + cc];
;                     const float r = sigmoidf_(ar[n][j] + ba), ig = sigmoidf_(ai[n][j] + bx);
;                     const float a = __expf(-8.0f * r * sp);
;                     const float mult = sqrtf(fmaxf(1.0f - a * a, 0.f));
;                     const int sb = m0 - MP + 4 * fq + j;
;                     const float h0 = p->in[4][(size_t)(l * MS + sb) * D + ch];
;                     const float h = a * h0 + mult * ig * xc;
;                     const size_t o = (size_t)(m0 + 4 * fq + j) * D + ch; HLOC[o] = (bf16_t)(cvt_pk_bf16(h, 0.f) & 0xffffu); PCUM[o] = 0;
;                     p->out[O_SRG + (size_t)(l * MS + sb) * D + ch] = h; }
;             }
	v_fmac_f32_e32 v118, v92, v96
	v_or_b32_e32 v92, 3, v114
	v_ashrrev_i32_e32 v93, 31, v92
	v_lshlrev_b64 v[96:97], 10, v[92:93]
	v_or_b32_e32 v92, v96, v122
	v_mov_b32_e32 v93, v97
	v_lshlrev_b64 v[92:93], 1, v[92:93]
	v_lshl_add_u64 v[114:115], v[92:93], 1, s[62:63]
	v_cvt_pk_bf16_f32 v119, v118, v1
	v_lshl_add_u64 v[92:93], s[12:13], 0, v[110:111]
	v_lshl_add_u64 v[92:93], v[92:93], 0, s[18:19]
	global_store_dword v[114:115], v119, off
	v_lshl_add_u64 v[114:115], v[92:93], 0, v[116:117]
	global_store_dword v[114:115], v118, off
	v_add_u32_e32 v114, 64, v232
	ds_read2st64_b32 v[118:119], v114 offset0:39 offset1:40
	ds_read_b32 v121, v232 offset:10560
	v_add_lshl_u32 v114, s75, v223, 2
	v_mov_b32_e32 v115, v1
	v_lshl_add_u64 v[114:115], s[14:15], 0, v[114:115]
	s_waitcnt lgkmcnt(1)
	v_add_f32_e32 v86, v86, v118
	v_mul_f32_e32 v86, 0xbfb8aa3b, v86
	v_exp_f32_e32 v86, v86
	v_lshl_add_u64 v[106:107], v[114:115], 0, v[106:107]
	v_add_f32_e32 v82, v82, v119
	v_mul_f32_e32 v82, 0xbfb8aa3b, v82
	v_add_f32_e32 v86, 1.0, v86
	v_rcp_f32_e32 v86, v86
	v_exp_f32_e32 v82, v82
	ds_read_b32 v116, v241 offset:64
	v_or_b32_e32 v120, s75, v233
	v_mul_f32_e32 v86, 0xc1000000, v86
	s_waitcnt lgkmcnt(1)
	v_mul_f32_e32 v86, v121, v86
	v_mul_f32_e32 v86, 0x3fb8aa3b, v86
	v_exp_f32_e32 v86, v86
	v_add_f32_e32 v82, 1.0, v82
	v_rcp_f32_e32 v82, v82
	v_add_f32_e32 v83, v83, v119
	v_fma_f32 v117, -v86, v86, 1.0
	v_max_f32_e32 v117, 0, v117
	v_mul_f32_e32 v83, 0xbfb8aa3b, v83
	v_exp_f32_e32 v83, v83
	v_add_f32_e32 v84, v84, v119
	v_mul_f32_e32 v84, 0xbfb8aa3b, v84
	v_add_f32_e32 v83, 1.0, v83
	v_exp_f32_e32 v84, v84
	v_add_f32_e32 v85, v85, v119
	v_add_f32_e32 v84, 1.0, v84
	v_rcp_f32_e32 v84, v84
	v_sqrt_f32_e32 v117, v117
	s_nop 0
	global_load_dword v122, v[106:107], off offset:64
	v_mul_f32_e32 v82, v82, v117
	s_waitcnt lgkmcnt(0)
	v_mul_f32_e32 v82, v116, v82
	v_or_b32_e32 v116, v102, v120
	v_mov_b32_e32 v117, v103
	v_lshlrev_b64 v[116:117], 1, v[116:117]
	v_mul_f32_e32 v85, 0xbfb8aa3b, v85
	v_exp_f32_e32 v85, v85
	s_waitcnt vmcnt(0)
	v_fmac_f32_e32 v82, v122, v86
	v_lshl_add_u64 v[122:123], v[116:117], 1, s[62:63]
	v_cvt_pk_bf16_f32 v86, v82, v1
	v_lshlrev_b32_e32 v116, 2, v120
	v_mov_b32_e32 v117, v1
	global_store_dword v[122:123], v86, off
	v_lshl_add_u64 v[122:123], v[98:99], 0, v[116:117]
	global_store_dword v[122:123], v82, off
	v_add_f32_e32 v82, v87, v118
	v_mul_f32_e32 v82, 0xbfb8aa3b, v82
	v_exp_f32_e32 v82, v82
	v_rcp_f32_e32 v87, v83
	ds_read_b32 v86, v241 offset:336
	v_add_f32_e32 v85, 1.0, v85
	v_add_f32_e32 v82, 1.0, v82
	v_rcp_f32_e32 v82, v82
	s_nop 0
	v_mul_f32_e32 v82, 0xc1000000, v82
	v_mul_f32_e32 v82, v121, v82
	v_mul_f32_e32 v82, 0x3fb8aa3b, v82
	v_exp_f32_e32 v122, v82
	s_nop 0
	v_fma_f32 v82, -v122, v122, 1.0
	v_max_f32_e32 v82, 0, v82
	s_nop 0
	s_nop 0
	s_nop 0
	s_nop 1
	s_nop 1
	v_sqrt_f32_e32 v123, v82
	s_nop 0
	v_lshl_add_u64 v[82:83], v[114:115], 0, v[112:113]
	global_load_dword v112, v[82:83], off offset:64
	v_mul_f32_e32 v87, v87, v123
	s_waitcnt lgkmcnt(0)
	v_mul_f32_e32 v123, v86, v87
	v_or_b32_e32 v86, v100, v120
	v_mov_b32_e32 v87, v101
	v_lshlrev_b64 v[86:87], 1, v[86:87]
	s_waitcnt vmcnt(0)
	v_fmac_f32_e32 v123, v122, v112
	v_lshl_add_u64 v[112:113], v[86:87], 1, s[62:63]
	v_cvt_pk_bf16_f32 v122, v123, v1
	v_lshl_add_u64 v[86:87], v[90:91], 0, v[116:117]
	global_store_dword v[86:87], v123, off
	v_add_f32_e32 v86, v88, v118
	v_mul_f32_e32 v86, 0xbfb8aa3b, v86
	v_exp_f32_e32 v86, v86
	global_store_dword v[112:113], v122, off
	ds_read_b32 v112, v241 offset:608
	v_add_f32_e32 v86, 1.0, v86
	v_rcp_f32_e32 v86, v86
	s_nop 0
	v_mul_f32_e32 v86, 0xc1000000, v86
	v_mul_f32_e32 v86, v121, v86
	v_mul_f32_e32 v86, 0x3fb8aa3b, v86
	v_exp_f32_e32 v88, v86
	s_nop 0
	v_fma_f32 v86, -v88, v88, 1.0
	v_max_f32_e32 v86, 0, v86
	s_nop 0
	s_nop 0
	s_nop 0
	s_nop 1
	s_nop 1
	v_sqrt_f32_e32 v113, v86
	s_nop 0
	v_lshl_add_u64 v[86:87], v[114:115], 0, v[108:109]
	global_load_dword v108, v[86:87], off offset:64
	v_mov_b32_e32 v109, v105
	v_mul_f32_e32 v84, v84, v113
	s_waitcnt vmcnt(0)
	v_mul_f32_e32 v88, v88, v108
	v_or_b32_e32 v108, v104, v120
	v_lshlrev_b64 v[108:109], 1, v[108:109]
	s_waitcnt lgkmcnt(0)
	v_fmac_f32_e32 v88, v84, v112
	v_cvt_pk_bf16_f32 v84, v88, v1
	v_lshl_add_u64 v[112:113], v[108:109], 1, s[62:63]
	global_store_dword v[112:113], v84, off
	v_add_f32_e32 v84, v89, v118
	v_mul_f32_e32 v84, 0xbfb8aa3b, v84
	v_exp_f32_e32 v84, v84
	v_lshl_add_u64 v[108:109], v[94:95], 0, v[116:117]
	v_add_f32_e32 v84, 1.0, v84
	v_rcp_f32_e32 v84, v84
	global_store_dword v[108:109], v88, off
	v_rcp_f32_e32 v89, v85
	ds_read_b32 v88, v241 offset:880
	v_mul_f32_e32 v84, 0xc1000000, v84
	v_mul_f32_e32 v84, v121, v84
	v_mul_f32_e32 v84, 0x3fb8aa3b, v84
	v_exp_f32_e32 v108, v84
	s_nop 0
	v_fma_f32 v84, -v108, v108, 1.0
	v_max_f32_e32 v84, 0, v84
	s_nop 0
	s_nop 0
	s_nop 0
	s_nop 1
	s_nop 1
	v_sqrt_f32_e32 v109, v84
	s_nop 0
	v_lshl_add_u64 v[84:85], v[114:115], 0, v[110:111]
	global_load_dword v110, v[84:85], off offset:64
	v_mul_f32_e32 v89, v89, v109
	s_waitcnt vmcnt(0)
	v_mul_f32_e32 v110, v108, v110
	s_waitcnt lgkmcnt(0)
	v_fmac_f32_e32 v110, v89, v88
	v_or_b32_e32 v88, v96, v120
	v_mov_b32_e32 v89, v97
	v_lshlrev_b64 v[88:89], 1, v[88:89]
	v_lshl_add_u64 v[108:109], v[88:89], 1, s[62:63]
	v_cvt_pk_bf16_f32 v111, v110, v1
	v_lshl_add_u64 v[88:89], v[92:93], 0, v[116:117]
	global_store_dword v[108:109], v111, off
	global_store_dword v[88:89], v110, off
	v_add_u32_e32 v88, 0x80, v232
	ds_read2st64_b32 v[108:109], v88 offset0:39 offset1:40
	ds_read_b32 v111, v232 offset:10624
	ds_read_b32 v88, v241 offset:128
	v_or_b32_e32 v110, s75, v234
	s_waitcnt lgkmcnt(2)
; __device__ __forceinline__ unsigned cvt_pk_bf16(float lo, float hi) { unsigned r; asm volatile("v_cvt_pk_bf16_f32 %0, %1, %2" : "=v"(r) : "v"(lo), "v"(hi)); return r; }
; __device__ __forceinline__ float sigmoidf_(float x) { return __builtin_amdgcn_rcpf(1.0f + __expf(-x)); }
; __device__ __forceinline__ void scan_phase(KP p, int l, LAS unsigned char* lds) {
;     ...
; #pragma unroll
;             for (int n = 0; n < 4; ++n) {
;                 const int cc = 16 * n + fr, ch = hc0 + cc;
;                 const float ba = CST[5 * 64 + cc], bx = CST[6 * 64 + cc], sp = CST[7 * 64 + cc];
; #pragma unroll
;                 for (int j = 0; j < 4; ++j) {
;                     const float xc = XC[(4 * fq + j) * 68 + cc];
;                     const float r = sigmoidf_(ar[n][j] + ba), ig = sigmoidf_(ai[n][j] + bx);
;                     const float a = __expf(-8.0f * r * sp);
;                     const float mult = sqrtf(fmaxf(1.0f - a * a, 0.f));
;                     const int sb = m0 - MP + 4 * fq + j;
;                     const float h0 = p->in[4][(size_t)(l * MS + sb) * D + ch];
;                     const float h = a * h0 + mult * ig * xc;
;                     const size_t o = (size_t)(m0 + 4 * fq + j) * D + ch; HLOC[o] = (bf16_t)(cvt_pk_bf16(h, 0.f) & 0xffffu); PCUM[o] = 0;
;                     p->out[O_SRG + (size_t)(l * MS + sb) * D + ch] = h; }
;             }
	v_add_f32_e32 v78, v78, v108
	v_mul_f32_e32 v78, 0xbfb8aa3b, v78
	v_exp_f32_e32 v78, v78
	v_add_f32_e32 v74, v74, v109
	v_mul_f32_e32 v74, 0xbfb8aa3b, v74
	v_exp_f32_e32 v74, v74
	v_add_f32_e32 v78, 1.0, v78
	v_rcp_f32_e32 v78, v78
	v_add_f32_e32 v75, v75, v109
	v_add_f32_e32 v74, 1.0, v74
	v_rcp_f32_e32 v74, v74
	v_mul_f32_e32 v78, 0xc1000000, v78
	s_waitcnt lgkmcnt(1)
	v_mul_f32_e32 v78, v111, v78
	v_mul_f32_e32 v78, 0x3fb8aa3b, v78
	v_exp_f32_e32 v78, v78
	v_mul_f32_e32 v75, 0xbfb8aa3b, v75
	v_exp_f32_e32 v75, v75
	v_add_f32_e32 v76, v76, v109
	v_fma_f32 v89, -v78, v78, 1.0
	v_max_f32_e32 v89, 0, v89
	v_add_f32_e32 v75, 1.0, v75
	v_rcp_f32_e32 v75, v75
	v_mul_f32_e32 v76, 0xbfb8aa3b, v76
	v_exp_f32_e32 v76, v76
	s_nop 0
	v_add_f32_e32 v76, 1.0, v76
	v_rcp_f32_e32 v76, v76
	s_nop 0
	s_nop 1
	v_sqrt_f32_e32 v89, v89
	s_nop 0
	global_load_dword v112, v[106:107], off offset:128
	v_mul_f32_e32 v74, v74, v89
	s_waitcnt lgkmcnt(0)
	v_mul_f32_e32 v74, v88, v74
	v_or_b32_e32 v88, v102, v110
	v_mov_b32_e32 v89, v103
	v_lshlrev_b64 v[88:89], 1, v[88:89]
	s_waitcnt vmcnt(0)
	v_fmac_f32_e32 v74, v112, v78
	v_cvt_pk_bf16_f32 v78, v74, v1
	v_lshl_add_u64 v[112:113], v[88:89], 1, s[62:63]
	global_store_dword v[112:113], v78, off
	v_add_f32_e32 v78, v79, v108
	v_mul_f32_e32 v78, 0xbfb8aa3b, v78
	v_exp_f32_e32 v78, v78
	v_lshlrev_b32_e32 v88, 2, v110
	v_add_f32_e32 v78, 1.0, v78
	v_rcp_f32_e32 v78, v78
	v_mov_b32_e32 v89, v1
	v_lshl_add_u64 v[112:113], v[98:99], 0, v[88:89]
	global_store_dword v[112:113], v74, off
	v_mul_f32_e32 v78, 0xc1000000, v78
	v_mul_f32_e32 v78, v111, v78
	v_mul_f32_e32 v78, 0x3fb8aa3b, v78
	v_exp_f32_e32 v78, v78
	ds_read_b32 v74, v241 offset:400
	v_fma_f32 v79, -v78, v78, 1.0
	v_max_f32_e32 v79, 0, v79
	s_nop 0
	s_nop 0
	s_nop 0
	s_nop 1
	s_nop 1
	v_sqrt_f32_e32 v79, v79
	s_nop 0
	global_load_dword v112, v[82:83], off offset:128
	v_mul_f32_e32 v75, v75, v79
	s_waitcnt lgkmcnt(0)
	v_mul_f32_e32 v113, v74, v75
	v_or_b32_e32 v74, v100, v110
	v_mov_b32_e32 v75, v101
	v_lshlrev_b64 v[74:75], 1, v[74:75]
	s_waitcnt vmcnt(0)
	v_fmac_f32_e32 v113, v78, v112
	v_lshl_add_u64 v[78:79], v[74:75], 1, s[62:63]
	v_cvt_pk_bf16_f32 v112, v113, v1
	v_lshl_add_u64 v[74:75], v[90:91], 0, v[88:89]
	global_store_dword v[74:75], v113, off
	v_add_f32_e32 v75, v80, v108
	v_mul_f32_e32 v75, 0xbfb8aa3b, v75
	v_exp_f32_e32 v75, v75
	global_store_dword v[78:79], v112, off
	ds_read_b32 v74, v241 offset:672
	v_add_f32_e32 v75, 1.0, v75
	v_rcp_f32_e32 v75, v75
	s_nop 0
	v_mul_f32_e32 v75, 0xc1000000, v75
	v_mul_f32_e32 v75, v111, v75
	v_mul_f32_e32 v75, 0x3fb8aa3b, v75
	v_exp_f32_e32 v75, v75
	s_nop 0
	v_fma_f32 v78, -v75, v75, 1.0
	v_max_f32_e32 v78, 0, v78
	s_nop 0
	s_nop 0
	s_nop 0
	s_nop 1
	s_nop 1
	v_sqrt_f32_e32 v78, v78
	s_nop 0
	global_load_dword v79, v[86:87], off offset:128
	s_waitcnt vmcnt(0)
	v_mul_f32_e32 v80, v75, v79
	v_mul_f32_e32 v75, v76, v78
	s_waitcnt lgkmcnt(0)
	v_fmac_f32_e32 v80, v75, v74
	v_or_b32_e32 v74, v104, v110
	v_mov_b32_e32 v75, v105
	v_lshlrev_b64 v[74:75], 1, v[74:75]
	v_lshl_add_u64 v[78:79], v[74:75], 1, s[62:63]
	v_cvt_pk_bf16_f32 v76, v80, v1
	v_lshl_add_u64 v[74:75], v[94:95], 0, v[88:89]
	global_store_dword v[74:75], v80, off
	v_add_f32_e32 v75, v81, v108
	v_mul_f32_e32 v75, 0xbfb8aa3b, v75
	v_exp_f32_e32 v75, v75
	global_store_dword v[78:79], v76, off
	v_add_f32_e32 v76, v77, v109
	v_mul_f32_e32 v76, 0xbfb8aa3b, v76
	v_add_f32_e32 v75, 1.0, v75
	v_rcp_f32_e32 v75, v75
	v_exp_f32_e32 v76, v76
	ds_read_b32 v74, v241 offset:944
	v_mul_f32_e32 v75, 0xc1000000, v75
	v_mul_f32_e32 v75, v111, v75
	v_mul_f32_e32 v75, 0x3fb8aa3b, v75
	v_exp_f32_e32 v75, v75
	v_add_f32_e32 v76, 1.0, v76
	v_rcp_f32_e32 v76, v76
	v_fma_f32 v77, -v75, v75, 1.0
	v_max_f32_e32 v77, 0, v77
	s_nop 0
	s_nop 0
	s_nop 0
	s_nop 1
	s_nop 1
	v_sqrt_f32_e32 v77, v77
	s_nop 0
	global_load_dword v78, v[84:85], off offset:128
	s_waitcnt vmcnt(0)
	v_mul_f32_e32 v78, v75, v78
	v_mul_f32_e32 v75, v76, v77
	s_waitcnt lgkmcnt(0)
	v_fmac_f32_e32 v78, v75, v74
	v_or_b32_e32 v74, v96, v110
	v_mov_b32_e32 v75, v97
	v_lshlrev_b64 v[74:75], 1, v[74:75]
	v_lshl_add_u64 v[76:77], v[74:75], 1, s[62:63]
	v_cvt_pk_bf16_f32 v79, v78, v1
	v_lshl_add_u64 v[74:75], v[92:93], 0, v[88:89]
	global_store_dword v[76:77], v79, off
	global_store_dword v[74:75], v78, off
	v_add_u32_e32 v74, 0xc0, v232
	ds_read2st64_b32 v[76:77], v74 offset0:39 offset1:40
	ds_read_b32 v79, v232 offset:10688
	ds_read_b32 v74, v241 offset:192
	v_or_b32_e32 v78, s75, v235
	v_or_b32_e32 v102, v102, v78
	s_waitcnt lgkmcnt(2)
; __device__ __forceinline__ unsigned cvt_pk_bf16(float lo, float hi) { unsigned r; asm volatile("v_cvt_pk_bf16_f32 %0, %1, %2" : "=v"(r) : "v"(lo), "v"(hi)); return r; }
; __device__ __forceinline__ float sigmoidf_(float x) { return __builtin_amdgcn_rcpf(1.0f + __expf(-x)); }
; __device__ __forceinline__ void scan_phase(KP p, int l, LAS unsigned char* lds) {
;     ...
; #pragma unroll
;             for (int n = 0; n < 4; ++n) {
;                 const int cc = 16 * n + fr, ch = hc0 + cc;
;                 const float ba = CST[5 * 64 + cc], bx = CST[6 * 64 + cc], sp = CST[7 * 64 + cc];
; #pragma unroll
;                 for (int j = 0; j < 4; ++j) {
;                     const float xc = XC[(4 * fq + j) * 68 + cc];
;                     const float r = sigmoidf_(ar[n][j] + ba), ig = sigmoidf_(ai[n][j] + bx);
;                     const float a = __expf(-8.0f * r * sp);
;                     const float mult = sqrtf(fmaxf(1.0f - a * a, 0.f));
;                     const int sb = m0 - MP + 4 * fq + j;
;                     const float h0 = p->in[4][(size_t)(l * MS + sb) * D + ch];
;                     const float h = a * h0 + mult * ig * xc;
;                     const size_t o = (size_t)(m0 + 4 * fq + j) * D + ch; HLOC[o] = (bf16_t)(cvt_pk_bf16(h, 0.f) & 0xffffu); PCUM[o] = 0;
;                     p->out[O_SRG + (size_t)(l * MS + sb) * D + ch] = h; }
;             }
	v_add_f32_e32 v70, v70, v76
	v_mul_f32_e32 v70, 0xbfb8aa3b, v70
	v_exp_f32_e32 v70, v70
	v_add_f32_e32 v66, v66, v77
	v_mul_f32_e32 v66, 0xbfb8aa3b, v66
	v_exp_f32_e32 v66, v66
	v_add_f32_e32 v70, 1.0, v70
	v_rcp_f32_e32 v70, v70
	v_add_f32_e32 v67, v67, v77
	v_add_f32_e32 v66, 1.0, v66
	v_rcp_f32_e32 v66, v66
	v_mul_f32_e32 v70, 0xc1000000, v70
	s_waitcnt lgkmcnt(1)
	v_mul_f32_e32 v70, v79, v70
	v_mul_f32_e32 v70, 0x3fb8aa3b, v70
	v_exp_f32_e32 v70, v70
	v_mul_f32_e32 v67, 0xbfb8aa3b, v67
	v_exp_f32_e32 v67, v67
	v_or_b32_e32 v100, v100, v78
	v_fma_f32 v75, -v70, v70, 1.0
	v_max_f32_e32 v75, 0, v75
	v_add_f32_e32 v67, 1.0, v67
	v_rcp_f32_e32 v67, v67
	v_add_f32_e32 v68, v68, v77
	v_mul_f32_e32 v68, 0xbfb8aa3b, v68
	v_exp_f32_e32 v68, v68
	s_nop 0
	v_add_f32_e32 v68, 1.0, v68
	v_rcp_f32_e32 v68, v68
	v_or_b32_e32 v104, v104, v78
	v_or_b32_e32 v96, v96, v78
	v_sqrt_f32_e32 v75, v75
	s_nop 0
	global_load_dword v80, v[106:107], off offset:192
	v_mul_f32_e32 v66, v66, v75
	s_waitcnt lgkmcnt(0)
	v_mul_f32_e32 v66, v74, v66
	v_lshlrev_b64 v[74:75], 1, v[102:103]
	s_waitcnt vmcnt(0)
	v_fmac_f32_e32 v66, v80, v70
	v_cvt_pk_bf16_f32 v70, v66, v1
	v_lshl_add_u64 v[80:81], v[74:75], 1, s[62:63]
	global_store_dword v[80:81], v70, off
	v_add_f32_e32 v70, v71, v76
	v_mul_f32_e32 v70, 0xbfb8aa3b, v70
	v_exp_f32_e32 v70, v70
	v_lshlrev_b32_e32 v74, 2, v78
	v_add_f32_e32 v70, 1.0, v70
	v_rcp_f32_e32 v70, v70
	v_mov_b32_e32 v75, v1
	v_lshl_add_u64 v[80:81], v[98:99], 0, v[74:75]
	global_store_dword v[80:81], v66, off
	v_mul_f32_e32 v70, 0xc1000000, v70
	v_mul_f32_e32 v70, v79, v70
	v_mul_f32_e32 v70, 0x3fb8aa3b, v70
	v_exp_f32_e32 v70, v70
	ds_read_b32 v66, v241 offset:464
	v_fma_f32 v71, -v70, v70, 1.0
	v_max_f32_e32 v71, 0, v71
	s_nop 0
	s_nop 0
	s_nop 0
	s_nop 1
	s_nop 1
	v_sqrt_f32_e32 v71, v71
	s_nop 0
	global_load_dword v80, v[82:83], off offset:192
	v_mul_f32_e32 v67, v67, v71
	s_waitcnt lgkmcnt(0)
	v_mul_f32_e32 v81, v66, v67
	v_lshlrev_b64 v[66:67], 1, v[100:101]
	s_waitcnt vmcnt(0)
	v_fmac_f32_e32 v81, v70, v80
	v_lshl_add_u64 v[70:71], v[66:67], 1, s[62:63]
	v_cvt_pk_bf16_f32 v80, v81, v1
	v_lshl_add_u64 v[66:67], v[90:91], 0, v[74:75]
	global_store_dword v[66:67], v81, off
	v_add_f32_e32 v67, v72, v76
	v_mul_f32_e32 v67, 0xbfb8aa3b, v67
	v_exp_f32_e32 v67, v67
	global_store_dword v[70:71], v80, off
	ds_read_b32 v66, v241 offset:736
	v_add_f32_e32 v67, 1.0, v67
	v_rcp_f32_e32 v67, v67
	s_nop 0
	v_mul_f32_e32 v67, 0xc1000000, v67
	v_mul_f32_e32 v67, v79, v67
	v_mul_f32_e32 v67, 0x3fb8aa3b, v67
	v_exp_f32_e32 v67, v67
	s_nop 0
	v_fma_f32 v70, -v67, v67, 1.0
	v_max_f32_e32 v70, 0, v70
	s_nop 0
	s_nop 0
	s_nop 0
	s_nop 1
	s_nop 1
	v_sqrt_f32_e32 v70, v70
	s_nop 0
	global_load_dword v71, v[86:87], off offset:192
	s_waitcnt vmcnt(0)
	v_mul_f32_e32 v72, v67, v71
	v_mul_f32_e32 v67, v68, v70
	s_waitcnt lgkmcnt(0)
	v_fmac_f32_e32 v72, v67, v66
	v_lshlrev_b64 v[66:67], 1, v[104:105]
	v_lshl_add_u64 v[70:71], v[66:67], 1, s[62:63]
	v_cvt_pk_bf16_f32 v68, v72, v1
	v_lshl_add_u64 v[66:67], v[94:95], 0, v[74:75]
	global_store_dword v[66:67], v72, off
	v_add_f32_e32 v67, v73, v76
	v_mul_f32_e32 v67, 0xbfb8aa3b, v67
	v_exp_f32_e32 v67, v67
	global_store_dword v[70:71], v68, off
	v_add_f32_e32 v68, v69, v77
	v_mul_f32_e32 v68, 0xbfb8aa3b, v68
	v_add_f32_e32 v67, 1.0, v67
	v_rcp_f32_e32 v67, v67
	v_exp_f32_e32 v68, v68
	ds_read_b32 v66, v241 offset:1008
	v_mul_f32_e32 v67, 0xc1000000, v67
	v_mul_f32_e32 v67, v79, v67
	v_mul_f32_e32 v67, 0x3fb8aa3b, v67
	v_exp_f32_e32 v67, v67
	v_add_f32_e32 v68, 1.0, v68
	v_rcp_f32_e32 v68, v68
	v_fma_f32 v69, -v67, v67, 1.0
	v_max_f32_e32 v69, 0, v69
	s_nop 0
	s_nop 0
	s_nop 0
	s_nop 1
	s_nop 1
	v_sqrt_f32_e32 v69, v69
	s_nop 0
	global_load_dword v70, v[84:85], off offset:192
	s_waitcnt vmcnt(0)
	v_mul_f32_e32 v70, v67, v70
	v_mul_f32_e32 v67, v68, v69
	s_waitcnt lgkmcnt(0)
	v_fmac_f32_e32 v70, v67, v66
	v_lshlrev_b64 v[66:67], 1, v[96:97]
	v_lshl_add_u64 v[68:69], v[66:67], 1, s[62:63]
	v_cvt_pk_bf16_f32 v71, v70, v1
	v_lshl_add_u64 v[66:67], v[92:93], 0, v[74:75]
	global_store_dword v[68:69], v71, off
	global_store_dword v[66:67], v70, off
	s_cbranch_execnz .LBB0_330
	s_branch .LBB0_334

; #define LAS __attribute__((address_space(3)))
; #define LDS_WAIT() asm volatile("s_waitcnt lgkmcnt(0)" ::: "memory")
; template <int NT> ...
;     ...
;     for (int u = 0; u < NT; ++u) { const int m = m0 + 16 * u + rr, t = m - b * TP;
; #pragma unroll
;         for (int k = 0; k < 4; ++k) {
;             if (t - 3 + k >= 0) { const bf16_t* src = P + (size_t)(m - 3 + k) * DP + C_XR + hc0 + cl; raw[u][k][0] = *(const u32x4*)src; raw[u][k][1] = *(const u32x4*)(src + 8); }
;             else { raw[u][k][0] = (u32x4){0u, 0u, 0u, 0u}; raw[u][k][1] = (u32x4){0u, 0u, 0u, 0u}; } } }
;     LDS_WAIT();
; #pragma unroll
;     for (int u = 0; u < NT; ++u) { const int m = m0 + 16 * u + rr, t = m - b * TP; LAS float* XC = XCb + u * (16 * 68);
;         float xv[4][16];
; #pragma unroll
;         for (int k = 0; k < 4; ++k) { float f0[8], f1[8]; unpack8(raw[u][k][0], f0); unpack8(raw[u][k][1], f1);
; #pragma unroll
;             for (int e = 0; e < 8; ++e) { xv[k][e] = f0[e]; xv[k][8 + e] = f1[e]; } }
;         if (t >= TP - 3) { float* o = p->out + O_PCB + ((size_t)(l * NB + b) * 3 + (t - (TP - 3))) * D + hc0 + cl;
; #pragma unroll
;             for (int e = 0; e < 16; e += 4) *(f32x4*)(o + e) = (f32x4){xv[3][e], xv[3][e + 1], xv[3][e + 2], xv[3][e + 3]}; }
; #pragma unroll
;         for (int e = 0; e < 16; e += 4) {
;             const f32x4 w0 = *(const LAS f32x4*)(CST + 0 * 64 + cl + e), w1 = *(const LAS f32x4*)(CST + 1 * 64 + cl + e), w2 = *(const LAS f32x4*)(CST + 2 * 64 + cl + e),
;                         w3 = *(const LAS f32x4*)(CST + 3 * 64 + cl + e), bb = *(const LAS f32x4*)(CST + 4 * 64 + cl + e);
;             f32x4 r;
; #pragma unroll
;             for (int q = 0; q < 4; ++q) r[q] = w0[q] * xv[0][e + q] + w1[q] * xv[1][e + q] + w2[q] * xv[2][e + q] + w3[q] * xv[3][e + q] + bb[q];
;             *(LAS f32x4*)(XC + rr * 68 + cl + e) = r;
;         } }
.LBB0_335:
	s_or_b64 exec, exec, s[10:11]
	v_mov_b64_e32 v[84:85], s[60:61]
	v_mad_i64_i32 v[86:87], s[10:11], v82, s33, v[84:85]
	s_lshl_b32 s16, s75, 1
	v_lshl_add_u64 v[86:87], v[86:87], 0, s[16:17]
	v_lshl_add_u64 v[86:87], v[86:87], 0, v[0:1]
	v_add_co_u32_e32 v88, vcc, s38, v86
	v_add_u32_e32 v83, 13, v82
	s_nop 0
	v_addc_co_u32_e32 v89, vcc, 0, v87, vcc
	global_load_dwordx4 v[170:173], v[88:89], off
	v_lshl_add_u64 v[86:87], v[86:87], 0, s[28:29]
	global_load_dwordx4 v[136:139], v[86:87], off offset:16
	v_add_u32_e32 v92, 16, v82
	v_add_u32_e32 v88, 14, v82
	v_add_u32_e32 v90, 15, v82
	v_mad_i64_i32 v[82:83], s[10:11], v83, s33, v[84:85]
	v_lshl_add_u64 v[82:83], v[82:83], 0, s[16:17]
	v_mad_i64_i32 v[88:89], s[10:11], v88, s33, v[84:85]
	v_lshl_add_u64 v[82:83], v[82:83], 0, v[0:1]
	v_mad_i64_i32 v[90:91], s[10:11], v90, s33, v[84:85]
	v_mad_i64_i32 v[84:85], s[10:11], v92, s33, v[84:85]
	v_lshl_add_u64 v[88:89], v[88:89], 0, s[16:17]
	v_lshl_add_u64 v[92:93], v[82:83], 0, s[28:29]
	v_add_co_u32_e32 v82, vcc, s38, v82
	v_lshl_add_u64 v[88:89], v[88:89], 0, v[0:1]
	s_nop 0
	v_addc_co_u32_e32 v83, vcc, 0, v83, vcc
	v_lshl_add_u64 v[90:91], v[90:91], 0, s[16:17]
	v_add_co_u32_e32 v86, vcc, s38, v88
	v_lshl_add_u64 v[90:91], v[90:91], 0, v[0:1]
	s_nop 0
	v_addc_co_u32_e32 v87, vcc, 0, v89, vcc
	v_lshl_add_u64 v[84:85], v[84:85], 0, s[16:17]
	v_lshl_add_u64 v[96:97], v[90:91], 0, s[28:29]
	v_add_co_u32_e32 v90, vcc, s38, v90
	v_lshl_add_u64 v[84:85], v[84:85], 0, v[0:1]
	s_nop 0
	v_addc_co_u32_e32 v91, vcc, 0, v91, vcc
	v_add_co_u32_e32 v118, vcc, s38, v84
	v_lshl_add_u64 v[94:95], v[88:89], 0, s[28:29]
	s_nop 0
	v_addc_co_u32_e32 v119, vcc, 0, v85, vcc
	s_waitcnt vmcnt(3)
	v_lshlrev_b32_e32 v154, 16, v120
	v_and_b32_e32 v155, 0xffff0000, v120
	v_lshlrev_b32_e32 v158, 16, v121
	v_and_b32_e32 v159, 0xffff0000, v121
	v_lshl_add_u64 v[128:129], v[84:85], 0, s[28:29]
	global_load_dwordx4 v[106:109], v[82:83], off
	s_nop 0
	global_load_dwordx4 v[82:85], v[92:93], off offset:16
	global_load_dwordx4 v[110:113], v[86:87], off
	s_nop 0
	global_load_dwordx4 v[86:89], v[94:95], off offset:16
	global_load_dwordx4 v[114:117], v[90:91], off
	s_nop 0
	global_load_dwordx4 v[90:93], v[96:97], off offset:16
	s_nop 0
	global_load_dwordx4 v[118:121], v[118:119], off
	s_nop 0
	global_load_dwordx4 v[94:97], v[128:129], off offset:16
	s_waitcnt lgkmcnt(0)
	ds_read_b128 v[128:131], v227 offset:8704
	ds_read_b128 v[132:135], v227 offset:8960
	ds_read_b128 v[140:143], v227 offset:9216
	ds_read_b128 v[144:147], v227 offset:9472
	ds_read_b128 v[148:151], v227 offset:9728
	v_lshlrev_b32_e32 v156, 16, v102
	v_and_b32_e32 v157, 0xffff0000, v102
	v_lshlrev_b32_e32 v152, 16, v124
	s_waitcnt lgkmcnt(3)
	v_pk_mul_f32 v[154:155], v[132:133], v[154:155]
	v_and_b32_e32 v153, 0xffff0000, v124
	v_pk_fma_f32 v[154:155], v[128:129], v[156:157], v[154:155]
	v_lshlrev_b32_e32 v102, 16, v103
	s_waitcnt lgkmcnt(2)
	v_pk_fma_f32 v[152:153], v[140:141], v[152:153], v[154:155]
	v_and_b32_e32 v103, 0xffff0000, v103
	v_lshlrev_b32_e32 v124, 16, v125
	v_and_b32_e32 v125, 0xffff0000, v125
	v_lshlrev_b32_e32 v174, 16, v122
	v_and_b32_e32 v175, 0xffff0000, v122
	v_lshlrev_b32_e32 v176, 16, v104
	v_and_b32_e32 v177, 0xffff0000, v104
	v_lshlrev_b32_e32 v122, 16, v123
	v_and_b32_e32 v123, 0xffff0000, v123
	v_lshlrev_b32_e32 v104, 16, v105
	v_and_b32_e32 v105, 0xffff0000, v105
	s_waitcnt vmcnt(10)
	v_lshlrev_b32_e32 v186, 16, v78
	v_and_b32_e32 v187, 0xffff0000, v78
	v_lshlrev_b32_e32 v188, 16, v74
	v_and_b32_e32 v189, 0xffff0000, v74
	v_lshlrev_b32_e32 v184, 16, v98
	v_and_b32_e32 v185, 0xffff0000, v98
	v_lshlrev_b32_e32 v78, 16, v79
	v_and_b32_e32 v79, 0xffff0000, v79
	v_lshlrev_b32_e32 v74, 16, v75
	v_and_b32_e32 v75, 0xffff0000, v75
	v_lshlrev_b32_e32 v98, 16, v99
	s_waitcnt vmcnt(9)
	v_lshlrev_b32_e32 v154, 16, v170
	v_and_b32_e32 v155, 0xffff0000, v170
	s_waitcnt lgkmcnt(1)
	v_pk_fma_f32 v[152:153], v[144:145], v[154:155], v[152:153]
	v_pk_mul_f32 v[154:155], v[134:135], v[158:159]
	v_lshlrev_b32_e32 v156, 16, v171
	v_pk_fma_f32 v[102:103], v[130:131], v[102:103], v[154:155]
	v_and_b32_e32 v157, 0xffff0000, v171
	v_pk_fma_f32 v[102:103], v[142:143], v[124:125], v[102:103]
	s_waitcnt lgkmcnt(0)
	v_pk_add_f32 v[152:153], v[148:149], v[152:153]
	v_pk_fma_f32 v[102:103], v[146:147], v[156:157], v[102:103]
	v_lshlrev_b32_e32 v124, 16, v126
	v_pk_add_f32 v[154:155], v[150:151], v[102:103]
	ds_write_b128 v240, v[152:155]
	ds_read_b128 v[152:155], v227 offset:8720
	ds_read_b128 v[168:171], v227 offset:8976
	ds_read_b128 v[156:159], v227 offset:9232
	ds_read_b128 v[160:163], v227 offset:9488
	ds_read_b128 v[164:167], v227 offset:9744
	v_and_b32_e32 v125, 0xffff0000, v126
	s_waitcnt lgkmcnt(3)
	v_pk_mul_f32 v[174:175], v[168:169], v[174:175]
	v_pk_mul_f32 v[122:123], v[170:171], v[122:123]
	v_pk_fma_f32 v[174:175], v[152:153], v[176:177], v[174:175]
	v_lshlrev_b32_e32 v102, 16, v172
	v_and_b32_e32 v103, 0xffff0000, v172
	s_waitcnt lgkmcnt(2)
	v_pk_fma_f32 v[124:125], v[156:157], v[124:125], v[174:175]
	v_lshlrev_b32_e32 v126, 16, v127
	v_and_b32_e32 v127, 0xffff0000, v127
	v_pk_fma_f32 v[104:105], v[154:155], v[104:105], v[122:123]
	s_waitcnt lgkmcnt(1)
	v_pk_fma_f32 v[102:103], v[160:161], v[102:103], v[124:125]
	v_lshlrev_b32_e32 v124, 16, v173
	v_and_b32_e32 v125, 0xffff0000, v173
	v_pk_fma_f32 v[104:105], v[158:159], v[126:127], v[104:105]
	s_waitcnt lgkmcnt(0)
	v_pk_add_f32 v[102:103], v[164:165], v[102:103]
	v_pk_fma_f32 v[104:105], v[162:163], v[124:125], v[104:105]
	s_waitcnt vmcnt(8)
; #define LAS __attribute__((address_space(3)))
; template <int NT> ...
;     ...
;     for (int u = 0; u < NT; ++u) { const int m = m0 + 16 * u + rr, t = m - b * TP; LAS float* XC = XCb + u * (16 * 68);
;         float xv[4][16];
; #pragma unroll
;         for (int k = 0; k < 4; ++k) { float f0[8], f1[8]; unpack8(raw[u][k][0], f0); unpack8(raw[u][k][1], f1);
; #pragma unroll
;             for (int e = 0; e < 8; ++e) { xv[k][e] = f0[e]; xv[k][8 + e] = f1[e]; } }
;         if (t >= TP - 3) { float* o = p->out + O_PCB + ((size_t)(l * NB + b) * 3 + (t - (TP - 3))) * D + hc0 + cl;
; #pragma unroll
;             for (int e = 0; e < 16; e += 4) *(f32x4*)(o + e) = (f32x4){xv[3][e], xv[3][e + 1], xv[3][e + 2], xv[3][e + 3]}; }
; #pragma unroll
;         for (int e = 0; e < 16; e += 4) {
;             const f32x4 w0 = *(const LAS f32x4*)(CST + 0 * 64 + cl + e), w1 = *(const LAS f32x4*)(CST + 1 * 64 + cl + e), w2 = *(const LAS f32x4*)(CST + 2 * 64 + cl + e),
;                         w3 = *(const LAS f32x4*)(CST + 3 * 64 + cl + e), bb = *(const LAS f32x4*)(CST + 4 * 64 + cl + e);
;             f32x4 r;
; #pragma unroll
;             for (int q = 0; q < 4; ++q) r[q] = w0[q] * xv[0][e + q] + w1[q] * xv[1][e + q] + w2[q] * xv[2][e + q] + w3[q] * xv[3][e + q] + bb[q];
;             *(LAS f32x4*)(XC + rr * 68 + cl + e) = r;
;         } }
	v_lshlrev_b32_e32 v126, 16, v136
	v_pk_add_f32 v[104:105], v[166:167], v[104:105]
	ds_write_b128 v240, v[102:105] offset:16
	ds_read_b128 v[102:105], v227 offset:8736
	ds_read_b128 v[180:183], v227 offset:8992
	ds_read_b128 v[122:125], v227 offset:9248
	ds_read_b128 v[172:175], v227 offset:9504
	ds_read_b128 v[176:179], v227 offset:9760
	v_and_b32_e32 v127, 0xffff0000, v136
	s_waitcnt lgkmcnt(3)
	v_pk_mul_f32 v[186:187], v[180:181], v[186:187]
	v_pk_mul_f32 v[78:79], v[182:183], v[78:79]
	v_pk_fma_f32 v[186:187], v[102:103], v[188:189], v[186:187]
	v_and_b32_e32 v99, 0xffff0000, v99
	s_waitcnt lgkmcnt(2)
	v_pk_fma_f32 v[184:185], v[122:123], v[184:185], v[186:187]
	v_pk_fma_f32 v[74:75], v[104:105], v[74:75], v[78:79]
	s_waitcnt lgkmcnt(1)
	v_pk_fma_f32 v[126:127], v[172:173], v[126:127], v[184:185]
	v_pk_fma_f32 v[74:75], v[124:125], v[98:99], v[74:75]
	s_waitcnt lgkmcnt(0)
	v_pk_add_f32 v[184:185], v[176:177], v[126:127]
	v_lshlrev_b32_e32 v126, 16, v137
	v_and_b32_e32 v127, 0xffff0000, v137
	v_pk_fma_f32 v[74:75], v[174:175], v[126:127], v[74:75]
	v_lshlrev_b32_e32 v78, 16, v76
	v_pk_add_f32 v[186:187], v[178:179], v[74:75]
	ds_write_b128 v240, v[184:187] offset:32
	ds_read_b128 v[184:187], v227 offset:8752
	ds_read_b128 v[200:203], v227 offset:9008
	ds_read_b128 v[188:191], v227 offset:9264
	ds_read_b128 v[192:195], v227 offset:9520
	ds_read_b128 v[196:199], v227 offset:9776
	v_lshlrev_b32_e32 v74, 16, v80
	v_and_b32_e32 v75, 0xffff0000, v80
	v_and_b32_e32 v79, 0xffff0000, v76
	s_waitcnt lgkmcnt(3)
	v_pk_mul_f32 v[74:75], v[200:201], v[74:75]
	v_lshlrev_b32_e32 v80, 16, v81
	v_and_b32_e32 v81, 0xffff0000, v81
	v_pk_fma_f32 v[74:75], v[184:185], v[78:79], v[74:75]
	v_lshlrev_b32_e32 v78, 16, v100
	v_and_b32_e32 v79, 0xffff0000, v100
	v_lshlrev_b32_e32 v76, 16, v77
	v_and_b32_e32 v77, 0xffff0000, v77
	v_pk_mul_f32 v[80:81], v[202:203], v[80:81]
	s_waitcnt lgkmcnt(2)
	v_pk_fma_f32 v[74:75], v[188:189], v[78:79], v[74:75]
	v_lshlrev_b32_e32 v78, 16, v138
	v_and_b32_e32 v79, 0xffff0000, v138
	v_lshlrev_b32_e32 v98, 16, v101
	v_and_b32_e32 v99, 0xffff0000, v101
	v_pk_fma_f32 v[76:77], v[186:187], v[76:77], v[80:81]
	s_waitcnt lgkmcnt(1)
	v_pk_fma_f32 v[74:75], v[192:193], v[78:79], v[74:75]
	v_lshlrev_b32_e32 v78, 16, v139
	v_and_b32_e32 v79, 0xffff0000, v139
	v_pk_fma_f32 v[76:77], v[190:191], v[98:99], v[76:77]
	s_waitcnt vmcnt(7)
	v_lshlrev_b32_e32 v80, 16, v106
	v_pk_fma_f32 v[76:77], v[194:195], v[78:79], v[76:77]
	s_waitcnt vmcnt(5)
	v_lshlrev_b32_e32 v78, 16, v110
	v_and_b32_e32 v79, 0xffff0000, v110
	v_and_b32_e32 v81, 0xffff0000, v106
	v_pk_mul_f32 v[78:79], v[132:133], v[78:79]
	s_waitcnt lgkmcnt(0)
	v_pk_add_f32 v[74:75], v[196:197], v[74:75]
	v_pk_add_f32 v[76:77], v[198:199], v[76:77]
	v_pk_fma_f32 v[78:79], v[128:129], v[80:81], v[78:79]
	v_lshlrev_b32_e32 v80, 16, v111
	v_and_b32_e32 v81, 0xffff0000, v111
	ds_write_b128 v240, v[74:77] offset:48
	s_waitcnt vmcnt(3)
	v_lshlrev_b32_e32 v76, 16, v114
	v_and_b32_e32 v77, 0xffff0000, v114
	v_lshlrev_b32_e32 v98, 16, v107
	v_and_b32_e32 v99, 0xffff0000, v107
	v_pk_mul_f32 v[80:81], v[134:135], v[80:81]
	s_waitcnt vmcnt(1)
	v_lshlrev_b32_e32 v74, 16, v118
	v_and_b32_e32 v75, 0xffff0000, v118
	v_pk_fma_f32 v[76:77], v[140:141], v[76:77], v[78:79]
	v_lshlrev_b32_e32 v78, 16, v115
	v_and_b32_e32 v79, 0xffff0000, v115
	v_pk_fma_f32 v[80:81], v[130:131], v[98:99], v[80:81]
	v_pk_fma_f32 v[74:75], v[144:145], v[74:75], v[76:77]
	v_lshlrev_b32_e32 v76, 16, v119
	v_and_b32_e32 v77, 0xffff0000, v119
	v_pk_fma_f32 v[78:79], v[142:143], v[78:79], v[80:81]
	v_lshlrev_b32_e32 v80, 16, v108
	v_pk_fma_f32 v[76:77], v[146:147], v[76:77], v[78:79]
	v_lshlrev_b32_e32 v78, 16, v112
	v_and_b32_e32 v79, 0xffff0000, v112
	v_and_b32_e32 v81, 0xffff0000, v108
	v_pk_mul_f32 v[78:79], v[168:169], v[78:79]
	v_pk_add_f32 v[74:75], v[148:149], v[74:75]
	v_pk_add_f32 v[76:77], v[150:151], v[76:77]
	v_pk_fma_f32 v[78:79], v[152:153], v[80:81], v[78:79]
	v_lshlrev_b32_e32 v80, 16, v113
	v_and_b32_e32 v81, 0xffff0000, v113
	ds_write_b128 v240, v[74:77] offset:4352
	v_lshlrev_b32_e32 v76, 16, v116
	v_and_b32_e32 v77, 0xffff0000, v116
	v_lshlrev_b32_e32 v98, 16, v109
	v_and_b32_e32 v99, 0xffff0000, v109
	v_pk_mul_f32 v[80:81], v[170:171], v[80:81]
	v_lshlrev_b32_e32 v74, 16, v120
	v_and_b32_e32 v75, 0xffff0000, v120
	v_pk_fma_f32 v[76:77], v[156:157], v[76:77], v[78:79]
	v_lshlrev_b32_e32 v78, 16, v117
	v_and_b32_e32 v79, 0xffff0000, v117
	v_pk_fma_f32 v[80:81], v[154:155], v[98:99], v[80:81]
	v_pk_fma_f32 v[74:75], v[160:161], v[74:75], v[76:77]
	v_lshlrev_b32_e32 v76, 16, v121
	v_and_b32_e32 v77, 0xffff0000, v121
	v_pk_fma_f32 v[78:79], v[158:159], v[78:79], v[80:81]
	v_lshlrev_b32_e32 v80, 16, v82
	v_pk_fma_f32 v[76:77], v[162:163], v[76:77], v[78:79]
	v_lshlrev_b32_e32 v78, 16, v86
	v_and_b32_e32 v79, 0xffff0000, v86
	v_and_b32_e32 v81, 0xffff0000, v82
	v_pk_mul_f32 v[78:79], v[180:181], v[78:79]
	v_pk_add_f32 v[74:75], v[164:165], v[74:75]
	v_pk_add_f32 v[76:77], v[166:167], v[76:77]
	v_pk_fma_f32 v[78:79], v[102:103], v[80:81], v[78:79]
	v_lshlrev_b32_e32 v80, 16, v87
	v_and_b32_e32 v81, 0xffff0000, v87
	ds_write_b128 v240, v[74:77] offset:4368
	v_lshlrev_b32_e32 v76, 16, v90
	v_and_b32_e32 v77, 0xffff0000, v90
	v_lshlrev_b32_e32 v82, 16, v83
	v_and_b32_e32 v83, 0xffff0000, v83
	v_pk_mul_f32 v[80:81], v[182:183], v[80:81]
	s_waitcnt vmcnt(0)
; #define LAS __attribute__((address_space(3)))
; template <int NT> ...
;     ...
;         for (int e = 0; e < 16; e += 4) {
;             const f32x4 w0 = *(const LAS f32x4*)(CST + 0 * 64 + cl + e), w1 = *(const LAS f32x4*)(CST + 1 * 64 + cl + e), w2 = *(const LAS f32x4*)(CST + 2 * 64 + cl + e),
;                         w3 = *(const LAS f32x4*)(CST + 3 * 64 + cl + e), bb = *(const LAS f32x4*)(CST + 4 * 64 + cl + e);
;             f32x4 r;
; #pragma unroll
;             for (int q = 0; q < 4; ++q) r[q] = w0[q] * xv[0][e + q] + w1[q] * xv[1][e + q] + w2[q] * xv[2][e + q] + w3[q] * xv[3][e + q] + bb[q];
;             *(LAS f32x4*)(XC + rr * 68 + cl + e) = r;
;         } }
;     LDS_WAIT();
;     f32x4 ar[NT][4], ai[NT][4];
; #pragma unroll
;     for (int u = 0; u < NT; ++u) { const LAS float* XC = XCb + u * (16 * 68);
; #pragma unroll
;         for (int n = 0; n < 4; ++n) { ar[u][n] = (f32x4){0.f, 0.f, 0.f, 0.f}; ai[u][n] = (f32x4){0.f, 0.f, 0.f, 0.f}; }
; #pragma unroll
;         for (int s = 0; s < 2; ++s) {
;             const f32x4 x0 = *(const LAS f32x4*)(XC + fr * 68 + 32 * s + 8 * fq), x1 = *(const LAS f32x4*)(XC + fr * 68 + 32 * s + 8 * fq + 4);
;             u32x4 aw; aw.x = cvt_pk_bf16(x0[0], x0[1]); aw.y = cvt_pk_bf16(x0[2], x0[3]); aw.z = cvt_pk_bf16(x1[0], x1[1]); aw.w = cvt_pk_bf16(x1[2], x1[3]);
;             const bf16x8 af = __builtin_bit_cast(bf16x8, aw);
; #pragma unroll
;             for (int n = 0; n < 4; ++n) { ar[u][n] = __builtin_amdgcn_mfma_f32_16x16x32_bf16(af, Wa[n][s], ar[u][n], 0, 0, 0); ai[u][n] = __builtin_amdgcn_mfma_f32_16x16x32_bf16(af, Wx[n][s], ai[u][n], 0, 0, 0); }
;         } }
;     float av[NT][4][4], bv[NT][4][4];
; #pragma unroll
;     for (int u = 0; u < NT; ++u) { const LAS float* XC = XCb + u * (16 * 68); const int t0 = m0 + 16 * u - b * TP;
; #pragma unroll
;         for (int n = 0; n < 4; ++n) { const int cc = 16 * n + fr;
;             const float ba = CST[5 * 64 + cc], bx = CST[6 * 64 + cc], sp = CST[7 * 64 + cc];
; #pragma unroll
;             for (int j = 0; j < 4; ++j) {
;                 const float xc = XC[(4 * fq + j) * 68 + cc];
;                 const float r = sigmoidf_(ar[u][n][j] + ba), ig = sigmoidf_(ai[u][n][j] + bx);
;                 const float a = __expf(-8.0f * r * sp);
;                 float mult = sqrtf(fmaxf(1.0f - a * a, 0.f));
;                 if (t0 + 4 * fq + j == 0) mult = 1.0f;
	v_lshlrev_b32_e32 v74, 16, v94
	v_and_b32_e32 v75, 0xffff0000, v94
	v_pk_fma_f32 v[76:77], v[122:123], v[76:77], v[78:79]
	v_lshlrev_b32_e32 v78, 16, v91
	v_and_b32_e32 v79, 0xffff0000, v91
	v_pk_fma_f32 v[80:81], v[104:105], v[82:83], v[80:81]
	v_pk_fma_f32 v[74:75], v[172:173], v[74:75], v[76:77]
	v_lshlrev_b32_e32 v76, 16, v95
	v_and_b32_e32 v77, 0xffff0000, v95
	v_pk_fma_f32 v[78:79], v[124:125], v[78:79], v[80:81]
	v_lshlrev_b32_e32 v80, 16, v84
	v_pk_fma_f32 v[76:77], v[174:175], v[76:77], v[78:79]
	v_lshlrev_b32_e32 v78, 16, v88
	v_and_b32_e32 v79, 0xffff0000, v88
	v_and_b32_e32 v81, 0xffff0000, v84
	v_pk_mul_f32 v[78:79], v[200:201], v[78:79]
	v_pk_add_f32 v[74:75], v[176:177], v[74:75]
	v_pk_add_f32 v[76:77], v[178:179], v[76:77]
	v_pk_fma_f32 v[78:79], v[184:185], v[80:81], v[78:79]
	v_lshlrev_b32_e32 v80, 16, v89
	v_and_b32_e32 v81, 0xffff0000, v89
	ds_write_b128 v240, v[74:77] offset:4384
	v_lshlrev_b32_e32 v76, 16, v92
	v_and_b32_e32 v77, 0xffff0000, v92
	v_lshlrev_b32_e32 v82, 16, v85
	v_and_b32_e32 v83, 0xffff0000, v85
	v_pk_mul_f32 v[80:81], v[202:203], v[80:81]
	v_lshlrev_b32_e32 v74, 16, v96
	v_and_b32_e32 v75, 0xffff0000, v96
	v_pk_fma_f32 v[76:77], v[188:189], v[76:77], v[78:79]
	v_lshlrev_b32_e32 v78, 16, v93
	v_and_b32_e32 v79, 0xffff0000, v93
	v_pk_fma_f32 v[80:81], v[186:187], v[82:83], v[80:81]
	v_pk_fma_f32 v[74:75], v[192:193], v[74:75], v[76:77]
	v_lshlrev_b32_e32 v76, 16, v97
	v_and_b32_e32 v77, 0xffff0000, v97
	v_pk_fma_f32 v[78:79], v[190:191], v[78:79], v[80:81]
	v_pk_add_f32 v[74:75], v[196:197], v[74:75]
	v_pk_fma_f32 v[76:77], v[194:195], v[76:77], v[78:79]
	v_add_u32_e32 v177, 0x2400, v232
	v_pk_add_f32 v[76:77], v[198:199], v[76:77]
	ds_write_b128 v240, v[74:77] offset:4400
	s_waitcnt lgkmcnt(0)
	ds_read_b128 v[74:77], v239
	ds_read_b128 v[78:81], v239 offset:16
	s_waitcnt lgkmcnt(1)
	v_cvt_pk_bf16_f32 v74, v74, v75
	v_cvt_pk_bf16_f32 v75, v76, v77
	s_waitcnt lgkmcnt(0)
	v_cvt_pk_bf16_f32 v76, v78, v79
	v_cvt_pk_bf16_f32 v77, v80, v81
	ds_read_b128 v[106:109], v239 offset:128
	ds_read_b128 v[110:113], v239 offset:144
	v_mfma_f32_16x16x32_bf16 v[78:81], v[74:77], v[34:37], 0
	s_waitcnt lgkmcnt(1)
	v_cvt_pk_bf16_f32 v106, v106, v107
	v_mfma_f32_16x16x32_bf16 v[82:85], v[74:77], v[38:41], 0
	v_cvt_pk_bf16_f32 v107, v108, v109
	s_waitcnt lgkmcnt(0)
	v_cvt_pk_bf16_f32 v108, v110, v111
	v_cvt_pk_bf16_f32 v109, v112, v113
	v_mfma_f32_16x16x32_bf16 v[86:89], v[74:77], v[42:45], 0
	v_add_u32_e32 v176, 0x2800, v232
	s_add_i32 s21, s21, 2
	v_add_u32_e32 v243, 32, v243
	v_mfma_f32_16x16x32_bf16 v[132:135], v[106:109], v[10:13], v[78:81]
	s_cmp_gt_u32 s21, 5
	v_subrev_u32_e32 v244, 32, v244
	v_mfma_f32_16x16x32_bf16 v[140:143], v[106:109], v[14:17], v[82:85]
	ds_read_b128 v[78:81], v239 offset:4352
	s_nop 1
	ds_read_b128 v[82:85], v239 offset:4368
	v_mfma_f32_16x16x32_bf16 v[90:93], v[74:77], v[46:49], 0
	v_mfma_f32_16x16x32_bf16 v[94:97], v[74:77], v[50:53], 0
	v_mfma_f32_16x16x32_bf16 v[98:101], v[74:77], v[54:57], 0
	v_mfma_f32_16x16x32_bf16 v[102:105], v[74:77], v[62:65], 0
	v_mfma_f32_16x16x32_bf16 v[74:77], v[74:77], v[58:61], 0
	v_mfma_f32_16x16x32_bf16 v[126:129], v[106:109], v[22:25], v[86:89]
	v_mfma_f32_16x16x32_bf16 v[122:125], v[106:109], v[26:29], v[90:93]
	v_mfma_f32_16x16x32_bf16 v[118:121], v[106:109], v[30:33], v[94:97]
	v_mfma_f32_16x16x32_bf16 v[114:117], v[106:109], v[18:21], v[98:101]
	v_mfma_f32_16x16x32_bf16 v[110:113], v[106:109], v[6:9], v[102:105]
	v_mfma_f32_16x16x32_bf16 v[106:109], v[106:109], v[2:5], v[74:77]
	s_waitcnt lgkmcnt(1)
	v_cvt_pk_bf16_f32 v74, v78, v79
	v_cvt_pk_bf16_f32 v75, v80, v81
	s_waitcnt lgkmcnt(0)
	v_cvt_pk_bf16_f32 v76, v82, v83
	v_cvt_pk_bf16_f32 v77, v84, v85
	ds_read_b128 v[94:97], v239 offset:4480
	ds_read_b128 v[98:101], v239 offset:4496
	s_waitcnt lgkmcnt(1)
	v_cvt_pk_bf16_f32 v152, v94, v95
	v_cvt_pk_bf16_f32 v153, v96, v97
	s_waitcnt lgkmcnt(0)
	v_cvt_pk_bf16_f32 v154, v98, v99
	v_cvt_pk_bf16_f32 v155, v100, v101
	ds_read2_b32 v[168:169], v177 offset0:192 offset1:208
	v_mfma_f32_16x16x32_bf16 v[78:81], v[74:77], v[34:37], 0
	ds_read2_b32 v[164:165], v176 offset0:64 offset1:80
	ds_read2_b32 v[166:167], v176 offset1:16
	ds_read2_b32 v[156:157], v177 offset0:224 offset1:240
	v_mfma_f32_16x16x32_bf16 v[102:105], v[152:155], v[10:13], v[78:81]
	s_waitcnt lgkmcnt(3)
	v_add_f32_e32 v133, v133, v168
	v_mul_f32_e32 v133, 0xbfb8aa3b, v133
	v_exp_f32_e32 v133, v133
	v_add_f32_e32 v78, v132, v168
	v_mul_f32_e32 v78, 0xbfb8aa3b, v78
	v_exp_f32_e32 v130, v78
	v_mfma_f32_16x16x32_bf16 v[82:85], v[74:77], v[38:41], 0
	v_add_f32_e32 v133, 1.0, v133
	v_add_f32_e32 v134, v134, v168
	v_add_f32_e32 v130, 1.0, v130
	v_rcp_f32_e32 v130, v130
	v_mfma_f32_16x16x32_bf16 v[144:147], v[74:77], v[54:57], 0
	v_mul_f32_e32 v134, 0xbfb8aa3b, v134
	v_exp_f32_e32 v134, v134
	v_mul_f32_e32 v130, 0xc1000000, v130
	s_waitcnt lgkmcnt(2)
	v_mul_f32_e32 v130, v164, v130
	v_mul_f32_e32 v130, 0x3fb8aa3b, v130
	v_mfma_f32_16x16x32_bf16 v[98:101], v[152:155], v[14:17], v[82:85]
	v_add_f32_e32 v135, v135, v168
	v_mul_f32_e32 v135, 0xbfb8aa3b, v135
	v_exp_f32_e32 v135, v135
	v_mfma_f32_16x16x32_bf16 v[82:85], v[152:155], v[18:21], v[144:147]
	v_add_f32_e32 v126, v126, v169
	v_mul_f32_e32 v126, 0xbfb8aa3b, v126
	v_add_f32_e32 v135, 1.0, v135
	v_exp_f32_e32 v146, v130
	v_mfma_f32_16x16x32_bf16 v[86:89], v[74:77], v[42:45], 0
	s_waitcnt lgkmcnt(1)
; #define LAS __attribute__((address_space(3)))
; __device__ __forceinline__ float sigmoidf_(float x) { return __builtin_amdgcn_rcpf(1.0f + __expf(-x)); }
; template <int NT> ...
;     ...
;     for (int u = 0; u < NT; ++u) { const LAS float* XC = XCb + u * (16 * 68); const int t0 = m0 + 16 * u - b * TP;
; #pragma unroll
;         for (int n = 0; n < 4; ++n) { const int cc = 16 * n + fr;
;             const float ba = CST[5 * 64 + cc], bx = CST[6 * 64 + cc], sp = CST[7 * 64 + cc];
; #pragma unroll
;             for (int j = 0; j < 4; ++j) {
;                 const float xc = XC[(4 * fq + j) * 68 + cc];
;                 const float r = sigmoidf_(ar[u][n][j] + ba), ig = sigmoidf_(ai[u][n][j] + bx);
;                 const float a = __expf(-8.0f * r * sp);
;                 float mult = sqrtf(fmaxf(1.0f - a * a, 0.f));
;                 if (t0 + 4 * fq + j == 0) mult = 1.0f;
;                 av[u][n][j] = a; bv[u][n][j] = mult * ig * xc; } } }
	v_add_f32_e32 v130, v140, v166
	v_mul_f32_e32 v130, 0xbfb8aa3b, v130
	v_fma_f32 v131, -v146, v146, 1.0
	v_mfma_f32_16x16x32_bf16 v[136:139], v[74:77], v[50:53], 0
	v_max_f32_e32 v131, 0, v131
	s_nop 0
	s_nop 0
	v_exp_f32_e32 v130, v130
	v_mfma_f32_16x16x32_bf16 v[94:97], v[152:155], v[22:25], v[86:89]
	v_mov_b32_e32 v132, v131
	ds_read2_b32 v[144:145], v241 offset1:16
	v_add_f32_e32 v130, 1.0, v130
	v_mfma_f32_16x16x32_bf16 v[86:89], v[152:155], v[30:33], v[136:139]
	v_rcp_f32_e32 v131, v130
	v_rcp_f32_e32 v135, v135
	v_exp_f32_e32 v126, v126
	s_nop 0
	v_mfma_f32_16x16x32_bf16 v[148:151], v[74:77], v[62:65], 0
	v_add_f32_e32 v122, v122, v167
	v_add_f32_e32 v126, 1.0, v126
	s_nop 0
	s_nop 0
	s_nop 0
	v_rcp_f32_e32 v126, v126
	s_nop 0
	v_mul_f32_e32 v126, 0xc1000000, v126
	v_mul_f32_e32 v126, v165, v126
	v_rcp_f32_e32 v136, v133
	v_mul_f32_e32 v126, 0x3fb8aa3b, v126
	v_mfma_f32_16x16x32_bf16 v[78:81], v[152:155], v[6:9], v[148:151]
	v_sqrt_f32_e32 v130, v132
	s_nop 0
	v_cmp_eq_u32_e32 vcc, s19, v245
	v_mul_f32_e32 v122, 0xbfb8aa3b, v122
	v_exp_f32_e32 v148, v126
	v_cndmask_b32_e64 v133, v130, 1.0, vcc
	v_mul_f32_e32 v130, 0xc1000000, v136
	v_mul_f32_e32 v130, v164, v130
	v_mul_f32_e32 v130, 0x3fb8aa3b, v130
	v_exp_f32_e32 v138, v130
	v_add_f32_e32 v130, v141, v166
	v_mul_f32_e32 v130, 0xbfb8aa3b, v130
	v_exp_f32_e32 v130, v130
	v_fma_f32 v132, -v138, v138, 1.0
	v_max_f32_e32 v132, 0, v132
	v_add_f32_e32 v130, 1.0, v130
	v_rcp_f32_e32 v130, v130
	ds_read2_b32 v[136:137], v241 offset0:68 offset1:84
	v_fma_f32 v126, -v148, v148, 1.0
	v_max_f32_e32 v126, 0, v126
	v_exp_f32_e32 v122, v122
	v_add_f32_e32 v127, v127, v169
	v_mul_f32_e32 v127, 0xbfb8aa3b, v127
	v_add_f32_e32 v122, 1.0, v122
	v_exp_f32_e32 v127, v127
	v_sqrt_f32_e32 v132, v132
	s_nop 0
	v_pk_mul_f32 v[130:131], v[130:131], v[132:133]
	v_add_f32_e32 v132, 1.0, v134
	v_rcp_f32_e32 v134, v132
	s_waitcnt lgkmcnt(0)
	v_mov_b32_e32 v132, v136
	v_mov_b32_e32 v133, v144
	v_pk_mul_f32 v[132:133], v[132:133], v[130:131]
	v_mul_f32_e32 v130, 0xc1000000, v134
	v_mul_f32_e32 v130, v164, v130
	v_mul_f32_e32 v130, 0x3fb8aa3b, v130
	v_exp_f32_e32 v139, v130
	v_add_f32_e32 v130, v142, v166
	v_mul_f32_e32 v130, 0xbfb8aa3b, v130
	v_exp_f32_e32 v134, v130
	v_fma_f32 v130, -v139, v139, 1.0
	v_max_f32_e32 v130, 0, v130
	v_add_f32_e32 v134, 1.0, v134
	v_rcp_f32_e32 v134, v134
	v_mov_b32_e32 v136, v130
	v_rcp_f32_e32 v151, v122
	v_add_f32_e32 v127, 1.0, v127
	v_rcp_f32_e32 v127, v127
	v_add_f32_e32 v123, v123, v167
	v_mul_f32_e32 v123, 0xbfb8aa3b, v123
	v_add_f32_e32 v128, v128, v169
	v_mul_f32_e32 v128, 0xbfb8aa3b, v128
	v_exp_f32_e32 v128, v128
	v_sqrt_f32_e32 v136, v136
	s_nop 0
	v_mul_f32_e32 v136, v134, v136
	v_mul_f32_e32 v134, 0xc1000000, v135
	v_mul_f32_e32 v134, v164, v134
	v_mul_f32_e32 v134, 0x3fb8aa3b, v134
	v_exp_f32_e32 v141, v134
	v_add_f32_e32 v134, v143, v166
	v_mul_f32_e32 v134, 0xbfb8aa3b, v134
	v_exp_f32_e32 v140, v134
	v_fma_f32 v134, -v141, v141, 1.0
	v_max_f32_e32 v134, 0, v134
	v_add_f32_e32 v140, 1.0, v140
	v_rcp_f32_e32 v140, v140
	v_mov_b32_e32 v142, v134
	v_add_f32_e32 v129, v129, v169
	v_mul_f32_e32 v129, 0xbfb8aa3b, v129
	v_exp_f32_e32 v129, v129
	s_nop 0
	v_add_f32_e32 v129, 1.0, v129
	v_rcp_f32_e32 v129, v129
	v_add_f32_e32 v124, v124, v167
	v_mov_b32_e32 v144, v137
	v_mul_f32_e32 v129, 0xc1000000, v129
	v_sqrt_f32_e32 v142, v142
	s_nop 0
	v_mul_f32_e32 v142, v140, v142
	v_mul_f32_e32 v129, v165, v129
	v_mul_f32_e32 v129, 0x3fb8aa3b, v129
	v_exp_f32_e32 v129, v129
	v_add_f32_e32 v118, v118, v156
	v_mul_f32_e32 v124, 0xbfb8aa3b, v124
	v_mul_f32_e32 v118, 0xbfb8aa3b, v118
	v_exp_f32_e32 v124, v124
	v_exp_f32_e32 v118, v118
	v_mfma_f32_16x16x32_bf16 v[90:93], v[74:77], v[46:49], 0
	v_sqrt_f32_e32 v122, v126
	s_nop 0
	v_mul_f32_e32 v126, 0xc1000000, v127
	v_mul_f32_e32 v126, v165, v126
	v_mul_f32_e32 v126, 0x3fb8aa3b, v126
	v_exp_f32_e32 v126, v126
	v_exp_f32_e32 v127, v123
	v_mfma_f32_16x16x32_bf16 v[74:77], v[74:77], v[58:61], 0
	v_add_f32_e32 v124, 1.0, v124
	v_fma_f32 v123, -v126, v126, 1.0
	v_max_f32_e32 v123, 0, v123
	v_add_f32_e32 v118, 1.0, v118
	v_mfma_f32_16x16x32_bf16 v[90:93], v[152:155], v[26:29], v[90:93]
	v_mov_b32_e32 v140, v123
	v_cndmask_b32_e64 v123, v122, 1.0, vcc
	v_add_f32_e32 v122, 1.0, v127
	v_rcp_f32_e32 v150, v122
	v_mfma_f32_16x16x32_bf16 v[74:77], v[152:155], v[2:5], v[74:77]
	v_rcp_f32_e32 v124, v124
	ds_read2_b32 v[152:153], v176 offset0:96 offset1:112
	v_add_f32_e32 v127, 1.0, v128
	v_rcp_f32_e32 v127, v127
	v_rcp_f32_e32 v118, v118
	v_add_f32_e32 v125, v125, v167
	v_mul_f32_e32 v127, 0xc1000000, v127
	v_mul_f32_e32 v127, v165, v127
	v_mul_f32_e32 v127, 0x3fb8aa3b, v127
	v_exp_f32_e32 v127, v127
	v_sqrt_f32_e32 v122, v140
	s_nop 0
	v_mul_f32_e32 v125, 0xbfb8aa3b, v125
	v_exp_f32_e32 v125, v125
	v_fma_f32 v128, -v127, v127, 1.0
	v_max_f32_e32 v128, 0, v128
	v_mul_f32_e32 v118, 0xc1000000, v118
	s_waitcnt lgkmcnt(0)
	v_mul_f32_e32 v118, v152, v118
	v_mul_f32_e32 v118, 0x3fb8aa3b, v118
	ds_read2_b32 v[154:155], v176 offset0:32 offset1:48
	v_exp_f32_e32 v160, v118
	v_add_f32_e32 v125, 1.0, v125
	v_rcp_f32_e32 v125, v125
	v_fma_f32 v118, -v160, v160, 1.0
	v_pk_mul_f32 v[122:123], v[150:151], v[122:123]
	s_waitcnt lgkmcnt(0)
; #define LAS __attribute__((address_space(3)))
; __device__ __forceinline__ float sigmoidf_(float x) { return __builtin_amdgcn_rcpf(1.0f + __expf(-x)); }
; template <int NT> ...
;     ...
;     for (int u = 0; u < NT; ++u) { const LAS float* XC = XCb + u * (16 * 68); const int t0 = m0 + 16 * u - b * TP;
; #pragma unroll
;         for (int n = 0; n < 4; ++n) { const int cc = 16 * n + fr;
;             const float ba = CST[5 * 64 + cc], bx = CST[6 * 64 + cc], sp = CST[7 * 64 + cc];
; #pragma unroll
;             for (int j = 0; j < 4; ++j) {
;                 const float xc = XC[(4 * fq + j) * 68 + cc];
;                 const float r = sigmoidf_(ar[u][n][j] + ba), ig = sigmoidf_(ai[u][n][j] + bx);
;                 const float a = __expf(-8.0f * r * sp);
;                 float mult = sqrtf(fmaxf(1.0f - a * a, 0.f));
;                 if (t0 + 4 * fq + j == 0) mult = 1.0f;
;                 av[u][n][j] = a; bv[u][n][j] = mult * ig * xc; } } }
	v_add_f32_e32 v114, v114, v154
	v_sqrt_f32_e32 v128, v128
	s_nop 0
	v_fma_f32 v137, -v129, v129, 1.0
	v_max_f32_e32 v137, 0, v137
	v_mul_f32_e32 v124, v124, v128
	v_max_f32_e32 v118, 0, v118
	v_pk_mul_f32 v[122:123], v[144:145], v[122:123]
	v_mul_f32_e32 v114, 0xbfb8aa3b, v114
	v_exp_f32_e32 v114, v114
	s_nop 0
	v_add_f32_e32 v114, 1.0, v114
	v_rcp_f32_e32 v163, v114
	v_add_f32_e32 v119, v119, v156
	v_mul_f32_e32 v119, 0xbfb8aa3b, v119
	v_exp_f32_e32 v119, v119
	v_sqrt_f32_e32 v128, v137
	s_nop 0
	v_mul_f32_e32 v144, v125, v128
	v_add_f32_e32 v119, 1.0, v119
	ds_read2_b32 v[158:159], v241 offset0:32 offset1:48
	ds_read2_b32 v[170:171], v241 offset0:100 offset1:116
	v_add_f32_e32 v121, v121, v156
	v_mul_f32_e32 v121, 0xbfb8aa3b, v121
	v_exp_f32_e32 v121, v121
	s_nop 0
	v_add_f32_e32 v121, 1.0, v121
	v_rcp_f32_e32 v121, v121
	v_rcp_f32_e32 v125, v119
	v_add_f32_e32 v110, v110, v157
	v_mul_f32_e32 v110, 0xbfb8aa3b, v110
	v_sqrt_f32_e32 v114, v118
	s_nop 0
	v_cndmask_b32_e64 v119, v114, 1.0, vcc
	v_mul_f32_e32 v114, 0xc1000000, v125
	v_mul_f32_e32 v114, v152, v114
	v_mul_f32_e32 v114, 0x3fb8aa3b, v114
	v_exp_f32_e32 v151, v114
	v_add_f32_e32 v114, v115, v154
	v_mul_f32_e32 v114, 0xbfb8aa3b, v114
	v_exp_f32_e32 v114, v114
	v_fma_f32 v115, -v151, v151, 1.0
	v_max_f32_e32 v115, 0, v115
	v_add_f32_e32 v114, 1.0, v114
	v_rcp_f32_e32 v162, v114
	v_exp_f32_e32 v110, v110
	v_add_f32_e32 v106, v106, v155
	v_mul_f32_e32 v106, 0xbfb8aa3b, v106
	v_add_f32_e32 v110, 1.0, v110
	v_rcp_f32_e32 v110, v110
	v_exp_f32_e32 v106, v106
	v_add_f32_e32 v118, v120, v156
	v_mul_f32_e32 v118, 0xbfb8aa3b, v118
	v_exp_f32_e32 v120, v118
	v_mul_f32_e32 v110, 0xc1000000, v110
	v_mul_f32_e32 v110, v153, v110
	v_sqrt_f32_e32 v118, v115
	s_nop 0
	v_pk_mul_f32 v[114:115], v[162:163], v[118:119]
	v_add_f32_e32 v118, 1.0, v120
	v_rcp_f32_e32 v120, v118
	s_waitcnt lgkmcnt(0)
	v_mov_b32_e32 v118, v170
	v_mov_b32_e32 v119, v158
	v_pk_mul_f32 v[118:119], v[118:119], v[114:115]
	v_mul_f32_e32 v114, 0xc1000000, v120
	v_mul_f32_e32 v114, v152, v114
	v_mul_f32_e32 v114, 0x3fb8aa3b, v114
	v_exp_f32_e32 v147, v114
	v_add_f32_e32 v114, v116, v154
	v_mul_f32_e32 v114, 0xbfb8aa3b, v114
	v_exp_f32_e32 v116, v114
	v_fma_f32 v114, -v147, v147, 1.0
	v_max_f32_e32 v114, 0, v114
	v_add_f32_e32 v116, 1.0, v116
	v_rcp_f32_e32 v116, v116
	v_mov_b32_e32 v120, v114
	v_mul_f32_e32 v110, 0x3fb8aa3b, v110
	v_exp_f32_e32 v162, v110
	v_add_f32_e32 v111, v111, v157
	v_fma_f32 v110, -v162, v162, 1.0
	v_max_f32_e32 v110, 0, v110
	v_mul_f32_e32 v111, 0xbfb8aa3b, v111
	v_add_f32_e32 v106, 1.0, v106
	v_exp_f32_e32 v111, v111
	v_sqrt_f32_e32 v120, v120
	s_nop 0
	v_mul_f32_e32 v120, v116, v120
	v_mul_f32_e32 v116, 0xc1000000, v121
	v_mul_f32_e32 v116, v152, v116
	v_mul_f32_e32 v116, 0x3fb8aa3b, v116
	v_exp_f32_e32 v149, v116
	v_add_f32_e32 v116, v117, v154
	v_mul_f32_e32 v116, 0xbfb8aa3b, v116
	v_exp_f32_e32 v121, v116
	v_fma_f32 v116, -v149, v149, 1.0
	v_max_f32_e32 v116, 0, v116
	v_add_f32_e32 v121, 1.0, v121
	v_rcp_f32_e32 v121, v121
	v_mov_b32_e32 v125, v116
	v_rcp_f32_e32 v173, v106
	v_add_f32_e32 v111, 1.0, v111
	v_rcp_f32_e32 v111, v111
	v_add_f32_e32 v107, v107, v155
	v_mul_f32_e32 v107, 0xbfb8aa3b, v107
	v_add_f32_e32 v112, v112, v157
	v_mul_f32_e32 v112, 0xbfb8aa3b, v112
	v_exp_f32_e32 v112, v112
	v_sqrt_f32_e32 v125, v125
	s_nop 0
	v_mul_f32_e32 v150, v121, v125
	v_add_f32_e32 v113, v113, v157
	v_mul_f32_e32 v113, 0xbfb8aa3b, v113
	v_exp_f32_e32 v113, v113
	v_add_f32_e32 v108, v108, v155
	v_add_f32_e32 v113, 1.0, v113
	v_rcp_f32_e32 v113, v113
	s_nop 0
	v_mul_f32_e32 v113, 0xc1000000, v113
	v_mul_f32_e32 v113, v153, v113
	v_sqrt_f32_e32 v106, v110
	s_nop 0
	v_mul_f32_e32 v110, 0xc1000000, v111
	v_mul_f32_e32 v110, v153, v110
	v_mul_f32_e32 v110, 0x3fb8aa3b, v110
	v_exp_f32_e32 v110, v110
	v_exp_f32_e32 v111, v107
	v_mul_f32_e32 v113, 0x3fb8aa3b, v113
	v_exp_f32_e32 v113, v113
	v_fma_f32 v107, -v110, v110, 1.0
	v_max_f32_e32 v107, 0, v107
	v_add_f32_e32 v102, v102, v168
	v_mul_f32_e32 v108, 0xbfb8aa3b, v108
	v_mov_b32_e32 v121, v107
	v_cndmask_b32_e64 v107, v106, 1.0, vcc
	v_add_f32_e32 v106, 1.0, v111
	v_rcp_f32_e32 v172, v106
	v_mul_f32_e32 v102, 0xbfb8aa3b, v102
	v_exp_f32_e32 v108, v108
	v_exp_f32_e32 v102, v102
	v_add_f32_e32 v111, 1.0, v112
	v_rcp_f32_e32 v111, v111
	v_add_f32_e32 v108, 1.0, v108
	v_add_f32_e32 v102, 1.0, v102
	v_mul_f32_e32 v111, 0xc1000000, v111
	v_mul_f32_e32 v111, v153, v111
	v_mul_f32_e32 v111, 0x3fb8aa3b, v111
	v_exp_f32_e32 v111, v111
	v_sqrt_f32_e32 v106, v121
	s_nop 0
	v_rcp_f32_e32 v108, v108
	v_rcp_f32_e32 v102, v102
	v_fma_f32 v112, -v111, v111, 1.0
	v_max_f32_e32 v112, 0, v112
	v_add_f32_e32 v109, v109, v155
	v_mul_f32_e32 v109, 0xbfb8aa3b, v109
	v_exp_f32_e32 v109, v109
	v_mul_f32_e32 v102, 0xc1000000, v102
	v_mul_f32_e32 v102, v164, v102
	v_mul_f32_e32 v102, 0x3fb8aa3b, v102
	v_exp_f32_e32 v178, v102
	v_add_f32_e32 v103, v103, v168
	v_add_f32_e32 v109, 1.0, v109
	v_mul_f32_e32 v103, 0xbfb8aa3b, v103
	v_sqrt_f32_e32 v112, v112
	s_nop 0
	v_fma_f32 v121, -v113, v113, 1.0
	v_max_f32_e32 v121, 0, v121
	v_mul_f32_e32 v108, v108, v112
	v_rcp_f32_e32 v109, v109
	v_exp_f32_e32 v103, v103
	v_fma_f32 v102, -v178, v178, 1.0
	v_pk_mul_f32 v[106:107], v[172:173], v[106:107]
	v_mov_b32_e32 v158, v171
	v_max_f32_e32 v102, 0, v102
	v_pk_mul_f32 v[106:107], v[158:159], v[106:107]
	v_add_f32_e32 v103, 1.0, v103
	v_rcp_f32_e32 v103, v103
	v_sqrt_f32_e32 v112, v121
	s_nop 0
	v_mul_f32_e32 v158, v109, v112
	v_mul_f32_e32 v103, 0xc1000000, v103
	v_mul_f32_e32 v103, v164, v103
	v_mul_f32_e32 v103, 0x3fb8aa3b, v103
	v_exp_f32_e32 v179, v103
	v_add_f32_e32 v98, v98, v166
	v_fma_f32 v103, -v179, v179, 1.0
	v_max_f32_e32 v103, 0, v103
	v_add_f32_e32 v99, v99, v166
	v_mul_f32_e32 v98, 0xbfb8aa3b, v98
	v_mul_f32_e32 v99, 0xbfb8aa3b, v99
	v_sqrt_f32_e32 v102, v102
	s_nop 0
	v_exp_f32_e32 v98, v98
	v_exp_f32_e32 v99, v99
	v_add_f32_e32 v104, v104, v168
	v_add_f32_e32 v98, 1.0, v98
	v_add_f32_e32 v99, 1.0, v99
	v_mul_f32_e32 v104, 0xbfb8aa3b, v104
	v_rcp_f32_e32 v98, v98
	v_rcp_f32_e32 v99, v99
	v_exp_f32_e32 v104, v104
	v_add_u32_e32 v109, 0x1000, v241
	ds_read2_b32 v[170:171], v109 offset0:64 offset1:80
	ds_read2_b32 v[172:173], v109 offset0:132 offset1:148
	v_sqrt_f32_e32 v103, v103
	s_nop 0
	v_pk_mul_f32 v[98:99], v[98:99], v[102:103]
	v_add_f32_e32 v102, 1.0, v104
	v_rcp_f32_e32 v104, v102
	s_waitcnt lgkmcnt(1)
; #define LAS __attribute__((address_space(3)))
; __device__ __forceinline__ float sigmoidf_(float x) { return __builtin_amdgcn_rcpf(1.0f + __expf(-x)); }
; template <int NT> ...
;     ...
;     for (int u = 0; u < NT; ++u) { const LAS float* XC = XCb + u * (16 * 68); const int t0 = m0 + 16 * u - b * TP;
; #pragma unroll
;         for (int n = 0; n < 4; ++n) { const int cc = 16 * n + fr;
;             const float ba = CST[5 * 64 + cc], bx = CST[6 * 64 + cc], sp = CST[7 * 64 + cc];
; #pragma unroll
;             for (int j = 0; j < 4; ++j) {
;                 const float xc = XC[(4 * fq + j) * 68 + cc];
;                 const float r = sigmoidf_(ar[u][n][j] + ba), ig = sigmoidf_(ai[u][n][j] + bx);
;                 const float a = __expf(-8.0f * r * sp);
;                 float mult = sqrtf(fmaxf(1.0f - a * a, 0.f));
;                 if (t0 + 4 * fq + j == 0) mult = 1.0f;
;                 av[u][n][j] = a; bv[u][n][j] = mult * ig * xc; } } }
	v_mov_b32_e32 v102, v170
	s_waitcnt lgkmcnt(0)
	v_mov_b32_e32 v103, v172
	v_pk_mul_f32 v[102:103], v[98:99], v[102:103]
	v_mul_f32_e32 v98, 0xc1000000, v104
	v_mul_f32_e32 v98, v164, v98
	v_mul_f32_e32 v98, 0x3fb8aa3b, v98
	v_exp_f32_e32 v161, v98
	v_add_f32_e32 v98, v100, v166
	v_mul_f32_e32 v98, 0xbfb8aa3b, v98
	v_exp_f32_e32 v100, v98
	v_fma_f32 v98, -v161, v161, 1.0
	v_max_f32_e32 v98, 0, v98
	v_add_f32_e32 v105, v105, v168
	v_mul_f32_e32 v105, 0xbfb8aa3b, v105
	v_mov_b32_e32 v104, v98
	v_exp_f32_e32 v105, v105
	v_add_f32_e32 v100, 1.0, v100
	v_rcp_f32_e32 v100, v100
	v_add_f32_e32 v105, 1.0, v105
	v_rcp_f32_e32 v105, v105
	v_add_f32_e32 v94, v94, v169
	v_mul_f32_e32 v94, 0xbfb8aa3b, v94
	v_exp_f32_e32 v94, v94
	v_sqrt_f32_e32 v104, v104
	s_nop 0
	v_mul_f32_e32 v104, v100, v104
	v_mul_f32_e32 v100, 0xc1000000, v105
	v_mul_f32_e32 v100, v164, v100
	v_mul_f32_e32 v100, 0x3fb8aa3b, v100
	v_exp_f32_e32 v163, v100
	v_add_f32_e32 v100, v101, v166
	v_mul_f32_e32 v100, 0xbfb8aa3b, v100
	v_exp_f32_e32 v105, v100
	v_fma_f32 v100, -v163, v163, 1.0
	v_max_f32_e32 v100, 0, v100
	v_add_f32_e32 v94, 1.0, v94
	v_rcp_f32_e32 v94, v94
	v_mov_b32_e32 v121, v100
	v_add_f32_e32 v105, 1.0, v105
	v_mul_f32_e32 v94, 0xc1000000, v94
	v_mul_f32_e32 v94, v165, v94
	v_mul_f32_e32 v94, 0x3fb8aa3b, v94
	v_exp_f32_e32 v168, v94
	s_nop 0
	v_fma_f32 v94, -v168, v168, 1.0
	v_max_f32_e32 v94, 0, v94
	v_rcp_f32_e32 v105, v105
	v_add_f32_e32 v95, v95, v169
	v_sqrt_f32_e32 v121, v121
	s_nop 0
	v_mul_f32_e32 v125, 0x4f800000, v94
	v_cmp_gt_f32_e32 vcc, s47, v94
	v_mul_f32_e32 v95, 0xbfb8aa3b, v95
	v_exp_f32_e32 v95, v95
	v_cndmask_b32_e32 v125, v94, v125, vcc
	v_sqrt_f32_e32 v94, v125
	v_mul_f32_e32 v164, v105, v121
	v_add_f32_e32 v95, 1.0, v95
	v_rcp_f32_e32 v95, v95
	v_add_u32_e32 v105, -1, v94
	v_fma_f32 v121, -v105, v94, v125
	v_cmp_ge_f32_e64 s[10:11], 0, v121
	v_add_u32_e32 v121, 1, v94
	v_add_f32_e32 v96, v96, v169
	v_cndmask_b32_e64 v105, v94, v105, s[10:11]
	v_fma_f32 v94, -v121, v94, v125
	v_cmp_lt_f32_e64 s[10:11], 0, v94
	v_mul_f32_e32 v96, 0xbfb8aa3b, v96
	v_exp_f32_e32 v96, v96
	v_cndmask_b32_e64 v94, v105, v121, s[10:11]
	v_mul_f32_e32 v105, 0x37800000, v94
	v_cndmask_b32_e32 v105, v94, v105, vcc
	v_mul_f32_e32 v94, 0xc1000000, v95
	v_mul_f32_e32 v94, v165, v94
	v_mul_f32_e32 v94, 0x3fb8aa3b, v94
	v_exp_f32_e32 v94, v94
	v_cmp_class_f32_e64 s[10:11], v125, v219
	v_add_f32_e32 v96, 1.0, v96
	v_rcp_f32_e32 v96, v96
	v_fma_f32 v95, -v94, v94, 1.0
	v_max_f32_e32 v95, 0, v95
	v_cndmask_b32_e64 v174, v105, v125, s[10:11]
	v_add_f32_e32 v97, v97, v169
	v_mul_f32_e32 v97, 0xbfb8aa3b, v97
	v_exp_f32_e32 v97, v97
	v_add_f32_e32 v92, v92, v167
	v_add_f32_e32 v97, 1.0, v97
	v_rcp_f32_e32 v97, v97
	v_add_f32_e32 v86, v86, v156
	v_mul_f32_e32 v97, 0xc1000000, v97
	v_mul_f32_e32 v97, v165, v97
	v_sqrt_f32_e32 v175, v95
	s_nop 0
	v_mul_f32_e32 v95, 0xc1000000, v96
	v_mul_f32_e32 v95, v165, v95
	v_mul_f32_e32 v95, 0x3fb8aa3b, v95
	v_exp_f32_e32 v95, v95
	v_mul_f32_e32 v97, 0x3fb8aa3b, v97
	v_exp_f32_e32 v97, v97
	v_mul_f32_e32 v92, 0xbfb8aa3b, v92
	v_fma_f32 v96, -v95, v95, 1.0
	v_max_f32_e32 v96, 0, v96
	v_mul_f32_e32 v86, 0xbfb8aa3b, v86
	v_exp_f32_e32 v92, v92
	v_exp_f32_e32 v86, v86
	v_add_f32_e32 v92, 1.0, v92
	v_rcp_f32_e32 v92, v92
	v_add_f32_e32 v86, 1.0, v86
	v_rcp_f32_e32 v86, v86
	v_add_f32_e32 v93, v93, v167
	v_mul_f32_e32 v93, 0xbfb8aa3b, v93
	v_exp_f32_e32 v93, v93
	v_sqrt_f32_e32 v96, v96
	s_nop 0
	v_fma_f32 v105, -v97, v97, 1.0
	v_max_f32_e32 v105, 0, v105
	v_mul_f32_e32 v92, v92, v96
	v_mul_f32_e32 v86, 0xc1000000, v86
	v_mul_f32_e32 v86, v152, v86
	v_mul_f32_e32 v86, 0x3fb8aa3b, v86
	v_exp_f32_e32 v180, v86
	v_add_f32_e32 v87, v87, v156
	v_add_f32_e32 v93, 1.0, v93
	v_mul_f32_e32 v87, 0xbfb8aa3b, v87
	v_rcp_f32_e32 v93, v93
	v_exp_f32_e32 v87, v87
	v_fma_f32 v86, -v180, v180, 1.0
	v_max_f32_e32 v86, 0, v86
	v_sqrt_f32_e32 v96, v105
	s_nop 0
	v_mul_f32_e32 v166, v93, v96
	v_add_f32_e32 v87, 1.0, v87
	v_rcp_f32_e32 v87, v87
	v_add_f32_e32 v90, v90, v167
	v_mul_f32_e32 v87, 0xc1000000, v87
	v_mul_f32_e32 v87, v152, v87
	v_mul_f32_e32 v87, 0x3fb8aa3b, v87
	v_exp_f32_e32 v170, v87
	s_nop 0
	v_fma_f32 v87, -v170, v170, 1.0
	v_max_f32_e32 v87, 0, v87
	v_add_f32_e32 v91, v91, v167
	v_mul_f32_e32 v90, 0xbfb8aa3b, v90
	v_sqrt_f32_e32 v86, v86
	s_nop 0
	v_mul_f32_e32 v91, 0xbfb8aa3b, v91
	v_exp_f32_e32 v90, v90
	v_exp_f32_e32 v91, v91
	v_add_f32_e32 v82, v82, v154
	v_add_f32_e32 v83, v83, v154
	v_mul_f32_e32 v82, 0xbfb8aa3b, v82
	v_mul_f32_e32 v83, 0xbfb8aa3b, v83
	v_exp_f32_e32 v82, v82
	v_exp_f32_e32 v83, v83
	v_add_f32_e32 v90, 1.0, v90
	v_add_f32_e32 v91, 1.0, v91
	v_rcp_f32_e32 v90, v90
	v_rcp_f32_e32 v91, v91
	v_add_f32_e32 v88, v88, v156
	v_add_f32_e32 v82, 1.0, v82
	v_add_f32_e32 v83, 1.0, v83
	v_mul_f32_e32 v88, 0xbfb8aa3b, v88
	v_rcp_f32_e32 v82, v82
	v_rcp_f32_e32 v83, v83
	v_exp_f32_e32 v88, v88
	v_pk_mul_f32 v[90:91], v[90:91], v[174:175]
	v_mov_b32_e32 v172, v171
	v_pk_mul_f32 v[90:91], v[90:91], v[172:173]
	ds_read2_b32 v[172:173], v109 offset0:96 offset1:112
	ds_read2_b32 v[174:175], v109 offset0:164 offset1:180
	v_sqrt_f32_e32 v87, v87
	s_nop 0
	v_pk_mul_f32 v[82:83], v[82:83], v[86:87]
	v_add_f32_e32 v86, 1.0, v88
	v_rcp_f32_e32 v88, v86
	s_waitcnt lgkmcnt(1)
	v_mov_b32_e32 v86, v172
	s_waitcnt lgkmcnt(0)
; #define LAS __attribute__((address_space(3)))
; __device__ __forceinline__ float sigmoidf_(float x) { return __builtin_amdgcn_rcpf(1.0f + __expf(-x)); }
; template <int NT> ...
;     ...
;     for (int u = 0; u < NT; ++u) { const LAS float* XC = XCb + u * (16 * 68); const int t0 = m0 + 16 * u - b * TP;
; #pragma unroll
;         for (int n = 0; n < 4; ++n) { const int cc = 16 * n + fr;
;             const float ba = CST[5 * 64 + cc], bx = CST[6 * 64 + cc], sp = CST[7 * 64 + cc];
; #pragma unroll
;             for (int j = 0; j < 4; ++j) {
;                 const float xc = XC[(4 * fq + j) * 68 + cc];
;                 const float r = sigmoidf_(ar[u][n][j] + ba), ig = sigmoidf_(ai[u][n][j] + bx);
;                 const float a = __expf(-8.0f * r * sp);
;                 float mult = sqrtf(fmaxf(1.0f - a * a, 0.f));
;                 if (t0 + 4 * fq + j == 0) mult = 1.0f;
;                 av[u][n][j] = a; bv[u][n][j] = mult * ig * xc; } } }
; #pragma unroll
;     for (int u = 0; u < NT; ++u) {
; #pragma unroll
;         for (int n = 0; n < 4; ++n) { const int ch = hc0 + 16 * n + fr;
;             float hl[4], pl[4];
;             hl[0] = bv[u][n][0]; pl[0] = av[u][n][0];
; #pragma unroll
;             for (int j = 1; j < 4; ++j) { hl[j] = av[u][n][j] * hl[j - 1] + bv[u][n][j]; pl[j] = av[u][n][j] * pl[j - 1]; }
;             float He = 0.f, Pe = 1.f;
; #pragma unroll
;             for (int g = 0; g < 3; ++g) { const float Pg = __shfl(pl[3], fr + 16 * g), Hg = __shfl(hl[3], fr + 16 * g); if (g < fq) { He = Pg * He + Hg; Pe = Pg * Pe; } }
;             const float Hin = Pe * Hc[n] + He, Pin = Pe * Pc[n];
	v_mov_b32_e32 v87, v174
	v_pk_mul_f32 v[86:87], v[82:83], v[86:87]
	v_mul_f32_e32 v82, 0xc1000000, v88
	v_mul_f32_e32 v82, v152, v82
	v_mul_f32_e32 v82, 0x3fb8aa3b, v82
	v_exp_f32_e32 v169, v82
	v_add_f32_e32 v82, v84, v154
	v_mul_f32_e32 v82, 0xbfb8aa3b, v82
	v_exp_f32_e32 v84, v82
	v_fma_f32 v82, -v169, v169, 1.0
	v_max_f32_e32 v82, 0, v82
	v_add_f32_e32 v89, v89, v156
	v_mul_f32_e32 v89, 0xbfb8aa3b, v89
	v_mov_b32_e32 v88, v82
	v_exp_f32_e32 v89, v89
	v_add_f32_e32 v84, 1.0, v84
	v_rcp_f32_e32 v84, v84
	v_add_f32_e32 v89, 1.0, v89
	v_rcp_f32_e32 v89, v89
	v_add_f32_e32 v78, v78, v157
	v_mul_f32_e32 v78, 0xbfb8aa3b, v78
	v_exp_f32_e32 v78, v78
	v_sqrt_f32_e32 v88, v88
	s_nop 0
	v_mul_f32_e32 v88, v84, v88
	v_mul_f32_e32 v84, 0xc1000000, v89
	v_mul_f32_e32 v84, v152, v84
	v_mul_f32_e32 v84, 0x3fb8aa3b, v84
	v_exp_f32_e32 v171, v84
	v_add_f32_e32 v84, v85, v154
	v_mul_f32_e32 v84, 0xbfb8aa3b, v84
	v_exp_f32_e32 v89, v84
	v_fma_f32 v84, -v171, v171, 1.0
	v_max_f32_e32 v84, 0, v84
	v_add_f32_e32 v78, 1.0, v78
	v_rcp_f32_e32 v78, v78
	v_mov_b32_e32 v93, v84
	ds_read2_b32 v[98:99], v109 offset0:200 offset1:216
	v_mul_f32_e32 v78, 0xc1000000, v78
	v_mul_f32_e32 v78, v153, v78
	ds_read2_b32 v[82:83], v109 offset0:232 offset1:248
	v_mul_f32_e32 v78, 0x3fb8aa3b, v78
	v_add_f32_e32 v79, v79, v157
	v_exp_f32_e32 v152, v78
	v_mul_f32_e32 v79, 0xbfb8aa3b, v79
	v_exp_f32_e32 v79, v79
	v_add_f32_e32 v74, v74, v155
	v_mul_f32_e32 v74, 0xbfb8aa3b, v74
	v_exp_f32_e32 v78, v74
	v_fma_f32 v74, -v152, v152, 1.0
	v_max_f32_e32 v74, 0, v74
	v_add_f32_e32 v79, 1.0, v79
	v_sqrt_f32_e32 v93, v93
	s_nop 0
	v_mul_f32_e32 v96, 0x4f800000, v74
	v_cmp_gt_f32_e32 vcc, s47, v74
	v_rcp_f32_e32 v79, v79
	v_add_f32_e32 v89, 1.0, v89
	v_cndmask_b32_e32 v96, v74, v96, vcc
	v_rcp_f32_e32 v89, v89
	v_sqrt_f32_e32 v105, v96
	v_mul_f32_e32 v79, 0xc1000000, v79
	v_mul_f32_e32 v79, v153, v79
	v_mul_f32_e32 v74, v89, v93
	v_add_u32_e32 v89, -1, v105
	v_mul_f32_e32 v79, 0x3fb8aa3b, v79
	v_fma_f32 v93, -v89, v105, v96
	v_exp_f32_e32 v154, v79
	v_cmp_ge_f32_e64 s[10:11], 0, v93
	v_add_u32_e32 v93, 1, v105
	v_add_f32_e32 v75, v75, v155
	v_cndmask_b32_e64 v89, v105, v89, s[10:11]
	v_fma_f32 v105, -v93, v105, v96
	v_cmp_lt_f32_e64 s[10:11], 0, v105
	v_fma_f32 v79, -v154, v154, 1.0
	v_max_f32_e32 v79, 0, v79
	v_cndmask_b32_e64 v89, v89, v93, s[10:11]
	v_mul_f32_e32 v93, 0x37800000, v89
	v_cndmask_b32_e32 v89, v89, v93, vcc
	v_mul_f32_e32 v75, 0xbfb8aa3b, v75
	v_exp_f32_e32 v75, v75
	v_add_f32_e32 v80, v80, v157
	v_mov_b32_e32 v93, v79
	v_mul_f32_e32 v80, 0xbfb8aa3b, v80
	v_add_f32_e32 v75, 1.0, v75
	v_exp_f32_e32 v80, v80
	v_cmp_class_f32_e64 s[10:11], v96, v219
	v_rcp_f32_e32 v79, v75
	v_cndmask_b32_e64 v182, v89, v96, s[10:11]
	v_add_f32_e32 v80, 1.0, v80
	v_rcp_f32_e32 v80, v80
	v_mov_b32_e32 v174, v173
	v_add_f32_e32 v81, v81, v157
	v_mul_f32_e32 v81, 0xbfb8aa3b, v81
	v_sqrt_f32_e32 v183, v93
	s_nop 0
	v_mul_f32_e32 v75, 0xc1000000, v80
	v_mul_f32_e32 v75, v153, v75
	v_mul_f32_e32 v75, 0x3fb8aa3b, v75
	v_exp_f32_e32 v173, v75
	v_add_f32_e32 v75, v76, v155
	v_exp_f32_e32 v81, v81
	v_mul_f32_e32 v75, 0xbfb8aa3b, v75
	v_fma_f32 v76, -v173, v173, 1.0
	v_max_f32_e32 v76, 0, v76
	v_add_f32_e32 v81, 1.0, v81
	v_rcp_f32_e32 v81, v81
	v_exp_f32_e32 v75, v75
	v_add_f32_e32 v77, v77, v155
	v_mul_f32_e32 v77, 0xbfb8aa3b, v77
	v_add_f32_e32 v75, 1.0, v75
	v_rcp_f32_e32 v75, v75
	v_exp_f32_e32 v77, v77
	ds_read2_b32 v[130:131], v241 offset0:136 offset1:152
	ds_read2_b32 v[134:135], v241 offset0:204 offset1:220
	v_sqrt_f32_e32 v76, v76
	s_nop 0
	v_mul_f32_e32 v80, 0xc1000000, v81
	v_mul_f32_e32 v80, v153, v80
	v_mul_f32_e32 v80, 0x3fb8aa3b, v80
	v_exp_f32_e32 v81, v80
	v_mul_f32_e32 v76, v75, v76
	v_add_f32_e32 v75, 1.0, v77
	v_fma_f32 v137, v138, v133, v132
	v_fma_f32 v80, -v81, v81, 1.0
	v_max_f32_e32 v80, 0, v80
	s_waitcnt lgkmcnt(0)
	v_mov_b32_e32 v140, v134
	v_rcp_f32_e32 v75, v75
	v_add_u32_e32 v112, 0x1400, v241
	ds_read2_b32 v[100:101], v112 offset0:12 offset1:28
	ds_read2_b32 v[84:85], v112 offset0:44 offset1:60
	ds_read2_b32 v[114:115], v241 offset0:168 offset1:184
	ds_read2_b32 v[116:117], v241 offset0:236 offset1:252
	v_add_f32_e32 v78, 1.0, v78
	v_mul_f32_e32 v93, v138, v146
	v_mov_b32_e32 v138, v130
	v_sqrt_f32_e32 v77, v80
	s_nop 0
	v_mul_f32_e32 v80, v139, v137
	v_pk_fma_f32 v[156:157], v[138:139], v[136:137], v[80:81] op_sel_hi:[1,1,0]
	v_and_or_b32 v89, v207, 64, v223
	v_mov_b32_e32 v143, v156
	v_mul_f32_e32 v80, v139, v93
	v_pk_mul_f32 v[138:139], v[140:141], v[142:143]
	v_mul_f32_e32 v105, v141, v80
	v_add_f32_e32 v96, v138, v139
	v_lshlrev_b32_e32 v134, 2, v89
	ds_bpermute_b32 v89, v134, v105
	ds_bpermute_b32 v109, v134, v96
	v_mul_f32_e32 v130, v75, v77
	ds_bpermute_b32 v75, v134, v105 offset:64
	ds_bpermute_b32 v77, v134, v96 offset:64
	ds_bpermute_b32 v112, v134, v105 offset:128
	ds_bpermute_b32 v121, v134, v96 offset:128
	s_waitcnt lgkmcnt(4)
	v_fmac_f32_e32 v109, 0, v89
	v_cndmask_b32_e64 v109, v109, 0, s[8:9]
	v_cndmask_b32_e64 v89, v89, 1.0, s[8:9]
	s_waitcnt lgkmcnt(2)
	v_fmac_f32_e32 v77, v109, v75
	v_mul_f32_e32 v75, v89, v75
	v_cndmask_b32_e64 v77, v109, v77, s[4:5]
	v_cndmask_b32_e64 v75, v89, v75, s[4:5]
	v_add_u32_e32 v138, s19, v242
	s_waitcnt lgkmcnt(0)
; __device__ __forceinline__ unsigned cvt_pk_bf16(float lo, float hi) { unsigned r; asm volatile("v_cvt_pk_bf16_f32 %0, %1, %2" : "=v"(r) : "v"(lo), "v"(hi)); return r; }
; template <int NT> ...
;     ...
;     for (int u = 0; u < NT; ++u) {
; #pragma unroll
;         for (int n = 0; n < 4; ++n) { const int ch = hc0 + 16 * n + fr;
;             float hl[4], pl[4];
;             hl[0] = bv[u][n][0]; pl[0] = av[u][n][0];
; #pragma unroll
;             for (int j = 1; j < 4; ++j) { hl[j] = av[u][n][j] * hl[j - 1] + bv[u][n][j]; pl[j] = av[u][n][j] * pl[j - 1]; }
;             float He = 0.f, Pe = 1.f;
; #pragma unroll
;             for (int g = 0; g < 3; ++g) { const float Pg = __shfl(pl[3], fr + 16 * g), Hg = __shfl(hl[3], fr + 16 * g); if (g < fq) { He = Pg * He + Hg; Pe = Pg * Pe; } }
;             const float Hin = Pe * Hc[n] + He, Pin = Pe * Pc[n];
;             float hf[4], pf[4];
; #pragma unroll
;             for (int j = 0; j < 4; ++j) { hf[j] = hl[j] + pl[j] * Hin; pf[j] = pl[j] * Pin; }
; #pragma unroll
;             for (int j = 0; j < 4; ++j) { const size_t o = (size_t)(m0 + 16 * u + 4 * fq + j) * D + ch; HLOC[o] = (bf16_t)(cvt_pk_bf16(hf[j], 0.f) & 0xffffu); PCUM[o] = (bf16_t)(cvt_pk_bf16(pf[j], 0.f) & 0xffffu); }
;             Hc[n] = __shfl(hf[3], fr + 48); Pc[n] = __shfl(pf[3], fr + 48);
	v_fmac_f32_e32 v121, v77, v112
	v_mul_f32_e32 v89, v75, v112
	v_ashrrev_i32_e32 v139, 31, v138
	v_cndmask_b32_e64 v77, v77, v121, s[6:7]
	v_cndmask_b32_e64 v75, v75, v89, s[6:7]
	v_lshlrev_b64 v[140:141], 10, v[138:139]
	v_fmac_f32_e32 v77, v70, v75
	v_mul_f32_e32 v70, v72, v75
	v_fmac_f32_e32 v133, v146, v77
	v_or_b32_e32 v142, v140, v208
	v_mov_b32_e32 v143, v141
	v_mul_f32_e32 v72, v146, v70
	v_fmac_f32_e32 v137, v93, v77
	v_mul_f32_e32 v75, v93, v70
	v_fmac_f32_e32 v156, v80, v77
	v_mul_f32_e32 v80, v80, v70
	v_fmac_f32_e32 v96, v105, v77
	v_mul_f32_e32 v77, v105, v70
	v_cvt_pk_bf16_f32 v70, v133, v1
	v_lshlrev_b64 v[132:133], 1, v[142:143]
	v_lshl_add_u64 v[132:133], v[132:133], 1, s[62:63]
	v_mov_b32_e32 v247, v70
	v_cvt_pk_bf16_f32 v246, v1, v72
	v_or_b32_e32 v70, v247, v246
	global_store_dword v[132:133], v70, off
	v_add_u32_e32 v132, 1, v138
	v_ashrrev_i32_e32 v133, 31, v132
	v_lshlrev_b64 v[132:133], 10, v[132:133]
	v_or_b32_e32 v142, v132, v208
	v_mov_b32_e32 v143, v133
	v_cvt_pk_bf16_f32 v70, v137, v1
	v_lshlrev_b64 v[136:137], 1, v[142:143]
	v_lshl_add_u64 v[136:137], v[136:137], 1, s[62:63]
	v_mov_b32_e32 v247, v70
	v_cvt_pk_bf16_f32 v246, v1, v75
	v_or_b32_e32 v70, v247, v246
	global_store_dword v[136:137], v70, off
	v_add_u32_e32 v136, 2, v138
	v_ashrrev_i32_e32 v137, 31, v136
	v_lshlrev_b64 v[136:137], 10, v[136:137]
	v_or_b32_e32 v142, v136, v208
	v_mov_b32_e32 v143, v137
	v_lshlrev_b64 v[142:143], 1, v[142:143]
	v_cvt_pk_bf16_f32 v70, v156, v1
	v_lshl_add_u64 v[142:143], v[142:143], 1, s[62:63]
	v_rcp_f32_e32 v78, v78
	v_mov_b32_e32 v247, v70
	v_cvt_pk_bf16_f32 v246, v1, v80
	v_or_b32_e32 v70, v247, v246
	global_store_dword v[142:143], v70, off
	v_add_u32_e32 v142, 3, v138
	v_ashrrev_i32_e32 v143, 31, v142
	v_lshlrev_b64 v[142:143], 10, v[142:143]
	v_or_b32_e32 v156, v142, v208
	v_mov_b32_e32 v157, v143
	v_pk_mul_f32 v[78:79], v[78:79], v[182:183]
	v_lshlrev_b64 v[156:157], 1, v[156:157]
	v_pk_mul_f32 v[78:79], v[78:79], v[174:175]
	v_cvt_pk_bf16_f32 v70, v96, v1
	v_fma_f32 v125, v126, v123, v122
	v_mov_b32_e32 v247, v70
	v_mul_f32_e32 v75, v126, v148
	v_mov_b32_e32 v126, v131
	v_mul_f32_e32 v70, v127, v125
	v_pk_fma_f32 v[174:175], v[126:127], v[124:125], v[70:71] op_sel_hi:[1,1,0]
	v_mov_b32_e32 v128, v135
	v_mov_b32_e32 v145, v174
	v_mul_f32_e32 v70, v127, v75
	v_pk_mul_f32 v[126:127], v[128:129], v[144:145]
	v_mul_f32_e32 v89, v129, v70
	v_add_f32_e32 v80, v126, v127
	ds_bpermute_b32 v93, v134, v89
	ds_bpermute_b32 v105, v134, v80
	v_cvt_pk_bf16_f32 v246, v1, v77
	v_or_b32_e32 v72, v247, v246
	v_lshl_add_u64 v[126:127], v[156:157], 1, s[62:63]
	global_store_dword v[126:127], v72, off
	ds_bpermute_b32 v72, v134, v89 offset:64
	ds_bpermute_b32 v109, v134, v80 offset:64
	ds_bpermute_b32 v112, v134, v89 offset:128
	ds_bpermute_b32 v121, v134, v80 offset:128
	s_waitcnt lgkmcnt(4)
	v_fmac_f32_e32 v105, 0, v93
	v_cndmask_b32_e64 v105, v105, 0, s[8:9]
	v_cndmask_b32_e64 v93, v93, 1.0, s[8:9]
	s_waitcnt lgkmcnt(2)
	v_fmac_f32_e32 v109, v105, v72
	v_mul_f32_e32 v72, v93, v72
	v_cndmask_b32_e64 v105, v105, v109, s[4:5]
	v_cndmask_b32_e64 v72, v93, v72, s[4:5]
	s_waitcnt lgkmcnt(0)
	v_fmac_f32_e32 v121, v105, v112
	v_mul_f32_e32 v93, v72, v112
	v_cndmask_b32_e64 v105, v105, v121, s[6:7]
	v_cndmask_b32_e64 v72, v72, v93, s[6:7]
	v_fmac_f32_e32 v105, v71, v72
	v_mul_f32_e32 v71, v73, v72
	v_mul_f32_e32 v93, v148, v71
	v_fmac_f32_e32 v125, v75, v105
	v_mul_f32_e32 v75, v75, v71
	v_fmac_f32_e32 v174, v70, v105
	v_mul_f32_e32 v109, v70, v71
	v_fmac_f32_e32 v80, v89, v105
	v_mul_f32_e32 v89, v89, v71
	v_or_b32_e32 v70, v140, v214
	v_mov_b32_e32 v71, v141
	v_lshlrev_b64 v[70:71], 1, v[70:71]
	v_lshl_add_u64 v[70:71], v[70:71], 1, s[62:63]
	v_fmac_f32_e32 v123, v148, v105
	v_cvt_pk_bf16_f32 v105, v123, v1
	v_mov_b32_e32 v247, v105
	v_cvt_pk_bf16_f32 v246, v1, v93
	v_or_b32_e32 v72, v247, v246
	global_store_dword v[70:71], v72, off
	v_or_b32_e32 v70, v132, v214
	v_mov_b32_e32 v71, v133
	v_lshlrev_b64 v[70:71], 1, v[70:71]
	v_lshl_add_u64 v[70:71], v[70:71], 1, s[62:63]
	v_cvt_pk_bf16_f32 v93, v125, v1
	v_mov_b32_e32 v247, v93
	v_cvt_pk_bf16_f32 v246, v1, v75
	v_or_b32_e32 v72, v247, v246
	global_store_dword v[70:71], v72, off
	v_or_b32_e32 v70, v136, v214
	v_mov_b32_e32 v71, v137
	v_lshlrev_b64 v[70:71], 1, v[70:71]
	v_lshl_add_u64 v[70:71], v[70:71], 1, s[62:63]
	v_cvt_pk_bf16_f32 v75, v174, v1
	v_mov_b32_e32 v247, v75
	v_cvt_pk_bf16_f32 v246, v1, v109
	v_or_b32_e32 v72, v247, v246
	global_store_dword v[70:71], v72, off
	v_or_b32_e32 v70, v142, v214
	v_mov_b32_e32 v71, v143
	v_lshlrev_b64 v[70:71], 1, v[70:71]
	v_fma_f32 v121, v151, v119, v118
	v_cvt_pk_bf16_f32 v75, v80, v1
	v_mov_b32_e32 v247, v75
	v_mov_b32_e32 v146, v114
	v_mul_f32_e32 v72, v147, v121
	v_pk_fma_f32 v[72:73], v[146:147], v[120:121], v[72:73] op_sel_hi:[1,1,0]
	v_mul_f32_e32 v93, v151, v160
	v_mov_b32_e32 v148, v116
	v_mov_b32_e32 v151, v72
	v_mul_f32_e32 v73, v147, v93
	v_pk_mul_f32 v[122:123], v[148:149], v[150:151]
	v_mul_f32_e32 v109, v149, v73
	v_add_f32_e32 v105, v122, v123
	ds_bpermute_b32 v112, v134, v109
	ds_bpermute_b32 v114, v134, v105
	v_lshl_add_u64 v[70:71], v[70:71], 1, s[62:63]
	v_cvt_pk_bf16_f32 v246, v1, v89
	v_or_b32_e32 v75, v247, v246
	global_store_dword v[70:71], v75, off
	ds_bpermute_b32 v70, v134, v109 offset:64
	ds_bpermute_b32 v71, v134, v105 offset:64
	s_waitcnt lgkmcnt(2)
	v_fmac_f32_e32 v114, 0, v112
	ds_bpermute_b32 v75, v134, v80 offset:192
	ds_bpermute_b32 v80, v134, v89 offset:192
	v_cndmask_b32_e64 v89, v114, 0, s[8:9]
	ds_bpermute_b32 v114, v134, v109 offset:128
	ds_bpermute_b32 v116, v134, v105 offset:128
	v_cndmask_b32_e64 v112, v112, 1.0, s[8:9]
	s_waitcnt lgkmcnt(4)
; __device__ __forceinline__ unsigned cvt_pk_bf16(float lo, float hi) { unsigned r; asm volatile("v_cvt_pk_bf16_f32 %0, %1, %2" : "=v"(r) : "v"(lo), "v"(hi)); return r; }
; template <int NT> ...
;     ...
;     for (int u = 0; u < NT; ++u) {
; #pragma unroll
;         for (int n = 0; n < 4; ++n) { const int ch = hc0 + 16 * n + fr;
;             float hl[4], pl[4];
;             hl[0] = bv[u][n][0]; pl[0] = av[u][n][0];
; #pragma unroll
;             for (int j = 1; j < 4; ++j) { hl[j] = av[u][n][j] * hl[j - 1] + bv[u][n][j]; pl[j] = av[u][n][j] * pl[j - 1]; }
;             float He = 0.f, Pe = 1.f;
; #pragma unroll
;             for (int g = 0; g < 3; ++g) { const float Pg = __shfl(pl[3], fr + 16 * g), Hg = __shfl(hl[3], fr + 16 * g); if (g < fq) { He = Pg * He + Hg; Pe = Pg * Pe; } }
;             const float Hin = Pe * Hc[n] + He, Pin = Pe * Pc[n];
;             float hf[4], pf[4];
; #pragma unroll
;             for (int j = 0; j < 4; ++j) { hf[j] = hl[j] + pl[j] * Hin; pf[j] = pl[j] * Pin; }
; #pragma unroll
;             for (int j = 0; j < 4; ++j) { const size_t o = (size_t)(m0 + 16 * u + 4 * fq + j) * D + ch; HLOC[o] = (bf16_t)(cvt_pk_bf16(hf[j], 0.f) & 0xffffu); PCUM[o] = (bf16_t)(cvt_pk_bf16(pf[j], 0.f) & 0xffffu); }
;             Hc[n] = __shfl(hf[3], fr + 48); Pc[n] = __shfl(pf[3], fr + 48);
	v_fmac_f32_e32 v71, v89, v70
	v_mul_f32_e32 v70, v112, v70
	v_cndmask_b32_e64 v71, v89, v71, s[4:5]
	v_cndmask_b32_e64 v70, v112, v70, s[4:5]
	s_waitcnt lgkmcnt(0)
	v_fmac_f32_e32 v116, v71, v114
	v_mul_f32_e32 v89, v70, v114
	v_cndmask_b32_e64 v71, v71, v116, s[6:7]
	v_cndmask_b32_e64 v70, v70, v89, s[6:7]
	v_fmac_f32_e32 v71, v66, v70
	v_mul_f32_e32 v66, v68, v70
	v_fmac_f32_e32 v119, v160, v71
	v_fmac_f32_e32 v121, v93, v71
	v_fmac_f32_e32 v72, v73, v71
	v_fmac_f32_e32 v105, v109, v71
	v_or_b32_e32 v70, v140, v212
	v_mov_b32_e32 v71, v141
	v_lshlrev_b64 v[70:71], 1, v[70:71]
	v_mul_f32_e32 v68, v160, v66
	v_mul_f32_e32 v89, v93, v66
	v_mul_f32_e32 v93, v73, v66
	v_mul_f32_e32 v114, v109, v66
	v_cvt_pk_bf16_f32 v66, v119, v1
	v_lshl_add_u64 v[70:71], v[70:71], 1, s[62:63]
	v_mov_b32_e32 v247, v66
	v_cvt_pk_bf16_f32 v246, v1, v68
	v_or_b32_e32 v66, v247, v246
	global_store_dword v[70:71], v66, off
	v_or_b32_e32 v70, v132, v212
	v_mov_b32_e32 v71, v133
	v_lshlrev_b64 v[70:71], 1, v[70:71]
	v_cvt_pk_bf16_f32 v66, v121, v1
	v_lshl_add_u64 v[70:71], v[70:71], 1, s[62:63]
	v_mov_b32_e32 v247, v66
	v_cvt_pk_bf16_f32 v246, v1, v89
	v_or_b32_e32 v66, v247, v246
	global_store_dword v[70:71], v66, off
	v_or_b32_e32 v70, v136, v212
	v_mov_b32_e32 v71, v137
	v_lshlrev_b64 v[70:71], 1, v[70:71]
	v_cvt_pk_bf16_f32 v66, v72, v1
	v_lshl_add_u64 v[70:71], v[70:71], 1, s[62:63]
	v_mov_b32_e32 v247, v66
	v_cvt_pk_bf16_f32 v246, v1, v93
	v_or_b32_e32 v66, v247, v246
	global_store_dword v[70:71], v66, off
	v_or_b32_e32 v70, v142, v212
	v_mov_b32_e32 v71, v143
	v_lshlrev_b64 v[70:71], 1, v[70:71]
	v_cvt_pk_bf16_f32 v66, v105, v1
	v_fma_f32 v109, v110, v107, v106
	v_mov_b32_e32 v247, v66
	v_mul_f32_e32 v89, v110, v162
	v_mov_b32_e32 v110, v115
	v_mul_f32_e32 v66, v111, v109
	v_pk_fma_f32 v[72:73], v[110:111], v[108:109], v[66:67] op_sel_hi:[1,1,0]
	v_mov_b32_e32 v112, v117
	v_mov_b32_e32 v159, v72
	v_mul_f32_e32 v66, v111, v89
	v_pk_mul_f32 v[110:111], v[112:113], v[158:159]
	v_mul_f32_e32 v93, v113, v66
	v_add_f32_e32 v73, v110, v111
	ds_bpermute_b32 v106, v134, v93
	ds_bpermute_b32 v108, v134, v73
	v_cvt_pk_bf16_f32 v246, v1, v114
	v_or_b32_e32 v68, v247, v246
	v_lshl_add_u64 v[70:71], v[70:71], 1, s[62:63]
	global_store_dword v[70:71], v68, off
	ds_bpermute_b32 v68, v134, v93 offset:64
	ds_bpermute_b32 v70, v134, v73 offset:64
	s_waitcnt lgkmcnt(2)
	v_fmac_f32_e32 v108, 0, v106
	ds_bpermute_b32 v110, v134, v105 offset:192
	v_cndmask_b32_e64 v71, v108, 0, s[8:9]
	v_cndmask_b32_e64 v105, v106, 1.0, s[8:9]
	ds_bpermute_b32 v106, v134, v93 offset:128
	ds_bpermute_b32 v108, v134, v73 offset:128
	s_waitcnt lgkmcnt(3)
	v_fmac_f32_e32 v70, v71, v68
	v_mul_f32_e32 v68, v105, v68
	v_cndmask_b32_e64 v70, v71, v70, s[4:5]
	v_cndmask_b32_e64 v68, v105, v68, s[4:5]
	s_waitcnt lgkmcnt(0)
	v_fmac_f32_e32 v108, v70, v106
	v_mul_f32_e32 v71, v68, v106
	v_cndmask_b32_e64 v70, v70, v108, s[6:7]
	v_cndmask_b32_e64 v68, v68, v71, s[6:7]
	v_fmac_f32_e32 v70, v67, v68
	v_mul_f32_e32 v67, v69, v68
	v_or_b32_e32 v140, v140, v210
	v_fmac_f32_e32 v107, v162, v70
	v_mul_f32_e32 v71, v162, v67
	v_fmac_f32_e32 v109, v89, v70
	v_mul_f32_e32 v89, v89, v67
	v_fmac_f32_e32 v72, v66, v70
	v_mul_f32_e32 v105, v66, v67
	v_fmac_f32_e32 v73, v93, v70
	v_mul_f32_e32 v70, v93, v67
	v_lshlrev_b64 v[66:67], 1, v[140:141]
	v_lshl_add_u64 v[66:67], v[66:67], 1, s[62:63]
	v_or_b32_e32 v132, v132, v210
	v_cvt_pk_bf16_f32 v93, v107, v1
	v_mov_b32_e32 v247, v93
	v_cvt_pk_bf16_f32 v246, v1, v71
	v_or_b32_e32 v68, v247, v246
	global_store_dword v[66:67], v68, off
	v_lshlrev_b64 v[66:67], 1, v[132:133]
	v_lshl_add_u64 v[66:67], v[66:67], 1, s[62:63]
	v_or_b32_e32 v136, v136, v210
	v_cvt_pk_bf16_f32 v71, v109, v1
	v_mov_b32_e32 v247, v71
	v_cvt_pk_bf16_f32 v246, v1, v89
	v_or_b32_e32 v68, v247, v246
	global_store_dword v[66:67], v68, off
	v_lshlrev_b64 v[66:67], 1, v[136:137]
	v_lshl_add_u64 v[66:67], v[66:67], 1, s[62:63]
	v_or_b32_e32 v142, v142, v210
	v_cvt_pk_bf16_f32 v71, v72, v1
	v_mov_b32_e32 v247, v71
	v_cvt_pk_bf16_f32 v246, v1, v105
	v_or_b32_e32 v68, v247, v246
	global_store_dword v[66:67], v68, off
	v_lshlrev_b64 v[66:67], 1, v[142:143]
	v_lshl_add_u64 v[66:67], v[66:67], 1, s[62:63]
	v_fma_f32 v105, v179, v102, v103
	v_cvt_pk_bf16_f32 v71, v73, v1
	v_mov_b32_e32 v247, v71
	v_cvt_pk_bf16_f32 v246, v1, v70
	v_or_b32_e32 v68, v247, v246
	global_store_dword v[66:67], v68, off
	v_mov_b32_e32 v160, v98
	v_mul_f32_e32 v66, v105, v161
	v_pk_fma_f32 v[66:67], v[104:105], v[160:161], v[66:67] op_sel_hi:[1,1,0]
	v_mul_f32_e32 v71, v179, v178
	v_mov_b32_e32 v165, v66
	v_mov_b32_e32 v162, v100
	v_mul_f32_e32 v67, v161, v71
	v_pk_mul_f32 v[68:69], v[164:165], v[162:163]
	ds_bpermute_b32 v112, v134, v73 offset:192
	v_add_f32_e32 v72, v68, v69
	v_mul_f32_e32 v73, v163, v67
	ds_bpermute_b32 v89, v134, v73
	ds_bpermute_b32 v93, v134, v72
	v_add_u32_e32 v68, 16, v138
	v_ashrrev_i32_e32 v69, 31, v68
	v_lshlrev_b64 v[106:107], 10, v[68:69]
	ds_bpermute_b32 v68, v134, v73 offset:64
	ds_bpermute_b32 v69, v134, v72 offset:64
	s_waitcnt lgkmcnt(2)
	v_fmac_f32_e32 v93, 0, v89
	ds_bpermute_b32 v98, v134, v70 offset:192
	v_cndmask_b32_e64 v70, v93, 0, s[8:9]
	ds_bpermute_b32 v93, v134, v73 offset:128
	ds_bpermute_b32 v100, v134, v72 offset:128
	ds_bpermute_b32 v96, v134, v96 offset:192
	ds_bpermute_b32 v77, v134, v77 offset:192
	v_cndmask_b32_e64 v89, v89, 1.0, s[8:9]
	s_waitcnt lgkmcnt(5)
	v_fmac_f32_e32 v69, v70, v68
	v_mul_f32_e32 v68, v89, v68
	v_cndmask_b32_e64 v69, v70, v69, s[4:5]
	v_cndmask_b32_e64 v68, v89, v68, s[4:5]
	s_waitcnt lgkmcnt(2)
; __device__ __forceinline__ unsigned cvt_pk_bf16(float lo, float hi) { unsigned r; asm volatile("v_cvt_pk_bf16_f32 %0, %1, %2" : "=v"(r) : "v"(lo), "v"(hi)); return r; }
; template <int NT> ...
;     ...
;     for (int u = 0; u < NT; ++u) {
; #pragma unroll
;         for (int n = 0; n < 4; ++n) { const int ch = hc0 + 16 * n + fr;
;             float hl[4], pl[4];
;             hl[0] = bv[u][n][0]; pl[0] = av[u][n][0];
; #pragma unroll
;             for (int j = 1; j < 4; ++j) { hl[j] = av[u][n][j] * hl[j - 1] + bv[u][n][j]; pl[j] = av[u][n][j] * pl[j - 1]; }
;             float He = 0.f, Pe = 1.f;
; #pragma unroll
;             for (int g = 0; g < 3; ++g) { const float Pg = __shfl(pl[3], fr + 16 * g), Hg = __shfl(hl[3], fr + 16 * g); if (g < fq) { He = Pg * He + Hg; Pe = Pg * Pe; } }
;             const float Hin = Pe * Hc[n] + He, Pin = Pe * Pc[n];
;             float hf[4], pf[4];
; #pragma unroll
;             for (int j = 0; j < 4; ++j) { hf[j] = hl[j] + pl[j] * Hin; pf[j] = pl[j] * Pin; }
; #pragma unroll
;             for (int j = 0; j < 4; ++j) { const size_t o = (size_t)(m0 + 16 * u + 4 * fq + j) * D + ch; HLOC[o] = (bf16_t)(cvt_pk_bf16(hf[j], 0.f) & 0xffffu); PCUM[o] = (bf16_t)(cvt_pk_bf16(pf[j], 0.f) & 0xffffu); }
;             Hc[n] = __shfl(hf[3], fr + 48); Pc[n] = __shfl(pf[3], fr + 48);
	v_fmac_f32_e32 v100, v69, v93
	v_mul_f32_e32 v70, v68, v93
	v_cndmask_b32_e64 v69, v69, v100, s[6:7]
	v_cndmask_b32_e64 v68, v68, v70, s[6:7]
	s_waitcnt lgkmcnt(1)
	v_fmac_f32_e32 v69, v68, v96
	s_waitcnt lgkmcnt(0)
	v_mul_f32_e32 v68, v68, v77
	v_fmac_f32_e32 v102, v178, v69
	v_mul_f32_e32 v77, v178, v68
	v_fmac_f32_e32 v105, v71, v69
	v_mul_f32_e32 v89, v71, v68
	v_fmac_f32_e32 v66, v67, v69
	v_mul_f32_e32 v93, v67, v68
	v_fmac_f32_e32 v72, v73, v69
	v_mul_f32_e32 v73, v73, v68
	v_or_b32_e32 v68, v106, v208
	v_mov_b32_e32 v69, v107
	v_lshlrev_b64 v[68:69], 1, v[68:69]
	v_cvt_pk_bf16_f32 v67, v102, v1
	v_lshl_add_u64 v[68:69], v[68:69], 1, s[62:63]
	v_mov_b32_e32 v247, v67
	v_cvt_pk_bf16_f32 v246, v1, v77
	v_or_b32_e32 v67, v247, v246
	global_store_dword v[68:69], v67, off
	v_add_u32_e32 v68, 17, v138
	v_ashrrev_i32_e32 v69, 31, v68
	v_lshlrev_b64 v[102:103], 10, v[68:69]
	v_or_b32_e32 v68, v102, v208
	v_mov_b32_e32 v69, v103
	v_lshlrev_b64 v[68:69], 1, v[68:69]
	v_cvt_pk_bf16_f32 v67, v105, v1
	v_lshl_add_u64 v[68:69], v[68:69], 1, s[62:63]
	v_mov_b32_e32 v247, v67
	v_cvt_pk_bf16_f32 v246, v1, v89
	v_or_b32_e32 v67, v247, v246
	global_store_dword v[68:69], v67, off
	v_add_u32_e32 v68, 18, v138
	v_ashrrev_i32_e32 v69, 31, v68
	v_lshlrev_b64 v[104:105], 10, v[68:69]
	v_or_b32_e32 v68, v104, v208
	v_mov_b32_e32 v69, v105
	v_cvt_pk_bf16_f32 v70, v66, v1
	v_lshlrev_b64 v[66:67], 1, v[68:69]
	v_lshl_add_u64 v[66:67], v[66:67], 1, s[62:63]
	v_mov_b32_e32 v247, v70
	v_cvt_pk_bf16_f32 v246, v1, v93
	v_or_b32_e32 v68, v247, v246
	global_store_dword v[66:67], v68, off
	v_add_u32_e32 v66, 19, v138
	v_ashrrev_i32_e32 v67, 31, v66
	v_lshlrev_b64 v[108:109], 10, v[66:67]
	v_or_b32_e32 v66, v108, v208
	v_mov_b32_e32 v67, v109
	v_lshlrev_b64 v[66:67], 1, v[66:67]
	v_fma_f32 v93, v94, v90, v91
	v_cvt_pk_bf16_f32 v70, v72, v1
	v_mov_b32_e32 v247, v70
	v_mul_f32_e32 v89, v94, v168
	v_mov_b32_e32 v94, v99
	v_mul_f32_e32 v68, v93, v95
	v_pk_fma_f32 v[68:69], v[92:93], v[94:95], v[68:69] op_sel_hi:[1,1,0]
	v_mov_b32_e32 v96, v101
	v_mov_b32_e32 v167, v68
	v_mul_f32_e32 v69, v95, v89
	v_pk_mul_f32 v[70:71], v[166:167], v[96:97]
	v_mul_f32_e32 v91, v97, v69
	v_add_f32_e32 v71, v70, v71
	ds_bpermute_b32 v92, v134, v91
	ds_bpermute_b32 v94, v134, v71
	v_lshl_add_u64 v[66:67], v[66:67], 1, s[62:63]
	v_cvt_pk_bf16_f32 v246, v1, v73
	v_or_b32_e32 v77, v247, v246
	global_store_dword v[66:67], v77, off
	ds_bpermute_b32 v66, v134, v91 offset:64
	ds_bpermute_b32 v67, v134, v71 offset:64
	s_waitcnt lgkmcnt(2)
	v_fmac_f32_e32 v94, 0, v92
	ds_bpermute_b32 v70, v134, v72 offset:192
	ds_bpermute_b32 v72, v134, v73 offset:192
	v_cndmask_b32_e64 v73, v94, 0, s[8:9]
	v_cndmask_b32_e64 v77, v92, 1.0, s[8:9]
	ds_bpermute_b32 v92, v134, v91 offset:128
	ds_bpermute_b32 v94, v134, v71 offset:128
	s_waitcnt lgkmcnt(4)
	v_fmac_f32_e32 v67, v73, v66
	v_mul_f32_e32 v66, v77, v66
	v_cndmask_b32_e64 v67, v73, v67, s[4:5]
	v_cndmask_b32_e64 v66, v77, v66, s[4:5]
	s_waitcnt lgkmcnt(0)
	v_fmac_f32_e32 v94, v67, v92
	v_mul_f32_e32 v73, v66, v92
	v_cndmask_b32_e64 v67, v67, v94, s[6:7]
	v_cndmask_b32_e64 v66, v66, v73, s[6:7]
	v_fmac_f32_e32 v67, v66, v75
	v_mul_f32_e32 v66, v66, v80
	v_fmac_f32_e32 v90, v168, v67
	v_mul_f32_e32 v73, v168, v66
	v_fmac_f32_e32 v93, v89, v67
	v_mul_f32_e32 v75, v89, v66
	v_fmac_f32_e32 v68, v69, v67
	v_mul_f32_e32 v77, v69, v66
	v_fmac_f32_e32 v71, v91, v67
	v_mul_f32_e32 v80, v91, v66
	v_or_b32_e32 v66, v106, v214
	v_mov_b32_e32 v67, v107
	v_lshlrev_b64 v[66:67], 1, v[66:67]
	v_cvt_pk_bf16_f32 v69, v90, v1
	v_lshl_add_u64 v[66:67], v[66:67], 1, s[62:63]
	v_mov_b32_e32 v247, v69
	v_cvt_pk_bf16_f32 v246, v1, v73
	v_or_b32_e32 v69, v247, v246
	global_store_dword v[66:67], v69, off
	v_or_b32_e32 v66, v102, v214
	v_mov_b32_e32 v67, v103
	v_lshlrev_b64 v[66:67], 1, v[66:67]
	v_cvt_pk_bf16_f32 v69, v93, v1
	v_lshl_add_u64 v[66:67], v[66:67], 1, s[62:63]
	v_mov_b32_e32 v247, v69
	v_cvt_pk_bf16_f32 v246, v1, v75
	v_or_b32_e32 v69, v247, v246
	global_store_dword v[66:67], v69, off
	v_or_b32_e32 v66, v104, v214
	v_mov_b32_e32 v67, v105
	v_lshlrev_b64 v[66:67], 1, v[66:67]
	v_cvt_pk_bf16_f32 v73, v68, v1
	v_lshl_add_u64 v[66:67], v[66:67], 1, s[62:63]
	v_mov_b32_e32 v247, v73
	v_cvt_pk_bf16_f32 v246, v1, v77
	v_or_b32_e32 v68, v247, v246
	global_store_dword v[66:67], v68, off
	v_or_b32_e32 v66, v108, v214
	v_mov_b32_e32 v67, v109
	v_lshlrev_b64 v[66:67], 1, v[66:67]
	v_fma_f32 v89, v170, v86, v87
	v_cvt_pk_bf16_f32 v73, v71, v1
	v_mov_b32_e32 v247, v73
	v_mov_b32_e32 v168, v82
	v_mul_f32_e32 v68, v89, v169
	v_pk_fma_f32 v[68:69], v[88:89], v[168:169], v[68:69] op_sel_hi:[1,1,0]
	v_mul_f32_e32 v77, v170, v180
	v_mov_b32_e32 v75, v68
	v_mov_b32_e32 v170, v84
	v_mul_f32_e32 v69, v169, v77
	v_pk_mul_f32 v[74:75], v[74:75], v[170:171]
	v_lshl_add_u64 v[66:67], v[66:67], 1, s[62:63]
	v_add_f32_e32 v82, v74, v75
	v_mul_f32_e32 v74, v171, v69
	ds_bpermute_b32 v75, v134, v74
	ds_bpermute_b32 v84, v134, v82
	v_cvt_pk_bf16_f32 v246, v1, v80
	v_or_b32_e32 v73, v247, v246
	global_store_dword v[66:67], v73, off
	ds_bpermute_b32 v66, v134, v74 offset:64
	ds_bpermute_b32 v67, v134, v82 offset:64
	s_waitcnt lgkmcnt(2)
; __device__ __forceinline__ unsigned cvt_pk_bf16(float lo, float hi) { unsigned r; asm volatile("v_cvt_pk_bf16_f32 %0, %1, %2" : "=v"(r) : "v"(lo), "v"(hi)); return r; }
; template <int NT> ...
;     ...
;     for (int u = 0; u < NT; ++u) {
; #pragma unroll
;         for (int n = 0; n < 4; ++n) { const int ch = hc0 + 16 * n + fr;
;             float hl[4], pl[4];
;             hl[0] = bv[u][n][0]; pl[0] = av[u][n][0];
; #pragma unroll
;             for (int j = 1; j < 4; ++j) { hl[j] = av[u][n][j] * hl[j - 1] + bv[u][n][j]; pl[j] = av[u][n][j] * pl[j - 1]; }
;             float He = 0.f, Pe = 1.f;
; #pragma unroll
;             for (int g = 0; g < 3; ++g) { const float Pg = __shfl(pl[3], fr + 16 * g), Hg = __shfl(hl[3], fr + 16 * g); if (g < fq) { He = Pg * He + Hg; Pe = Pg * Pe; } }
;             const float Hin = Pe * Hc[n] + He, Pin = Pe * Pc[n];
;             float hf[4], pf[4];
; #pragma unroll
;             for (int j = 0; j < 4; ++j) { hf[j] = hl[j] + pl[j] * Hin; pf[j] = pl[j] * Pin; }
; #pragma unroll
;             for (int j = 0; j < 4; ++j) { const size_t o = (size_t)(m0 + 16 * u + 4 * fq + j) * D + ch; HLOC[o] = (bf16_t)(cvt_pk_bf16(hf[j], 0.f) & 0xffffu); PCUM[o] = (bf16_t)(cvt_pk_bf16(pf[j], 0.f) & 0xffffu); }
;             Hc[n] = __shfl(hf[3], fr + 48); Pc[n] = __shfl(pf[3], fr + 48);
	v_fmac_f32_e32 v84, 0, v75
	ds_bpermute_b32 v73, v134, v80 offset:192
	v_cndmask_b32_e64 v80, v84, 0, s[8:9]
	ds_bpermute_b32 v84, v134, v74 offset:128
	ds_bpermute_b32 v87, v134, v82 offset:128
	ds_bpermute_b32 v111, v134, v114 offset:192
	v_cndmask_b32_e64 v75, v75, 1.0, s[8:9]
	s_waitcnt lgkmcnt(4)
	v_fmac_f32_e32 v67, v80, v66
	v_mul_f32_e32 v66, v75, v66
	v_cndmask_b32_e64 v67, v80, v67, s[4:5]
	v_cndmask_b32_e64 v66, v75, v66, s[4:5]
	s_waitcnt lgkmcnt(1)
	v_fmac_f32_e32 v87, v67, v84
	v_mul_f32_e32 v75, v66, v84
	v_cndmask_b32_e64 v67, v67, v87, s[6:7]
	v_cndmask_b32_e64 v66, v66, v75, s[6:7]
	v_fmac_f32_e32 v67, v66, v110
	s_waitcnt lgkmcnt(0)
	v_mul_f32_e32 v66, v66, v111
	v_fmac_f32_e32 v86, v180, v67
	v_mul_f32_e32 v80, v180, v66
	v_fmac_f32_e32 v89, v77, v67
	v_mul_f32_e32 v77, v77, v66
	v_fmac_f32_e32 v68, v69, v67
	v_mul_f32_e32 v84, v69, v66
	v_fmac_f32_e32 v82, v74, v67
	v_mul_f32_e32 v87, v74, v66
	v_or_b32_e32 v66, v106, v212
	v_mov_b32_e32 v67, v107
	v_lshlrev_b64 v[66:67], 1, v[66:67]
	v_cvt_pk_bf16_f32 v69, v86, v1
	v_lshl_add_u64 v[66:67], v[66:67], 1, s[62:63]
	v_mov_b32_e32 v247, v69
	v_cvt_pk_bf16_f32 v246, v1, v80
	v_or_b32_e32 v69, v247, v246
	global_store_dword v[66:67], v69, off
	v_or_b32_e32 v66, v102, v212
	v_mov_b32_e32 v67, v103
	v_lshlrev_b64 v[66:67], 1, v[66:67]
	v_cvt_pk_bf16_f32 v69, v89, v1
	v_lshl_add_u64 v[66:67], v[66:67], 1, s[62:63]
	v_mov_b32_e32 v247, v69
	v_cvt_pk_bf16_f32 v246, v1, v77
	v_or_b32_e32 v69, v247, v246
	global_store_dword v[66:67], v69, off
	v_or_b32_e32 v66, v104, v212
	v_mov_b32_e32 v67, v105
	v_lshlrev_b64 v[66:67], 1, v[66:67]
	v_cvt_pk_bf16_f32 v74, v68, v1
	v_lshl_add_u64 v[66:67], v[66:67], 1, s[62:63]
	v_mov_b32_e32 v247, v74
	v_cvt_pk_bf16_f32 v246, v1, v84
	v_or_b32_e32 v68, v247, v246
	global_store_dword v[66:67], v68, off
	v_or_b32_e32 v66, v108, v212
	v_mov_b32_e32 v67, v109
	v_lshlrev_b64 v[66:67], 1, v[66:67]
	v_fma_f32 v77, v154, v78, v79
	v_cvt_pk_bf16_f32 v74, v82, v1
	v_mov_b32_e32 v247, v74
	v_mov_b32_e32 v172, v83
	v_mul_f32_e32 v68, v77, v173
	v_pk_fma_f32 v[74:75], v[76:77], v[172:173], v[68:69] op_sel_hi:[1,1,0]
	v_mul_f32_e32 v79, v154, v152
	v_mov_b32_e32 v131, v74
	v_mov_b32_e32 v80, v85
	v_mul_f32_e32 v75, v173, v79
	v_pk_mul_f32 v[68:69], v[130:131], v[80:81]
	v_mul_f32_e32 v76, v81, v75
	v_add_f32_e32 v69, v68, v69
	ds_bpermute_b32 v80, v134, v76
	ds_bpermute_b32 v81, v134, v69
	v_lshl_add_u64 v[66:67], v[66:67], 1, s[62:63]
	v_cvt_pk_bf16_f32 v246, v1, v87
	v_or_b32_e32 v84, v247, v246
	global_store_dword v[66:67], v84, off
	ds_bpermute_b32 v66, v134, v82 offset:192
	ds_bpermute_b32 v67, v134, v76 offset:64
	ds_bpermute_b32 v82, v134, v69 offset:64
	ds_bpermute_b32 v83, v134, v76 offset:128
	ds_bpermute_b32 v84, v134, v69 offset:128
	s_waitcnt lgkmcnt(5)
	v_fmac_f32_e32 v81, 0, v80
	v_cndmask_b32_e64 v81, v81, 0, s[8:9]
	v_cndmask_b32_e64 v80, v80, 1.0, s[8:9]
	s_waitcnt lgkmcnt(2)
	v_fmac_f32_e32 v82, v81, v67
	v_mul_f32_e32 v67, v80, v67
	v_cndmask_b32_e64 v81, v81, v82, s[4:5]
	v_cndmask_b32_e64 v67, v80, v67, s[4:5]
	s_waitcnt lgkmcnt(0)
	v_fmac_f32_e32 v84, v81, v83
	v_mul_f32_e32 v80, v67, v83
	v_cndmask_b32_e64 v81, v81, v84, s[6:7]
	v_cndmask_b32_e64 v67, v67, v80, s[6:7]
	v_fmac_f32_e32 v81, v67, v112
	v_mul_f32_e32 v67, v67, v98
	v_fmac_f32_e32 v78, v152, v81
	v_or_b32_e32 v106, v106, v210
	v_mul_f32_e32 v82, v152, v67
	v_fmac_f32_e32 v77, v79, v81
	v_mul_f32_e32 v83, v79, v67
	v_mul_f32_e32 v84, v75, v67
	v_mul_f32_e32 v85, v76, v67
	v_cvt_pk_bf16_f32 v67, v78, v1
	v_lshlrev_b64 v[78:79], 1, v[106:107]
	v_fmac_f32_e32 v74, v75, v81
	v_fmac_f32_e32 v69, v76, v81
	v_mov_b32_e32 v247, v67
	v_cvt_pk_bf16_f32 v246, v1, v82
	v_or_b32_e32 v67, v247, v246
	v_lshl_add_u64 v[78:79], v[78:79], 1, s[62:63]
	v_or_b32_e32 v102, v102, v210
	global_store_dword v[78:79], v67, off
	v_cvt_pk_bf16_f32 v67, v77, v1
	v_lshlrev_b64 v[76:77], 1, v[102:103]
	v_mov_b32_e32 v247, v67
	v_cvt_pk_bf16_f32 v246, v1, v83
	v_or_b32_e32 v67, v247, v246
	v_lshl_add_u64 v[76:77], v[76:77], 1, s[62:63]
	v_or_b32_e32 v104, v104, v210
	global_store_dword v[76:77], v67, off
	v_cvt_pk_bf16_f32 v67, v74, v1
	v_lshlrev_b64 v[74:75], 1, v[104:105]
	v_lshl_add_u64 v[74:75], v[74:75], 1, s[62:63]
	v_or_b32_e32 v108, v108, v210
	v_mov_b32_e32 v247, v67
	v_cvt_pk_bf16_f32 v246, v1, v84
	v_or_b32_e32 v67, v247, v246
	global_store_dword v[74:75], v67, off
	v_lshlrev_b64 v[74:75], 1, v[108:109]
	v_cvt_pk_bf16_f32 v67, v69, v1
	v_mov_b32_e32 v247, v67
	v_cvt_pk_bf16_f32 v246, v1, v85
	v_or_b32_e32 v67, v247, v246
	v_lshl_add_u64 v[74:75], v[74:75], 1, s[62:63]
	ds_bpermute_b32 v71, v134, v71 offset:192
	ds_bpermute_b32 v68, v134, v87 offset:192
	global_store_dword v[74:75], v67, off
	ds_bpermute_b32 v67, v134, v69 offset:192
	ds_bpermute_b32 v69, v134, v85 offset:192
	v_add_u32_e32 v242, 32, v242
	v_subrev_u32_e32 v245, 32, v245
	s_cbranch_scc1 .LBB0_342

; #define LAS __attribute__((address_space(3)))
; template <int NT> ...
;     ...
;     for (int u = 0; u < NT; ++u) { const int m = m0 + 16 * u + rr, t = m - b * TP; LAS float* XC = XCb + u * (16 * 68);
;         float xv[4][16];
; #pragma unroll
;         for (int k = 0; k < 4; ++k) { float f0[8], f1[8]; unpack8(raw[u][k][0], f0); unpack8(raw[u][k][1], f1);
; #pragma unroll
;             for (int e = 0; e < 8; ++e) { xv[k][e] = f0[e]; xv[k][8 + e] = f1[e]; } }
;         if (t >= TP - 3) { float* o = p->out + O_PCB + ((size_t)(l * NB + b) * 3 + (t - (TP - 3))) * D + hc0 + cl;
; #pragma unroll
;             for (int e = 0; e < 16; e += 4) *(f32x4*)(o + e) = (f32x4){xv[3][e], xv[3][e + 1], xv[3][e + 2], xv[3][e + 3]}; }
; #pragma unroll
;         for (int e = 0; e < 16; e += 4) {
;             const f32x4 w0 = *(const LAS f32x4*)(CST + 0 * 64 + cl + e), w1 = *(const LAS f32x4*)(CST + 1 * 64 + cl + e), w2 = *(const LAS f32x4*)(CST + 2 * 64 + cl + e),
;                         w3 = *(const LAS f32x4*)(CST + 3 * 64 + cl + e), bb = *(const LAS f32x4*)(CST + 4 * 64 + cl + e);
;             f32x4 r;
; #pragma unroll
;             for (int q = 0; q < 4; ++q) r[q] = w0[q] * xv[0][e + q] + w1[q] * xv[1][e + q] + w2[q] * xv[2][e + q] + w3[q] * xv[3][e + q] + bb[q];
;             *(LAS f32x4*)(XC + rr * 68 + cl + e) = r;
;         } }
.LBB0_353:
	s_or_b64 exec, exec, s[10:11]
	ds_read_b128 v[114:117], v227 offset:8704
	ds_read_b128 v[118:121], v227 offset:8960
	ds_read_b128 v[122:125], v227 offset:9216
	ds_read_b128 v[126:129], v227 offset:9472
	ds_read_b128 v[130:133], v227 offset:9728
	v_lshlrev_b32_e32 v138, 16, v86
	v_and_b32_e32 v139, 0xffff0000, v86
	v_lshlrev_b32_e32 v86, 16, v87
	v_and_b32_e32 v87, 0xffff0000, v87
	v_lshlrev_b32_e32 v140, 16, v82
	v_and_b32_e32 v141, 0xffff0000, v82
	s_waitcnt lgkmcnt(3)
	v_pk_mul_f32 v[118:119], v[118:119], v[138:139]
	v_lshlrev_b32_e32 v82, 16, v83
	v_and_b32_e32 v83, 0xffff0000, v83
	v_pk_mul_f32 v[86:87], v[120:121], v[86:87]
	v_lshlrev_b32_e32 v136, 16, v98
	v_and_b32_e32 v137, 0xffff0000, v98
	v_pk_fma_f32 v[114:115], v[114:115], v[140:141], v[118:119]
	v_lshlrev_b32_e32 v98, 16, v99
	v_and_b32_e32 v99, 0xffff0000, v99
	v_pk_fma_f32 v[82:83], v[116:117], v[82:83], v[86:87]
	s_waitcnt lgkmcnt(2)
	v_pk_fma_f32 v[114:115], v[122:123], v[136:137], v[114:115]
	v_pk_fma_f32 v[82:83], v[124:125], v[98:99], v[82:83]
	s_waitcnt lgkmcnt(1)
	v_pk_fma_f32 v[110:111], v[126:127], v[110:111], v[114:115]
	v_pk_fma_f32 v[82:83], v[128:129], v[112:113], v[82:83]
	s_waitcnt lgkmcnt(0)
	v_pk_add_f32 v[110:111], v[130:131], v[110:111]
	v_pk_add_f32 v[112:113], v[132:133], v[82:83]
	ds_write_b128 v240, v[110:113]
	ds_read_b128 v[110:113], v227 offset:8720
	ds_read_b128 v[114:117], v227 offset:8976
	ds_read_b128 v[118:121], v227 offset:9232
	ds_read_b128 v[122:125], v227 offset:9488
	ds_read_b128 v[126:129], v227 offset:9744
	v_lshlrev_b32_e32 v86, 16, v88
	v_and_b32_e32 v87, 0xffff0000, v88
	v_lshlrev_b32_e32 v98, 16, v84
	v_and_b32_e32 v99, 0xffff0000, v84
	s_waitcnt lgkmcnt(3)
	v_pk_mul_f32 v[86:87], v[114:115], v[86:87]
	v_lshlrev_b32_e32 v88, 16, v89
	v_and_b32_e32 v89, 0xffff0000, v89
	v_lshlrev_b32_e32 v82, 16, v100
	v_and_b32_e32 v83, 0xffff0000, v100
	v_pk_fma_f32 v[86:87], v[110:111], v[98:99], v[86:87]
	v_lshlrev_b32_e32 v84, 16, v85
	v_and_b32_e32 v85, 0xffff0000, v85
	v_pk_mul_f32 v[88:89], v[116:117], v[88:89]
	s_waitcnt lgkmcnt(2)
	v_pk_fma_f32 v[82:83], v[118:119], v[82:83], v[86:87]
	v_lshlrev_b32_e32 v86, 16, v101
	v_and_b32_e32 v87, 0xffff0000, v101
	v_pk_fma_f32 v[84:85], v[112:113], v[84:85], v[88:89]
	s_waitcnt lgkmcnt(1)
	v_pk_fma_f32 v[82:83], v[122:123], v[106:107], v[82:83]
	v_pk_fma_f32 v[84:85], v[120:121], v[86:87], v[84:85]
	s_waitcnt lgkmcnt(0)
	v_pk_add_f32 v[82:83], v[126:127], v[82:83]
	v_pk_fma_f32 v[84:85], v[124:125], v[108:109], v[84:85]
	v_lshlrev_b32_e32 v116, 16, v78
	v_pk_add_f32 v[84:85], v[128:129], v[84:85]
	ds_write_b128 v240, v[82:85] offset:16
	ds_read_b128 v[82:85], v227 offset:8736
	ds_read_b128 v[86:89], v227 offset:8992
	ds_read_b128 v[98:101], v227 offset:9248
	ds_read_b128 v[106:109], v227 offset:9504
	ds_read_b128 v[110:113], v227 offset:9760
	v_and_b32_e32 v117, 0xffff0000, v78
	v_lshlrev_b32_e32 v78, 16, v79
	v_and_b32_e32 v79, 0xffff0000, v79
	v_lshlrev_b32_e32 v118, 16, v74
	v_and_b32_e32 v119, 0xffff0000, v74
	s_waitcnt lgkmcnt(3)
	v_pk_mul_f32 v[86:87], v[86:87], v[116:117]
	v_lshlrev_b32_e32 v74, 16, v75
	v_and_b32_e32 v75, 0xffff0000, v75
	v_pk_mul_f32 v[78:79], v[88:89], v[78:79]
	v_lshlrev_b32_e32 v114, 16, v90
	v_and_b32_e32 v115, 0xffff0000, v90
	v_pk_fma_f32 v[82:83], v[82:83], v[118:119], v[86:87]
	v_lshlrev_b32_e32 v86, 16, v91
	v_and_b32_e32 v87, 0xffff0000, v91
	v_pk_fma_f32 v[74:75], v[84:85], v[74:75], v[78:79]
	s_waitcnt lgkmcnt(2)
	v_pk_fma_f32 v[82:83], v[98:99], v[114:115], v[82:83]
	v_pk_fma_f32 v[74:75], v[100:101], v[86:87], v[74:75]
	s_waitcnt lgkmcnt(1)
	v_pk_fma_f32 v[82:83], v[106:107], v[102:103], v[82:83]
	v_pk_fma_f32 v[74:75], v[108:109], v[104:105], v[74:75]
	s_waitcnt lgkmcnt(0)
	v_pk_add_f32 v[82:83], v[110:111], v[82:83]
	v_pk_add_f32 v[84:85], v[112:113], v[74:75]
	ds_write_b128 v240, v[82:85] offset:32
	ds_read_b128 v[82:85], v227 offset:8752
	ds_read_b128 v[86:89], v227 offset:9008
	ds_read_b128 v[98:101], v227 offset:9264
	ds_read_b128 v[102:105], v227 offset:9520
	ds_read_b128 v[106:109], v227 offset:9776
	v_lshlrev_b32_e32 v78, 16, v80
	v_and_b32_e32 v79, 0xffff0000, v80
	v_lshlrev_b32_e32 v90, 16, v76
	v_and_b32_e32 v91, 0xffff0000, v76
	s_waitcnt lgkmcnt(3)
	v_pk_mul_f32 v[78:79], v[86:87], v[78:79]
	v_lshlrev_b32_e32 v80, 16, v81
	v_and_b32_e32 v81, 0xffff0000, v81
	v_lshlrev_b32_e32 v74, 16, v92
	v_and_b32_e32 v75, 0xffff0000, v92
	v_pk_fma_f32 v[78:79], v[82:83], v[90:91], v[78:79]
	v_lshlrev_b32_e32 v76, 16, v77
	v_and_b32_e32 v77, 0xffff0000, v77
	v_pk_mul_f32 v[80:81], v[88:89], v[80:81]
	s_waitcnt lgkmcnt(2)
	v_pk_fma_f32 v[74:75], v[98:99], v[74:75], v[78:79]
	v_lshlrev_b32_e32 v78, 16, v93
	v_and_b32_e32 v79, 0xffff0000, v93
	v_pk_fma_f32 v[76:77], v[84:85], v[76:77], v[80:81]
	s_waitcnt lgkmcnt(1)
	v_pk_fma_f32 v[74:75], v[102:103], v[94:95], v[74:75]
	v_pk_fma_f32 v[76:77], v[100:101], v[78:79], v[76:77]
	s_waitcnt lgkmcnt(0)
	v_pk_add_f32 v[74:75], v[106:107], v[74:75]
	v_pk_fma_f32 v[76:77], v[104:105], v[96:97], v[76:77]
	s_add_i32 s12, s18, s12
	v_pk_add_f32 v[76:77], v[108:109], v[76:77]
	ds_write_b128 v240, v[74:77] offset:48
	s_waitcnt lgkmcnt(0)
	ds_read_b128 v[74:77], v239
	ds_read_b128 v[78:81], v239 offset:16
	s_waitcnt lgkmcnt(1)
	v_cvt_pk_bf16_f32 v74, v74, v75
	v_cvt_pk_bf16_f32 v75, v76, v77
	s_waitcnt lgkmcnt(0)
; #define LAS __attribute__((address_space(3)))
; __device__ __forceinline__ unsigned cvt_pk_bf16(float lo, float hi) { unsigned r; asm volatile("v_cvt_pk_bf16_f32 %0, %1, %2" : "=v"(r) : "v"(lo), "v"(hi)); return r; }
; __device__ __forceinline__ float sigmoidf_(float x) { return __builtin_amdgcn_rcpf(1.0f + __expf(-x)); }
; template <int NT> ...
;     ...
;     for (int u = 0; u < NT; ++u) { const LAS float* XC = XCb + u * (16 * 68);
; #pragma unroll
;         for (int n = 0; n < 4; ++n) { ar[u][n] = (f32x4){0.f, 0.f, 0.f, 0.f}; ai[u][n] = (f32x4){0.f, 0.f, 0.f, 0.f}; }
; #pragma unroll
;         for (int s = 0; s < 2; ++s) {
;             const f32x4 x0 = *(const LAS f32x4*)(XC + fr * 68 + 32 * s + 8 * fq), x1 = *(const LAS f32x4*)(XC + fr * 68 + 32 * s + 8 * fq + 4);
;             u32x4 aw; aw.x = cvt_pk_bf16(x0[0], x0[1]); aw.y = cvt_pk_bf16(x0[2], x0[3]); aw.z = cvt_pk_bf16(x1[0], x1[1]); aw.w = cvt_pk_bf16(x1[2], x1[3]);
;             const bf16x8 af = __builtin_bit_cast(bf16x8, aw);
; #pragma unroll
;             for (int n = 0; n < 4; ++n) { ar[u][n] = __builtin_amdgcn_mfma_f32_16x16x32_bf16(af, Wa[n][s], ar[u][n], 0, 0, 0); ai[u][n] = __builtin_amdgcn_mfma_f32_16x16x32_bf16(af, Wx[n][s], ai[u][n], 0, 0, 0); }
;         } }
;     float av[NT][4][4], bv[NT][4][4];
; #pragma unroll
;     for (int u = 0; u < NT; ++u) { const LAS float* XC = XCb + u * (16 * 68); const int t0 = m0 + 16 * u - b * TP;
; #pragma unroll
;         for (int n = 0; n < 4; ++n) { const int cc = 16 * n + fr;
;             const float ba = CST[5 * 64 + cc], bx = CST[6 * 64 + cc], sp = CST[7 * 64 + cc];
; #pragma unroll
;             for (int j = 0; j < 4; ++j) {
;                 const float xc = XC[(4 * fq + j) * 68 + cc];
;                 const float r = sigmoidf_(ar[u][n][j] + ba), ig = sigmoidf_(ai[u][n][j] + bx);
;                 const float a = __expf(-8.0f * r * sp);
;                 float mult = sqrtf(fmaxf(1.0f - a * a, 0.f));
;                 if (t0 + 4 * fq + j == 0) mult = 1.0f;
;                 av[u][n][j] = a; bv[u][n][j] = mult * ig * xc; } } }
	v_cvt_pk_bf16_f32 v76, v78, v79
	v_cvt_pk_bf16_f32 v77, v80, v81
	s_nop 0
	v_mfma_f32_16x16x32_bf16 v[78:81], v[74:77], v[54:57], 0
	ds_read_b128 v[54:57], v239 offset:128
	ds_read_b128 v[82:85], v239 offset:144
	v_mfma_f32_16x16x32_bf16 v[34:37], v[74:77], v[34:37], 0
	v_mfma_f32_16x16x32_bf16 v[42:45], v[74:77], v[42:45], 0
	v_mfma_f32_16x16x32_bf16 v[46:49], v[74:77], v[46:49], 0
	v_mfma_f32_16x16x32_bf16 v[38:41], v[74:77], v[38:41], 0
	v_mfma_f32_16x16x32_bf16 v[50:53], v[74:77], v[50:53], 0
	v_mfma_f32_16x16x32_bf16 v[62:65], v[74:77], v[62:65], 0
	v_mfma_f32_16x16x32_bf16 v[58:61], v[74:77], v[58:61], 0
	s_waitcnt lgkmcnt(1)
	v_cvt_pk_bf16_f32 v74, v54, v55
	v_cvt_pk_bf16_f32 v75, v56, v57
	s_waitcnt lgkmcnt(0)
	v_cvt_pk_bf16_f32 v76, v82, v83
	v_cvt_pk_bf16_f32 v77, v84, v85
	v_or_b32_e32 v55, 64, v134
	v_mfma_f32_16x16x32_bf16 v[82:85], v[74:77], v[10:13], v[34:37]
	v_or_b32_e32 v54, 0x80, v134
	v_mfma_f32_16x16x32_bf16 v[34:37], v[74:77], v[22:25], v[42:45]
	v_mfma_f32_16x16x32_bf16 v[22:25], v[74:77], v[26:29], v[46:49]
	ds_read2_b32 v[28:29], v177 offset0:192 offset1:208
	s_nop 0
	ds_read2_b32 v[42:43], v241 offset1:16
	s_waitcnt lgkmcnt(1)
	s_nop 0
	v_add_f32_e32 v0, v82, v28
	v_mul_f32_e32 v0, 0xbfb8aa3b, v0
	v_mfma_f32_16x16x32_bf16 v[10:13], v[74:77], v[18:21], v[78:81]
	v_exp_f32_e32 v18, v0
	ds_read2_b32 v[46:47], v241 offset0:68 offset1:84
	v_add_f32_e32 v34, v34, v29
	v_mfma_f32_16x16x32_bf16 v[86:89], v[74:77], v[14:17], v[38:41]
	v_add_f32_e32 v18, 1.0, v18
	v_rcp_f32_e32 v18, v18
	v_mul_f32_e32 v34, 0xbfb8aa3b, v34
	ds_read2_b32 v[38:39], v176 offset0:64 offset1:80
	ds_read2_b32 v[40:41], v176 offset1:16
	v_mul_f32_e32 v18, 0xc1000000, v18
	v_mfma_f32_16x16x32_bf16 v[14:17], v[74:77], v[30:33], v[50:53]
	v_exp_f32_e32 v34, v34
	s_waitcnt lgkmcnt(1)
	v_mul_f32_e32 v18, v38, v18
	v_mul_f32_e32 v18, 0x3fb8aa3b, v18
	v_exp_f32_e32 v44, v18
	s_waitcnt lgkmcnt(0)
	v_add_f32_e32 v18, v86, v40
	v_mul_f32_e32 v18, 0xbfb8aa3b, v18
	v_exp_f32_e32 v18, v18
	v_fma_f32 v19, -v44, v44, 1.0
	v_max_f32_e32 v19, 0, v19
	v_add_f32_e32 v18, 1.0, v18
	v_add_f32_e32 v34, 1.0, v34
	v_mov_b32_e32 v20, v19
	v_rcp_f32_e32 v19, v18
	v_rcp_f32_e32 v34, v34
	v_add_f32_e32 v22, v22, v41
	v_mul_f32_e32 v34, 0xc1000000, v34
	v_mul_f32_e32 v34, v39, v34
	v_mul_f32_e32 v34, 0x3fb8aa3b, v34
	v_add_f32_e32 v26, v83, v28
	v_mul_f32_e32 v26, 0xbfb8aa3b, v26
	v_exp_f32_e32 v26, v26
	v_or_b32_e32 v21, s12, v224
	v_exp_f32_e32 v56, v34
	v_sqrt_f32_e32 v18, v20
	s_nop 0
	v_add_f32_e32 v20, 1.0, v26
	v_rcp_f32_e32 v20, v20
	v_cmp_eq_u32_e32 vcc, 0, v21
	v_fma_f32 v34, -v56, v56, 1.0
	v_max_f32_e32 v34, 0, v34
	v_cndmask_b32_e64 v21, v18, 1.0, vcc
	v_mul_f32_e32 v18, 0xc1000000, v20
	v_mul_f32_e32 v18, v38, v18
	v_mul_f32_e32 v18, 0x3fb8aa3b, v18
	v_exp_f32_e32 v30, v18
	v_add_f32_e32 v18, v87, v40
	v_mul_f32_e32 v18, 0xbfb8aa3b, v18
	v_exp_f32_e32 v18, v18
	v_fma_f32 v20, -v30, v30, 1.0
	v_max_f32_e32 v20, 0, v20
	v_add_f32_e32 v18, 1.0, v18
	v_rcp_f32_e32 v18, v18
	v_mul_f32_e32 v22, 0xbfb8aa3b, v22
	v_exp_f32_e32 v22, v22
	v_add_f32_e32 v35, v35, v29
	v_mul_f32_e32 v35, 0xbfb8aa3b, v35
	v_exp_f32_e32 v35, v35
	v_add_f32_e32 v22, 1.0, v22
	v_add_f32_e32 v27, v84, v28
	v_mul_f32_e32 v27, 0xbfb8aa3b, v27
	v_exp_f32_e32 v27, v27
	v_add_f32_e32 v28, v85, v28
	v_mul_f32_e32 v28, 0xbfb8aa3b, v28
	v_sqrt_f32_e32 v20, v20
	s_nop 0
	v_pk_mul_f32 v[18:19], v[18:19], v[20:21]
	v_add_f32_e32 v20, 1.0, v27
	v_rcp_f32_e32 v26, v20
	v_mov_b32_e32 v20, v46
	v_mov_b32_e32 v21, v42
	v_pk_mul_f32 v[20:21], v[20:21], v[18:19]
	v_mul_f32_e32 v18, 0xc1000000, v26
	v_mul_f32_e32 v18, v38, v18
	v_mul_f32_e32 v18, 0x3fb8aa3b, v18
	v_exp_f32_e32 v31, v18
	v_add_f32_e32 v18, v88, v40
	v_mul_f32_e32 v18, 0xbfb8aa3b, v18
	v_exp_f32_e32 v26, v18
	v_fma_f32 v18, -v31, v31, 1.0
	v_max_f32_e32 v18, 0, v18
	v_exp_f32_e32 v28, v28
	v_add_f32_e32 v26, 1.0, v26
	v_mov_b32_e32 v27, v18
	v_add_f32_e32 v28, 1.0, v28
	v_rcp_f32_e32 v26, v26
	v_rcp_f32_e32 v49, v22
	v_add_f32_e32 v35, 1.0, v35
	v_rcp_f32_e32 v35, v35
	v_add_f32_e32 v23, v23, v41
	v_rcp_f32_e32 v33, v28
	v_mul_f32_e32 v23, 0xbfb8aa3b, v23
	v_add_f32_e32 v36, v36, v29
	v_sqrt_f32_e32 v27, v27
	s_nop 0
	v_mul_f32_e32 v28, v26, v27
	v_mul_f32_e32 v26, 0xc1000000, v33
	v_mul_f32_e32 v26, v38, v26
	v_mul_f32_e32 v26, 0x3fb8aa3b, v26
	v_exp_f32_e32 v33, v26
	v_add_f32_e32 v26, v89, v40
	v_mul_f32_e32 v26, 0xbfb8aa3b, v26
	v_exp_f32_e32 v32, v26
	v_fma_f32 v26, -v33, v33, 1.0
	v_max_f32_e32 v26, 0, v26
	v_add_f32_e32 v32, 1.0, v32
	v_rcp_f32_e32 v32, v32
	v_mov_b32_e32 v38, v26
	v_mul_f32_e32 v36, 0xbfb8aa3b, v36
	v_exp_f32_e32 v36, v36
	v_add_f32_e32 v29, v37, v29
	v_mul_f32_e32 v29, 0xbfb8aa3b, v29
	v_exp_f32_e32 v29, v29
	v_add_f32_e32 v24, v24, v41
	v_add_f32_e32 v29, 1.0, v29
	v_mov_b32_e32 v42, v47
	v_sqrt_f32_e32 v38, v38
	s_nop 0
	v_mul_f32_e32 v38, v32, v38
	v_rcp_f32_e32 v29, v29
	v_mul_f32_e32 v24, 0xbfb8aa3b, v24
	v_mul_f32_e32 v29, 0xc1000000, v29
	v_mul_f32_e32 v29, v39, v29
	v_mul_f32_e32 v29, 0x3fb8aa3b, v29
	v_exp_f32_e32 v24, v24
	ds_read2_b32 v[46:47], v176 offset0:96 offset1:112
	v_mul_f32_e32 v32, 0xc1000000, v35
	v_mul_f32_e32 v32, v39, v32
	v_mul_f32_e32 v32, 0x3fb8aa3b, v32
	v_add_f32_e32 v24, 1.0, v24
	v_sqrt_f32_e32 v22, v34
	s_nop 0
	v_exp_f32_e32 v34, v32
	v_exp_f32_e32 v32, v23
	v_rcp_f32_e32 v24, v24
	v_add_f32_e32 v25, v25, v41
	v_fma_f32 v23, -v34, v34, 1.0
	v_max_f32_e32 v23, 0, v23
	v_mul_f32_e32 v25, 0xbfb8aa3b, v25
	v_exp_f32_e32 v25, v25
	v_mov_b32_e32 v35, v23
	v_cndmask_b32_e64 v23, v22, 1.0, vcc
	v_add_f32_e32 v22, 1.0, v32
	v_rcp_f32_e32 v48, v22
	ds_read2_b32 v[50:51], v176 offset0:32 offset1:48
	v_add_f32_e32 v25, 1.0, v25
	v_rcp_f32_e32 v25, v25
	v_add_f32_e32 v32, 1.0, v36
	v_rcp_f32_e32 v32, v32
	s_waitcnt lgkmcnt(0)
; #define LAS __attribute__((address_space(3)))
; __device__ __forceinline__ float sigmoidf_(float x) { return __builtin_amdgcn_rcpf(1.0f + __expf(-x)); }
; template <int NT> ...
;     ...
;     for (int u = 0; u < NT; ++u) { const LAS float* XC = XCb + u * (16 * 68); const int t0 = m0 + 16 * u - b * TP;
; #pragma unroll
;         for (int n = 0; n < 4; ++n) { const int cc = 16 * n + fr;
;             const float ba = CST[5 * 64 + cc], bx = CST[6 * 64 + cc], sp = CST[7 * 64 + cc];
; #pragma unroll
;             for (int j = 0; j < 4; ++j) {
;                 const float xc = XC[(4 * fq + j) * 68 + cc];
;                 const float r = sigmoidf_(ar[u][n][j] + ba), ig = sigmoidf_(ai[u][n][j] + bx);
;                 const float a = __expf(-8.0f * r * sp);
;                 float mult = sqrtf(fmaxf(1.0f - a * a, 0.f));
;                 if (t0 + 4 * fq + j == 0) mult = 1.0f;
;                 av[u][n][j] = a; bv[u][n][j] = mult * ig * xc; } } }
; #pragma unroll
;     for (int u = 0; u < NT; ++u) {
; #pragma unroll
;         for (int n = 0; n < 4; ++n) { const int ch = hc0 + 16 * n + fr;
;             float hl[4], pl[4];
;             hl[0] = bv[u][n][0]; pl[0] = av[u][n][0];
; #pragma unroll
;             for (int j = 1; j < 4; ++j) { hl[j] = av[u][n][j] * hl[j - 1] + bv[u][n][j]; pl[j] = av[u][n][j] * pl[j - 1]; }
;             float He = 0.f, Pe = 1.f;
; #pragma unroll
;             for (int g = 0; g < 3; ++g) { const float Pg = __shfl(pl[3], fr + 16 * g), Hg = __shfl(hl[3], fr + 16 * g); if (g < fq) { He = Pg * He + Hg; Pe = Pg * Pe; } }
;             const float Hin = Pe * Hc[n] + He, Pin = Pe * Pc[n];
	v_add_f32_e32 v10, v10, v50
	v_mul_f32_e32 v10, 0xbfb8aa3b, v10
	v_mul_f32_e32 v32, 0xc1000000, v32
	v_mul_f32_e32 v32, v39, v32
	v_mul_f32_e32 v32, 0x3fb8aa3b, v32
	v_sqrt_f32_e32 v22, v35
	s_nop 0
	v_exp_f32_e32 v35, v32
	v_pk_mul_f32 v[22:23], v[48:49], v[22:23]
	ds_read2_b32 v[48:49], v177 offset0:224 offset1:240
	v_pk_mul_f32 v[22:23], v[42:43], v[22:23]
	v_fma_f32 v32, -v35, v35, 1.0
	v_max_f32_e32 v32, 0, v32
	s_waitcnt lgkmcnt(0)
	v_add_f32_e32 v14, v14, v48
	v_mul_f32_e32 v14, 0xbfb8aa3b, v14
	v_exp_f32_e32 v14, v14
	v_exp_f32_e32 v10, v10
	v_mfma_f32_16x16x32_bf16 v[2:5], v[74:77], v[2:5], v[58:61]
	v_add_f32_e32 v14, 1.0, v14
	v_rcp_f32_e32 v14, v14
	v_add_f32_e32 v10, 1.0, v10
	v_exp_f32_e32 v37, v29
	v_mul_f32_e32 v14, 0xc1000000, v14
	v_mul_f32_e32 v14, v46, v14
	v_fma_f32 v29, -v37, v37, 1.0
	v_max_f32_e32 v29, 0, v29
	v_sqrt_f32_e32 v32, v32
	s_nop 0
	v_mul_f32_e32 v24, v24, v32
	v_mul_f32_e32 v14, 0x3fb8aa3b, v14
	v_exp_f32_e32 v57, v14
	v_rcp_f32_e32 v59, v10
	v_add_f32_e32 v15, v15, v48
	v_fma_f32 v14, -v57, v57, 1.0
	v_max_f32_e32 v14, 0, v14
	v_mul_f32_e32 v15, 0xbfb8aa3b, v15
	v_exp_f32_e32 v15, v15
	ds_read2_b32 v[52:53], v241 offset0:32 offset1:48
	v_sqrt_f32_e32 v29, v29
	s_nop 0
	v_mul_f32_e32 v40, v25, v29
	v_add_f32_e32 v15, 1.0, v15
	ds_read2_b32 v[60:61], v241 offset0:100 offset1:116
	v_add_f32_e32 v17, v17, v48
	v_mul_f32_e32 v17, 0xbfb8aa3b, v17
	v_exp_f32_e32 v17, v17
	s_nop 0
	v_add_f32_e32 v17, 1.0, v17
	v_rcp_f32_e32 v17, v17
	v_mfma_f32_16x16x32_bf16 v[6:9], v[74:77], v[6:9], v[62:65]
	s_nop 0
	s_nop 0
	s_nop 0
	v_rcp_f32_e32 v25, v15
	s_nop 0
	s_nop 2
	v_add_f32_e32 v6, v6, v49
	v_mul_f32_e32 v6, 0xbfb8aa3b, v6
	v_sqrt_f32_e32 v10, v14
	s_nop 0
	v_cndmask_b32_e64 v15, v10, 1.0, vcc
	v_mul_f32_e32 v10, 0xc1000000, v25
	v_mul_f32_e32 v10, v46, v10
	v_mul_f32_e32 v10, 0x3fb8aa3b, v10
	v_exp_f32_e32 v42, v10
	v_add_f32_e32 v10, v11, v50
	v_mul_f32_e32 v10, 0xbfb8aa3b, v10
	v_exp_f32_e32 v10, v10
	v_fma_f32 v11, -v42, v42, 1.0
	v_max_f32_e32 v11, 0, v11
	v_add_f32_e32 v10, 1.0, v10
	v_rcp_f32_e32 v58, v10
	v_exp_f32_e32 v6, v6
	v_add_f32_e32 v2, v2, v51
	v_mul_f32_e32 v2, 0xbfb8aa3b, v2
	v_add_f32_e32 v6, 1.0, v6
	v_rcp_f32_e32 v6, v6
	v_exp_f32_e32 v2, v2
	v_add_f32_e32 v14, v16, v48
	v_mul_f32_e32 v14, 0xbfb8aa3b, v14
	v_exp_f32_e32 v16, v14
	v_mul_f32_e32 v6, 0xc1000000, v6
	v_mul_f32_e32 v6, v47, v6
	v_sqrt_f32_e32 v14, v11
	s_nop 0
	v_pk_mul_f32 v[10:11], v[58:59], v[14:15]
	v_add_f32_e32 v14, 1.0, v16
	v_rcp_f32_e32 v16, v14
	s_waitcnt lgkmcnt(0)
	v_mov_b32_e32 v14, v60
	v_mov_b32_e32 v15, v52
	v_pk_mul_f32 v[14:15], v[14:15], v[10:11]
	v_mul_f32_e32 v10, 0xc1000000, v16
	v_mul_f32_e32 v10, v46, v10
	v_mul_f32_e32 v10, 0x3fb8aa3b, v10
	v_exp_f32_e32 v43, v10
	v_add_f32_e32 v10, v12, v50
	v_mul_f32_e32 v10, 0xbfb8aa3b, v10
	v_exp_f32_e32 v12, v10
	v_fma_f32 v10, -v43, v43, 1.0
	v_max_f32_e32 v10, 0, v10
	v_add_f32_e32 v12, 1.0, v12
	v_rcp_f32_e32 v12, v12
	v_mov_b32_e32 v16, v10
	v_mul_f32_e32 v6, 0x3fb8aa3b, v6
	v_exp_f32_e32 v48, v6
	v_add_f32_e32 v7, v7, v49
	v_fma_f32 v6, -v48, v48, 1.0
	v_max_f32_e32 v6, 0, v6
	v_mul_f32_e32 v7, 0xbfb8aa3b, v7
	v_add_f32_e32 v2, 1.0, v2
	v_exp_f32_e32 v7, v7
	v_sqrt_f32_e32 v16, v16
	s_nop 0
	v_mul_f32_e32 v16, v12, v16
	v_mul_f32_e32 v12, 0xc1000000, v17
	v_mul_f32_e32 v12, v46, v12
	v_mul_f32_e32 v12, 0x3fb8aa3b, v12
	v_exp_f32_e32 v45, v12
	v_add_f32_e32 v12, v13, v50
	v_mul_f32_e32 v12, 0xbfb8aa3b, v12
	v_exp_f32_e32 v17, v12
	v_fma_f32 v12, -v45, v45, 1.0
	v_max_f32_e32 v12, 0, v12
	v_add_f32_e32 v17, 1.0, v17
	v_rcp_f32_e32 v17, v17
	v_mov_b32_e32 v25, v12
	v_rcp_f32_e32 v59, v2
	v_add_f32_e32 v7, 1.0, v7
	v_rcp_f32_e32 v7, v7
	v_add_f32_e32 v3, v3, v51
	v_mul_f32_e32 v3, 0xbfb8aa3b, v3
	v_add_f32_e32 v8, v8, v49
	v_mul_f32_e32 v8, 0xbfb8aa3b, v8
	v_exp_f32_e32 v8, v8
	v_sqrt_f32_e32 v25, v25
	s_nop 0
	v_mul_f32_e32 v46, v17, v25
	v_add_f32_e32 v9, v9, v49
	v_mul_f32_e32 v9, 0xbfb8aa3b, v9
	v_exp_f32_e32 v9, v9
	v_add_f32_e32 v4, v4, v51
	v_add_f32_e32 v9, 1.0, v9
	v_rcp_f32_e32 v9, v9
	v_mul_f32_e32 v4, 0xbfb8aa3b, v4
	v_exp_f32_e32 v4, v4
	v_sqrt_f32_e32 v2, v6
	s_nop 0
	v_mul_f32_e32 v6, 0xc1000000, v7
	v_mul_f32_e32 v6, v47, v6
	v_mul_f32_e32 v6, 0x3fb8aa3b, v6
	v_exp_f32_e32 v60, v6
	v_exp_f32_e32 v6, v3
	v_add_f32_e32 v4, 1.0, v4
	v_rcp_f32_e32 v4, v4
	v_fma_f32 v3, -v60, v60, 1.0
	v_max_f32_e32 v3, 0, v3
	ds_read2_b32 v[18:19], v241 offset0:136 offset1:152
	v_add_f32_e32 v5, v5, v51
	v_mov_b32_e32 v7, v3
	v_cndmask_b32_e64 v3, v2, 1.0, vcc
	v_add_f32_e32 v2, 1.0, v6
	v_rcp_f32_e32 v58, v2
	ds_read2_b32 v[26:27], v241 offset0:204 offset1:220
	v_mul_f32_e32 v5, 0xbfb8aa3b, v5
	v_exp_f32_e32 v5, v5
	v_add_f32_e32 v6, 1.0, v8
	v_rcp_f32_e32 v6, v6
	v_fma_f32 v29, v30, v21, v20
	v_add_f32_e32 v5, 1.0, v5
	v_mul_f32_e32 v6, 0xc1000000, v6
	v_mul_f32_e32 v6, v47, v6
	v_mul_f32_e32 v6, 0x3fb8aa3b, v6
	v_sqrt_f32_e32 v2, v7
	s_nop 0
	v_exp_f32_e32 v7, v6
	s_waitcnt lgkmcnt(0)
	v_mov_b32_e32 v32, v26
	v_rcp_f32_e32 v5, v5
	ds_read2_b32 v[10:11], v241 offset0:168 offset1:184
	v_fma_f32 v6, -v7, v7, 1.0
	v_max_f32_e32 v6, 0, v6
	ds_read2_b32 v[12:13], v241 offset0:236 offset1:252
	v_mov_b32_e32 v36, v27
	v_or_b32_e32 v0, 0xc0, v134
	v_pk_mul_f32 v[2:3], v[58:59], v[2:3]
	v_mov_b32_e32 v52, v61
	v_pk_mul_f32 v[2:3], v[52:53], v[2:3]
	s_nop 1
	s_nop 1
	v_sqrt_f32_e32 v6, v6
	s_nop 0
	v_mul_f32_e32 v8, 0xc1000000, v9
	v_mul_f32_e32 v8, v47, v8
	v_mul_f32_e32 v8, 0x3fb8aa3b, v8
	v_exp_f32_e32 v9, v8
	v_mul_f32_e32 v4, v4, v6
	v_fma_f32 v8, -v9, v9, 1.0
	v_max_f32_e32 v8, 0, v8
	s_nop 1
	s_nop 0
	s_nop 0
	s_nop 1
	v_mul_f32_e32 v17, v30, v44
	v_mov_b32_e32 v30, v18
	v_sqrt_f32_e32 v8, v8
	s_nop 0
	v_mul_f32_e32 v6, v31, v29
	v_pk_fma_f32 v[50:51], v[30:31], v[28:29], v[6:7] op_sel_hi:[1,1,0]
	v_mul_f32_e32 v6, v31, v17
	v_mov_b32_e32 v39, v50
	v_pk_mul_f32 v[30:31], v[32:33], v[38:39]
	v_mul_f32_e32 v20, v33, v6
	v_add_f32_e32 v47, v30, v31
	ds_bpermute_b32 v25, v134, v20
	ds_bpermute_b32 v26, v134, v47
	v_mul_f32_e32 v18, v5, v8
	v_or_b32_e32 v32, s18, v229
	ds_bpermute_b32 v5, v55, v20
	ds_bpermute_b32 v8, v55, v47
	v_ashrrev_i32_e32 v33, 31, v32
	v_lshlrev_b64 v[30:31], 10, v[32:33]
	ds_bpermute_b32 v28, v54, v20
	ds_bpermute_b32 v33, v54, v47
	s_waitcnt lgkmcnt(4)
; __device__ __forceinline__ unsigned cvt_pk_bf16(float lo, float hi) { unsigned r; asm volatile("v_cvt_pk_bf16_f32 %0, %1, %2" : "=v"(r) : "v"(lo), "v"(hi)); return r; }
; template <int NT> ...
;     ...
;     for (int u = 0; u < NT; ++u) {
; #pragma unroll
;         for (int n = 0; n < 4; ++n) { const int ch = hc0 + 16 * n + fr;
;             float hl[4], pl[4];
;             hl[0] = bv[u][n][0]; pl[0] = av[u][n][0];
; #pragma unroll
;             for (int j = 1; j < 4; ++j) { hl[j] = av[u][n][j] * hl[j - 1] + bv[u][n][j]; pl[j] = av[u][n][j] * pl[j - 1]; }
;             float He = 0.f, Pe = 1.f;
; #pragma unroll
;             for (int g = 0; g < 3; ++g) { const float Pg = __shfl(pl[3], fr + 16 * g), Hg = __shfl(hl[3], fr + 16 * g); if (g < fq) { He = Pg * He + Hg; Pe = Pg * Pe; } }
;             const float Hin = Pe * Hc[n] + He, Pin = Pe * Pc[n];
;             float hf[4], pf[4];
; #pragma unroll
;             for (int j = 0; j < 4; ++j) { hf[j] = hl[j] + pl[j] * Hin; pf[j] = pl[j] * Pin; }
; #pragma unroll
;             for (int j = 0; j < 4; ++j) { const size_t o = (size_t)(m0 + 16 * u + 4 * fq + j) * D + ch; HLOC[o] = (bf16_t)(cvt_pk_bf16(hf[j], 0.f) & 0xffffu); PCUM[o] = (bf16_t)(cvt_pk_bf16(pf[j], 0.f) & 0xffffu); }
;             Hc[n] = __shfl(hf[3], fr + 48); Pc[n] = __shfl(pf[3], fr + 48);
	v_fmac_f32_e32 v26, 0, v25
	v_cndmask_b32_e64 v26, v26, 0, s[8:9]
	v_cndmask_b32_e64 v25, v25, 1.0, s[8:9]
	s_waitcnt lgkmcnt(2)
	v_fmac_f32_e32 v8, v26, v5
	v_mul_f32_e32 v5, v25, v5
	v_cndmask_b32_e64 v8, v26, v8, s[4:5]
	v_cndmask_b32_e64 v5, v25, v5, s[4:5]
	s_waitcnt lgkmcnt(0)
	v_fmac_f32_e32 v33, v8, v28
	v_mul_f32_e32 v25, v5, v28
	v_cndmask_b32_e64 v8, v8, v33, s[6:7]
	v_cndmask_b32_e64 v5, v5, v25, s[6:7]
	v_fmac_f32_e32 v8, v5, v70
	v_mul_f32_e32 v5, v5, v72
	v_fmac_f32_e32 v21, v44, v8
	v_or_b32_e32 v38, v30, v208
	v_mov_b32_e32 v39, v31
	v_mul_f32_e32 v25, v44, v5
	v_fmac_f32_e32 v29, v17, v8
	v_mul_f32_e32 v17, v17, v5
	v_fmac_f32_e32 v50, v6, v8
	v_mul_f32_e32 v6, v6, v5
	v_fmac_f32_e32 v47, v20, v8
	v_mul_f32_e32 v5, v20, v5
	v_cvt_pk_bf16_f32 v8, v21, v1
	v_lshlrev_b64 v[20:21], 1, v[38:39]
	v_lshl_add_u64 v[20:21], v[20:21], 1, s[62:63]
	v_mov_b32_e32 v247, v8
	v_cvt_pk_bf16_f32 v246, v1, v25
	v_or_b32_e32 v8, v247, v246
	global_store_dword v[20:21], v8, off
	v_or_b32_e32 v20, 1, v32
	v_ashrrev_i32_e32 v21, 31, v20
	v_lshlrev_b64 v[20:21], 10, v[20:21]
	v_or_b32_e32 v38, v20, v208
	v_mov_b32_e32 v39, v21
	v_cvt_pk_bf16_f32 v8, v29, v1
	v_lshlrev_b64 v[28:29], 1, v[38:39]
	v_lshl_add_u64 v[28:29], v[28:29], 1, s[62:63]
	v_mov_b32_e32 v247, v8
	v_cvt_pk_bf16_f32 v246, v1, v17
	v_or_b32_e32 v8, v247, v246
	global_store_dword v[28:29], v8, off
	v_or_b32_e32 v28, 2, v32
	v_ashrrev_i32_e32 v29, 31, v28
	v_lshlrev_b64 v[28:29], 10, v[28:29]
	v_or_b32_e32 v38, v28, v208
	v_mov_b32_e32 v39, v29
	v_or_b32_e32 v32, 3, v32
	v_lshlrev_b64 v[38:39], 1, v[38:39]
	v_ashrrev_i32_e32 v33, 31, v32
	v_cvt_pk_bf16_f32 v8, v50, v1
	v_lshl_add_u64 v[38:39], v[38:39], 1, s[62:63]
	v_lshlrev_b64 v[32:33], 10, v[32:33]
	v_mov_b32_e32 v247, v8
	v_cvt_pk_bf16_f32 v246, v1, v6
	v_or_b32_e32 v6, v247, v246
	global_store_dword v[38:39], v6, off
	v_or_b32_e32 v38, v32, v208
	v_mov_b32_e32 v39, v33
	v_lshlrev_b64 v[38:39], 1, v[38:39]
	v_cvt_pk_bf16_f32 v6, v47, v1
	v_fma_f32 v25, v34, v23, v22
	v_mov_b32_e32 v247, v6
	v_mul_f32_e32 v17, v34, v56
	v_mov_b32_e32 v34, v19
	v_mul_f32_e32 v6, v35, v25
	v_pk_fma_f32 v[50:51], v[34:35], v[24:25], v[6:7] op_sel_hi:[1,1,0]
	v_mul_f32_e32 v6, v35, v17
	v_mov_b32_e32 v41, v50
	v_pk_mul_f32 v[26:27], v[36:37], v[40:41]
	v_mul_f32_e32 v22, v37, v6
	v_add_f32_e32 v19, v26, v27
	ds_bpermute_b32 v24, v134, v22
	ds_bpermute_b32 v34, v134, v19
	v_cvt_pk_bf16_f32 v246, v1, v5
	v_or_b32_e32 v8, v247, v246
	v_lshl_add_u64 v[26:27], v[38:39], 1, s[62:63]
	global_store_dword v[26:27], v8, off
	ds_bpermute_b32 v72, v0, v5
	ds_bpermute_b32 v5, v55, v22
	ds_bpermute_b32 v8, v55, v19
	s_waitcnt lgkmcnt(3)
	v_fmac_f32_e32 v34, 0, v24
	v_cndmask_b32_e64 v26, v34, 0, s[8:9]
	ds_bpermute_b32 v27, v54, v22
	ds_bpermute_b32 v34, v54, v19
	v_cndmask_b32_e64 v24, v24, 1.0, s[8:9]
	s_waitcnt lgkmcnt(2)
	v_fmac_f32_e32 v8, v26, v5
	v_mul_f32_e32 v5, v24, v5
	v_cndmask_b32_e64 v8, v26, v8, s[4:5]
	v_cndmask_b32_e64 v5, v24, v5, s[4:5]
	s_waitcnt lgkmcnt(0)
	v_fmac_f32_e32 v34, v8, v27
	v_mul_f32_e32 v24, v5, v27
	v_cndmask_b32_e64 v8, v8, v34, s[6:7]
	v_cndmask_b32_e64 v5, v5, v24, s[6:7]
	v_fmac_f32_e32 v8, v5, v71
	v_mul_f32_e32 v5, v5, v73
	v_fmac_f32_e32 v23, v56, v8
	v_or_b32_e32 v26, v30, v214
	v_mov_b32_e32 v27, v31
	v_mul_f32_e32 v24, v56, v5
	v_fmac_f32_e32 v25, v17, v8
	v_mul_f32_e32 v17, v17, v5
	v_fmac_f32_e32 v50, v6, v8
	v_mul_f32_e32 v6, v6, v5
	v_fmac_f32_e32 v19, v22, v8
	v_mul_f32_e32 v5, v22, v5
	v_cvt_pk_bf16_f32 v8, v23, v1
	v_lshlrev_b64 v[22:23], 1, v[26:27]
	v_lshl_add_u64 v[22:23], v[22:23], 1, s[62:63]
	v_mov_b32_e32 v247, v8
	v_cvt_pk_bf16_f32 v246, v1, v24
	v_or_b32_e32 v8, v247, v246
	global_store_dword v[22:23], v8, off
	v_or_b32_e32 v22, v20, v214
	v_mov_b32_e32 v23, v21
	v_lshlrev_b64 v[22:23], 1, v[22:23]
	v_cvt_pk_bf16_f32 v8, v25, v1
	v_lshl_add_u64 v[22:23], v[22:23], 1, s[62:63]
	v_mov_b32_e32 v247, v8
	v_cvt_pk_bf16_f32 v246, v1, v17
	v_or_b32_e32 v8, v247, v246
	global_store_dword v[22:23], v8, off
	v_or_b32_e32 v22, v28, v214
	v_mov_b32_e32 v23, v29
	v_lshlrev_b64 v[22:23], 1, v[22:23]
	v_lshl_add_u64 v[22:23], v[22:23], 1, s[62:63]
	v_cvt_pk_bf16_f32 v8, v50, v1
	v_mov_b32_e32 v247, v8
	v_cvt_pk_bf16_f32 v246, v1, v6
	v_or_b32_e32 v6, v247, v246
	global_store_dword v[22:23], v6, off
	v_or_b32_e32 v22, v32, v214
	v_mov_b32_e32 v23, v33
	v_lshlrev_b64 v[22:23], 1, v[22:23]
	v_cvt_pk_bf16_f32 v6, v19, v1
	v_fma_f32 v17, v42, v15, v14
	v_mov_b32_e32 v247, v6
	v_mul_f32_e32 v14, v42, v57
	v_mov_b32_e32 v42, v10
	v_mul_f32_e32 v6, v43, v17
	v_pk_fma_f32 v[24:25], v[42:43], v[16:17], v[6:7] op_sel_hi:[1,1,0]
	ds_bpermute_b32 v70, v0, v47
	v_mov_b32_e32 v44, v12
	v_mov_b32_e32 v47, v24
	v_mul_f32_e32 v6, v43, v14
	v_pk_mul_f32 v[26:27], v[44:45], v[46:47]
	v_mul_f32_e32 v10, v45, v6
	v_add_f32_e32 v12, v26, v27
	ds_bpermute_b32 v16, v134, v10
	ds_bpermute_b32 v25, v134, v12
	v_cvt_pk_bf16_f32 v246, v1, v5
	v_or_b32_e32 v8, v247, v246
	v_lshl_add_u64 v[22:23], v[22:23], 1, s[62:63]
	global_store_dword v[22:23], v8, off
	ds_bpermute_b32 v73, v0, v5
	ds_bpermute_b32 v5, v55, v10
	ds_bpermute_b32 v8, v55, v12
	ds_bpermute_b32 v22, v54, v10
	ds_bpermute_b32 v23, v54, v12
	s_waitcnt lgkmcnt(5)
; __device__ __forceinline__ unsigned cvt_pk_bf16(float lo, float hi) { unsigned r; asm volatile("v_cvt_pk_bf16_f32 %0, %1, %2" : "=v"(r) : "v"(lo), "v"(hi)); return r; }
; template <int NT> ...
;     ...
;     for (int u = 0; u < NT; ++u) {
; #pragma unroll
;         for (int n = 0; n < 4; ++n) { const int ch = hc0 + 16 * n + fr;
;             float hl[4], pl[4];
;             hl[0] = bv[u][n][0]; pl[0] = av[u][n][0];
; #pragma unroll
;             for (int j = 1; j < 4; ++j) { hl[j] = av[u][n][j] * hl[j - 1] + bv[u][n][j]; pl[j] = av[u][n][j] * pl[j - 1]; }
;             float He = 0.f, Pe = 1.f;
; #pragma unroll
;             for (int g = 0; g < 3; ++g) { const float Pg = __shfl(pl[3], fr + 16 * g), Hg = __shfl(hl[3], fr + 16 * g); if (g < fq) { He = Pg * He + Hg; Pe = Pg * Pe; } }
;             const float Hin = Pe * Hc[n] + He, Pin = Pe * Pc[n];
;             float hf[4], pf[4];
; #pragma unroll
;             for (int j = 0; j < 4; ++j) { hf[j] = hl[j] + pl[j] * Hin; pf[j] = pl[j] * Pin; }
; #pragma unroll
;             for (int j = 0; j < 4; ++j) { const size_t o = (size_t)(m0 + 16 * u + 4 * fq + j) * D + ch; HLOC[o] = (bf16_t)(cvt_pk_bf16(hf[j], 0.f) & 0xffffu); PCUM[o] = (bf16_t)(cvt_pk_bf16(pf[j], 0.f) & 0xffffu); }
;             Hc[n] = __shfl(hf[3], fr + 48); Pc[n] = __shfl(pf[3], fr + 48);
	v_fmac_f32_e32 v25, 0, v16
	ds_bpermute_b32 v71, v0, v19
	v_cndmask_b32_e64 v19, v25, 0, s[8:9]
	v_cndmask_b32_e64 v16, v16, 1.0, s[8:9]
	s_waitcnt lgkmcnt(3)
	v_fmac_f32_e32 v8, v19, v5
	v_mul_f32_e32 v5, v16, v5
	v_cndmask_b32_e64 v8, v19, v8, s[4:5]
	v_cndmask_b32_e64 v5, v16, v5, s[4:5]
	s_waitcnt lgkmcnt(1)
	v_fmac_f32_e32 v23, v8, v22
	v_mul_f32_e32 v16, v5, v22
	v_cndmask_b32_e64 v8, v8, v23, s[6:7]
	v_cndmask_b32_e64 v5, v5, v16, s[6:7]
	v_fmac_f32_e32 v8, v5, v66
	v_mul_f32_e32 v5, v5, v68
	v_fmac_f32_e32 v15, v57, v8
	v_or_b32_e32 v22, v30, v212
	v_mov_b32_e32 v23, v31
	v_mul_f32_e32 v16, v57, v5
	v_fmac_f32_e32 v17, v14, v8
	v_mul_f32_e32 v19, v14, v5
	v_fmac_f32_e32 v24, v6, v8
	v_mul_f32_e32 v6, v6, v5
	v_mul_f32_e32 v25, v10, v5
	v_cvt_pk_bf16_f32 v5, v15, v1
	v_lshlrev_b64 v[14:15], 1, v[22:23]
	v_lshl_add_u64 v[14:15], v[14:15], 1, s[62:63]
	v_mov_b32_e32 v247, v5
	v_cvt_pk_bf16_f32 v246, v1, v16
	v_or_b32_e32 v5, v247, v246
	global_store_dword v[14:15], v5, off
	v_or_b32_e32 v14, v20, v212
	v_mov_b32_e32 v15, v21
	v_lshlrev_b64 v[14:15], 1, v[14:15]
	v_cvt_pk_bf16_f32 v5, v17, v1
	v_lshl_add_u64 v[14:15], v[14:15], 1, s[62:63]
	v_mov_b32_e32 v247, v5
	v_cvt_pk_bf16_f32 v246, v1, v19
	v_or_b32_e32 v5, v247, v246
	global_store_dword v[14:15], v5, off
	v_or_b32_e32 v14, v28, v212
	v_mov_b32_e32 v15, v29
	v_lshlrev_b64 v[14:15], 1, v[14:15]
	v_cvt_pk_bf16_f32 v5, v24, v1
	v_lshl_add_u64 v[14:15], v[14:15], 1, s[62:63]
	v_mov_b32_e32 v247, v5
	v_cvt_pk_bf16_f32 v246, v1, v6
	v_or_b32_e32 v5, v247, v246
	global_store_dword v[14:15], v5, off
	v_or_b32_e32 v14, v32, v212
	v_mov_b32_e32 v15, v33
	v_lshlrev_b64 v[14:15], 1, v[14:15]
	v_fmac_f32_e32 v12, v10, v8
	v_cvt_pk_bf16_f32 v5, v12, v1
	v_mov_b32_e32 v247, v5
	v_fma_f32 v5, v60, v3, v2
	v_mov_b32_e32 v6, v11
	v_mul_f32_e32 v2, v7, v5
	v_pk_fma_f32 v[10:11], v[6:7], v[4:5], v[2:3] op_sel_hi:[1,1,0]
	v_mul_f32_e32 v17, v60, v48
	v_mov_b32_e32 v8, v13
	v_mov_b32_e32 v19, v10
	v_mul_f32_e32 v2, v7, v17
	v_pk_mul_f32 v[6:7], v[8:9], v[18:19]
	v_mul_f32_e32 v4, v9, v2
	v_add_f32_e32 v8, v6, v7
	ds_bpermute_b32 v9, v134, v4
	ds_bpermute_b32 v11, v134, v8
	v_lshl_add_u64 v[6:7], v[14:15], 1, s[62:63]
	v_cvt_pk_bf16_f32 v246, v1, v25
	v_or_b32_e32 v16, v247, v246
	global_store_dword v[6:7], v16, off
	ds_bpermute_b32 v6, v55, v4
	ds_bpermute_b32 v7, v55, v8
	ds_bpermute_b32 v66, v0, v12
	ds_bpermute_b32 v12, v54, v4
	ds_bpermute_b32 v13, v54, v8
	s_waitcnt lgkmcnt(5)
	v_fmac_f32_e32 v11, 0, v9
	v_cndmask_b32_e64 v11, v11, 0, s[8:9]
	v_cndmask_b32_e64 v9, v9, 1.0, s[8:9]
	s_waitcnt lgkmcnt(3)
	v_fmac_f32_e32 v7, v11, v6
	v_mul_f32_e32 v6, v9, v6
	v_cndmask_b32_e64 v7, v11, v7, s[4:5]
	v_cndmask_b32_e64 v6, v9, v6, s[4:5]
	s_waitcnt lgkmcnt(0)
	v_fmac_f32_e32 v13, v7, v12
	v_mul_f32_e32 v9, v6, v12
	v_cndmask_b32_e64 v7, v7, v13, s[6:7]
	v_cndmask_b32_e64 v6, v6, v9, s[6:7]
	v_fmac_f32_e32 v7, v6, v67
	v_mul_f32_e32 v6, v6, v69
	v_fmac_f32_e32 v3, v48, v7
	v_or_b32_e32 v30, v30, v210
	v_fmac_f32_e32 v10, v2, v7
	v_mul_f32_e32 v12, v2, v6
	v_fmac_f32_e32 v8, v4, v7
	v_mul_f32_e32 v13, v4, v6
	v_cvt_pk_bf16_f32 v4, v3, v1
	v_lshlrev_b64 v[2:3], 1, v[30:31]
	v_mul_f32_e32 v9, v48, v6
	v_fmac_f32_e32 v5, v17, v7
	v_mul_f32_e32 v11, v17, v6
	v_lshl_add_u64 v[2:3], v[2:3], 1, s[62:63]
	v_or_b32_e32 v20, v20, v210
	v_mov_b32_e32 v247, v4
	v_cvt_pk_bf16_f32 v246, v1, v9
	v_or_b32_e32 v4, v247, v246
	global_store_dword v[2:3], v4, off
	v_lshlrev_b64 v[2:3], 1, v[20:21]
	ds_bpermute_b32 v68, v0, v25
	v_cvt_pk_bf16_f32 v6, v5, v1
	v_lshl_add_u64 v[2:3], v[2:3], 1, s[62:63]
	v_or_b32_e32 v28, v28, v210
	ds_bpermute_b32 v67, v0, v8
	ds_bpermute_b32 v69, v0, v13
	v_mov_b32_e32 v247, v6
	v_cvt_pk_bf16_f32 v246, v1, v11
	v_or_b32_e32 v4, v247, v246
	global_store_dword v[2:3], v4, off
	v_lshlrev_b64 v[2:3], 1, v[28:29]
	v_lshl_add_u64 v[2:3], v[2:3], 1, s[62:63]
	v_or_b32_e32 v32, v32, v210
	v_cvt_pk_bf16_f32 v6, v10, v1
	v_mov_b32_e32 v247, v6
	v_cvt_pk_bf16_f32 v246, v1, v12
	v_or_b32_e32 v4, v247, v246
	global_store_dword v[2:3], v4, off
	v_lshlrev_b64 v[2:3], 1, v[32:33]
	v_lshl_add_u64 v[2:3], v[2:3], 1, s[62:63]
	v_cvt_pk_bf16_f32 v6, v8, v1
	v_mov_b32_e32 v247, v6
	v_cvt_pk_bf16_f32 v246, v1, v13
	v_or_b32_e32 v0, v247, v246
	global_store_dword v[2:3], v0, off

; __device__ __forceinline__ u32x4 pack8(const float (&f)[8]) { u32x4 o; o.x = cvt_pk_bf16(f[0], f[1]); o.y = cvt_pk_bf16(f[2], f[3]); o.z = cvt_pk_bf16(f[4], f[5]); o.w = cvt_pk_bf16(f[6], f[7]); return o; }
; __device__ __forceinline__ float gelu_tanh(float x) { return x * sigmoidf_(1.5957691216057308f * (x + 0.044715f * x * x * x)); }
; __device__ __forceinline__ void fixup_phase(KP p, int l) {
;     ...
; #pragma unroll 4
;         for (int i = 0; i < 16; ++i) {
;             const size_t m = (size_t)(m0 + i);
;             float hl[8], pc[8], gr[8], o[8], h[8];
;             unpack8(__builtin_nontemporal_load((const u32x4*)(HLOC + m * D + c0)), hl); unpack8(__builtin_nontemporal_load((const u32x4*)(PCUM + m * D + c0)), pc);
;             bf16_t* gp = P + m * DP + C_GR + c0; unpack8(*(const u32x4*)gp, gr);
; #pragma unroll
;             for (int e = 0; e < 8; ++e) { h[e] = hl[e] + pc[e] * carry[e]; o[e] = gelu_tanh(gr[e]) * h[e]; }
;             *(u32x4*)gp = pack8(o);
.Lfx_nocarry:
	s_lshl_b32 s44, s48, 12
	s_add_u32 s12, s34, 0x14a48000
	s_addc_u32 s13, s35, 0
	s_add_u32 s12, s12, s44
	s_addc_u32 s13, s13, 0
	s_add_u32 s14, s12, 0x2080000
	s_addc_u32 s15, s13, 0
	s_mul_i32 s44, s48, 0x2800
	s_add_u32 s96, s34, 0x66c9800
	s_addc_u32 s97, s35, 0
	s_add_u32 s96, s96, s44
	s_addc_u32 s97, s97, 0
	s_mov_b32 s24, s96
	s_mov_b32 s25, s97
	global_load_dwordx4 v[32:35], v31, s[12:13] nt
	global_load_dwordx4 v[36:39], v31, s[12:13] offset:16 nt
	global_load_dwordx4 v[40:43], v26, s[96:97] nt
	s_add_u32 s12, s12, 0x1000
	s_addc_u32 s13, s13, 0
	s_add_u32 s96, s96, 0x2800
	s_addc_u32 s97, s97, 0
	global_load_dwordx4 v[44:47], v31, s[12:13] nt
	global_load_dwordx4 v[48:51], v31, s[12:13] offset:16 nt
	global_load_dwordx4 v[52:55], v26, s[96:97] nt
	s_add_u32 s12, s12, 0x1000
	s_addc_u32 s13, s13, 0
	s_add_u32 s96, s96, 0x2800
	s_addc_u32 s97, s97, 0
	global_load_dwordx4 v[56:59], v31, s[12:13] nt
	global_load_dwordx4 v[60:63], v31, s[12:13] offset:16 nt
	global_load_dwordx4 v[64:67], v26, s[96:97] nt
	s_add_u32 s12, s12, 0x1000
	s_addc_u32 s13, s13, 0
	s_add_u32 s96, s96, 0x2800
	s_addc_u32 s97, s97, 0
	global_load_dwordx4 v[68:71], v31, s[12:13] nt
	global_load_dwordx4 v[72:75], v31, s[12:13] offset:16 nt
	global_load_dwordx4 v[76:79], v26, s[96:97] nt
	s_add_u32 s12, s12, 0x1000
	s_addc_u32 s13, s13, 0
	s_add_u32 s96, s96, 0x2800
	s_addc_u32 s97, s97, 0
	s_waitcnt vmcnt(9)
	v_lshlrev_b32_e32 v80, 16, v32
	v_and_b32_e32 v96, 0xffff0000, v32
	v_lshlrev_b32_e32 v81, 16, v33
	v_and_b32_e32 v97, 0xffff0000, v33
	v_lshlrev_b32_e32 v82, 16, v34
	v_and_b32_e32 v98, 0xffff0000, v34
	v_lshlrev_b32_e32 v83, 16, v35
	v_and_b32_e32 v99, 0xffff0000, v35
	v_lshlrev_b32_e32 v84, 16, v36
	v_and_b32_e32 v100, 0xffff0000, v36
	v_lshlrev_b32_e32 v85, 16, v37
	v_and_b32_e32 v101, 0xffff0000, v37
	v_lshlrev_b32_e32 v86, 16, v38
	v_and_b32_e32 v102, 0xffff0000, v38
	v_lshlrev_b32_e32 v87, 16, v39
	v_and_b32_e32 v103, 0xffff0000, v39
	v_lshlrev_b32_e32 v88, 16, v40
	v_and_b32_e32 v89, 0xffff0000, v40
	v_lshlrev_b32_e32 v90, 16, v41
	v_and_b32_e32 v91, 0xffff0000, v41
	v_lshlrev_b32_e32 v92, 16, v42
	v_and_b32_e32 v93, 0xffff0000, v42
	v_lshlrev_b32_e32 v94, 16, v43
	v_and_b32_e32 v95, 0xffff0000, v43
	v_fmac_f32_e32 v80, v96, v18
	v_fmac_f32_e32 v81, v97, v19
	v_fmac_f32_e32 v82, v98, v20
	v_fmac_f32_e32 v83, v99, v21
	v_fmac_f32_e32 v84, v100, v22
	v_fmac_f32_e32 v85, v101, v23
	v_fmac_f32_e32 v86, v102, v24
	v_fmac_f32_e32 v87, v103, v25
	v_mul_f32_e32 v104, 0x3d372713, v88
	v_mul_f32_e32 v105, 0x3d372713, v89
	v_mul_f32_e32 v106, 0x3d372713, v90
	v_mul_f32_e32 v107, 0x3d372713, v91
	v_mul_f32_e32 v108, 0x3d372713, v92
	v_mul_f32_e32 v109, 0x3d372713, v93
	v_mul_f32_e32 v110, 0x3d372713, v94
	v_mul_f32_e32 v111, 0x3d372713, v95
	v_mul_f32_e32 v104, v104, v88
	v_mul_f32_e32 v105, v105, v89
	v_mul_f32_e32 v106, v106, v90
	v_mul_f32_e32 v107, v107, v91
	v_mul_f32_e32 v108, v108, v92
	v_mul_f32_e32 v109, v109, v93
	v_mul_f32_e32 v110, v110, v94
	v_mul_f32_e32 v111, v111, v95
	v_fma_f32 v104, v104, v88, v88
	v_fma_f32 v105, v105, v89, v89
	v_fma_f32 v106, v106, v90, v90
	v_fma_f32 v107, v107, v91, v91
	v_fma_f32 v108, v108, v92, v92
	v_fma_f32 v109, v109, v93, v93
	v_fma_f32 v110, v110, v94, v94
	v_fma_f32 v111, v111, v95, v95
	v_mul_f32_e32 v104, 0x3fcc422a, v104
	v_mul_f32_e32 v105, 0x3fcc422a, v105
	v_mul_f32_e32 v106, 0x3fcc422a, v106
	v_mul_f32_e32 v107, 0x3fcc422a, v107
	v_mul_f32_e32 v108, 0x3fcc422a, v108
	v_mul_f32_e32 v109, 0x3fcc422a, v109
	v_mul_f32_e32 v110, 0x3fcc422a, v110
	v_mul_f32_e32 v111, 0x3fcc422a, v111
	v_mul_f32_e32 v104, 0xbfb8aa3b, v104
	v_mul_f32_e32 v105, 0xbfb8aa3b, v105
	v_mul_f32_e32 v106, 0xbfb8aa3b, v106
	v_mul_f32_e32 v107, 0xbfb8aa3b, v107
	v_mul_f32_e32 v108, 0xbfb8aa3b, v108
	v_mul_f32_e32 v109, 0xbfb8aa3b, v109
	v_mul_f32_e32 v110, 0xbfb8aa3b, v110
	v_mul_f32_e32 v111, 0xbfb8aa3b, v111
	v_exp_f32_e32 v104, v104
	v_exp_f32_e32 v105, v105
	v_exp_f32_e32 v106, v106
	v_exp_f32_e32 v107, v107
	v_exp_f32_e32 v108, v108
	v_exp_f32_e32 v109, v109
	v_exp_f32_e32 v110, v110
	v_exp_f32_e32 v111, v111
	v_add_f32_e32 v104, 1.0, v104
	v_add_f32_e32 v105, 1.0, v105
	v_add_f32_e32 v106, 1.0, v106
	v_add_f32_e32 v107, 1.0, v107
	v_add_f32_e32 v108, 1.0, v108
	v_add_f32_e32 v109, 1.0, v109
	v_add_f32_e32 v110, 1.0, v110
	v_add_f32_e32 v111, 1.0, v111
	v_rcp_f32_e32 v104, v104
	v_rcp_f32_e32 v105, v105
	v_rcp_f32_e32 v106, v106
	v_rcp_f32_e32 v107, v107
	v_rcp_f32_e32 v108, v108
	v_rcp_f32_e32 v109, v109
	v_rcp_f32_e32 v110, v110
	v_rcp_f32_e32 v111, v111
	v_mul_f32_e32 v104, v104, v88
	v_mul_f32_e32 v105, v105, v89
	v_mul_f32_e32 v106, v106, v90
	v_mul_f32_e32 v107, v107, v91
	v_mul_f32_e32 v108, v108, v92
	v_mul_f32_e32 v109, v109, v93
	v_mul_f32_e32 v110, v110, v94
	v_mul_f32_e32 v111, v111, v95
	v_mul_f32_e32 v104, v80, v104
	v_mul_f32_e32 v105, v81, v105
	v_mul_f32_e32 v106, v82, v106
	v_mul_f32_e32 v107, v83, v107
	v_mul_f32_e32 v108, v84, v108
	v_mul_f32_e32 v109, v85, v109
	v_mul_f32_e32 v110, v86, v110
	v_mul_f32_e32 v111, v87, v111
	v_cvt_pk_bf16_f32 v112, v104, v105
	v_cvt_pk_bf16_f32 v113, v106, v107
	v_cvt_pk_bf16_f32 v114, v108, v109
	v_cvt_pk_bf16_f32 v115, v110, v111
	global_store_dwordx4 v27, v[112:115], s[24:25]
	s_add_u32 s24, s24, 0x2800
	s_addc_u32 s25, s25, 0
	global_load_dwordx4 v[32:35], v31, s[12:13] nt
	global_load_dwordx4 v[36:39], v31, s[12:13] offset:16 nt
	global_load_dwordx4 v[40:43], v26, s[96:97] nt
	s_add_u32 s12, s12, 0x1000
	s_addc_u32 s13, s13, 0
	s_add_u32 s96, s96, 0x2800
	s_addc_u32 s97, s97, 0
	s_waitcnt vmcnt(10)
; __device__ __forceinline__ u32x4 pack8(const float (&f)[8]) { u32x4 o; o.x = cvt_pk_bf16(f[0], f[1]); o.y = cvt_pk_bf16(f[2], f[3]); o.z = cvt_pk_bf16(f[4], f[5]); o.w = cvt_pk_bf16(f[6], f[7]); return o; }
; __device__ __forceinline__ float gelu_tanh(float x) { return x * sigmoidf_(1.5957691216057308f * (x + 0.044715f * x * x * x)); }
; __device__ __forceinline__ void fixup_phase(KP p, int l) {
;     ...
;         for (int i = 0; i < 16; ++i) {
;             const size_t m = (size_t)(m0 + i);
;             float hl[8], pc[8], gr[8], o[8], h[8];
;             unpack8(__builtin_nontemporal_load((const u32x4*)(HLOC + m * D + c0)), hl); unpack8(__builtin_nontemporal_load((const u32x4*)(PCUM + m * D + c0)), pc);
;             bf16_t* gp = P + m * DP + C_GR + c0; unpack8(*(const u32x4*)gp, gr);
; #pragma unroll
;             for (int e = 0; e < 8; ++e) { h[e] = hl[e] + pc[e] * carry[e]; o[e] = gelu_tanh(gr[e]) * h[e]; }
;             *(u32x4*)gp = pack8(o);
	v_lshlrev_b32_e32 v80, 16, v44
	v_and_b32_e32 v96, 0xffff0000, v44
	v_lshlrev_b32_e32 v81, 16, v45
	v_and_b32_e32 v97, 0xffff0000, v45
	v_lshlrev_b32_e32 v82, 16, v46
	v_and_b32_e32 v98, 0xffff0000, v46
	v_lshlrev_b32_e32 v83, 16, v47
	v_and_b32_e32 v99, 0xffff0000, v47
	v_lshlrev_b32_e32 v84, 16, v48
	v_and_b32_e32 v100, 0xffff0000, v48
	v_lshlrev_b32_e32 v85, 16, v49
	v_and_b32_e32 v101, 0xffff0000, v49
	v_lshlrev_b32_e32 v86, 16, v50
	v_and_b32_e32 v102, 0xffff0000, v50
	v_lshlrev_b32_e32 v87, 16, v51
	v_and_b32_e32 v103, 0xffff0000, v51
	v_lshlrev_b32_e32 v88, 16, v52
	v_and_b32_e32 v89, 0xffff0000, v52
	v_lshlrev_b32_e32 v90, 16, v53
	v_and_b32_e32 v91, 0xffff0000, v53
	v_lshlrev_b32_e32 v92, 16, v54
	v_and_b32_e32 v93, 0xffff0000, v54
	v_lshlrev_b32_e32 v94, 16, v55
	v_and_b32_e32 v95, 0xffff0000, v55
	v_fmac_f32_e32 v80, v96, v18
	v_fmac_f32_e32 v81, v97, v19
	v_fmac_f32_e32 v82, v98, v20
	v_fmac_f32_e32 v83, v99, v21
	v_fmac_f32_e32 v84, v100, v22
	v_fmac_f32_e32 v85, v101, v23
	v_fmac_f32_e32 v86, v102, v24
	v_fmac_f32_e32 v87, v103, v25
	v_mul_f32_e32 v104, 0x3d372713, v88
	v_mul_f32_e32 v105, 0x3d372713, v89
	v_mul_f32_e32 v106, 0x3d372713, v90
	v_mul_f32_e32 v107, 0x3d372713, v91
	v_mul_f32_e32 v108, 0x3d372713, v92
	v_mul_f32_e32 v109, 0x3d372713, v93
	v_mul_f32_e32 v110, 0x3d372713, v94
	v_mul_f32_e32 v111, 0x3d372713, v95
	v_mul_f32_e32 v104, v104, v88
	v_mul_f32_e32 v105, v105, v89
	v_mul_f32_e32 v106, v106, v90
	v_mul_f32_e32 v107, v107, v91
	v_mul_f32_e32 v108, v108, v92
	v_mul_f32_e32 v109, v109, v93
	v_mul_f32_e32 v110, v110, v94
	v_mul_f32_e32 v111, v111, v95
	v_fma_f32 v104, v104, v88, v88
	v_fma_f32 v105, v105, v89, v89
	v_fma_f32 v106, v106, v90, v90
	v_fma_f32 v107, v107, v91, v91
	v_fma_f32 v108, v108, v92, v92
	v_fma_f32 v109, v109, v93, v93
	v_fma_f32 v110, v110, v94, v94
	v_fma_f32 v111, v111, v95, v95
	v_mul_f32_e32 v104, 0x3fcc422a, v104
	v_mul_f32_e32 v105, 0x3fcc422a, v105
	v_mul_f32_e32 v106, 0x3fcc422a, v106
	v_mul_f32_e32 v107, 0x3fcc422a, v107
	v_mul_f32_e32 v108, 0x3fcc422a, v108
	v_mul_f32_e32 v109, 0x3fcc422a, v109
	v_mul_f32_e32 v110, 0x3fcc422a, v110
	v_mul_f32_e32 v111, 0x3fcc422a, v111
	v_mul_f32_e32 v104, 0xbfb8aa3b, v104
	v_mul_f32_e32 v105, 0xbfb8aa3b, v105
	v_mul_f32_e32 v106, 0xbfb8aa3b, v106
	v_mul_f32_e32 v107, 0xbfb8aa3b, v107
	v_mul_f32_e32 v108, 0xbfb8aa3b, v108
	v_mul_f32_e32 v109, 0xbfb8aa3b, v109
	v_mul_f32_e32 v110, 0xbfb8aa3b, v110
	v_mul_f32_e32 v111, 0xbfb8aa3b, v111
	v_exp_f32_e32 v104, v104
	v_exp_f32_e32 v105, v105
	v_exp_f32_e32 v106, v106
	v_exp_f32_e32 v107, v107
	v_exp_f32_e32 v108, v108
	v_exp_f32_e32 v109, v109
	v_exp_f32_e32 v110, v110
	v_exp_f32_e32 v111, v111
	v_add_f32_e32 v104, 1.0, v104
	v_add_f32_e32 v105, 1.0, v105
	v_add_f32_e32 v106, 1.0, v106
	v_add_f32_e32 v107, 1.0, v107
	v_add_f32_e32 v108, 1.0, v108
	v_add_f32_e32 v109, 1.0, v109
	v_add_f32_e32 v110, 1.0, v110
	v_add_f32_e32 v111, 1.0, v111
	v_rcp_f32_e32 v104, v104
	v_rcp_f32_e32 v105, v105
	v_rcp_f32_e32 v106, v106
	v_rcp_f32_e32 v107, v107
	v_rcp_f32_e32 v108, v108
	v_rcp_f32_e32 v109, v109
	v_rcp_f32_e32 v110, v110
	v_rcp_f32_e32 v111, v111
	v_mul_f32_e32 v104, v104, v88
	v_mul_f32_e32 v105, v105, v89
	v_mul_f32_e32 v106, v106, v90
	v_mul_f32_e32 v107, v107, v91
	v_mul_f32_e32 v108, v108, v92
	v_mul_f32_e32 v109, v109, v93
	v_mul_f32_e32 v110, v110, v94
	v_mul_f32_e32 v111, v111, v95
	v_mul_f32_e32 v104, v80, v104
	v_mul_f32_e32 v105, v81, v105
	v_mul_f32_e32 v106, v82, v106
	v_mul_f32_e32 v107, v83, v107
	v_mul_f32_e32 v108, v84, v108
	v_mul_f32_e32 v109, v85, v109
	v_mul_f32_e32 v110, v86, v110
	v_mul_f32_e32 v111, v87, v111
	v_cvt_pk_bf16_f32 v112, v104, v105
	v_cvt_pk_bf16_f32 v113, v106, v107
	v_cvt_pk_bf16_f32 v114, v108, v109
	v_cvt_pk_bf16_f32 v115, v110, v111
	global_store_dwordx4 v27, v[112:115], s[24:25]
	s_add_u32 s24, s24, 0x2800
	s_addc_u32 s25, s25, 0
	global_load_dwordx4 v[44:47], v31, s[12:13] nt
	global_load_dwordx4 v[48:51], v31, s[12:13] offset:16 nt
	global_load_dwordx4 v[52:55], v26, s[96:97] nt
	s_add_u32 s12, s12, 0x1000
	s_addc_u32 s13, s13, 0
	s_add_u32 s96, s96, 0x2800
	s_addc_u32 s97, s97, 0
	s_waitcnt vmcnt(11)
	v_lshlrev_b32_e32 v80, 16, v56
	v_and_b32_e32 v96, 0xffff0000, v56
	v_lshlrev_b32_e32 v81, 16, v57
	v_and_b32_e32 v97, 0xffff0000, v57
	v_lshlrev_b32_e32 v82, 16, v58
	v_and_b32_e32 v98, 0xffff0000, v58
	v_lshlrev_b32_e32 v83, 16, v59
	v_and_b32_e32 v99, 0xffff0000, v59
	v_lshlrev_b32_e32 v84, 16, v60
	v_and_b32_e32 v100, 0xffff0000, v60
	v_lshlrev_b32_e32 v85, 16, v61
	v_and_b32_e32 v101, 0xffff0000, v61
	v_lshlrev_b32_e32 v86, 16, v62
	v_and_b32_e32 v102, 0xffff0000, v62
	v_lshlrev_b32_e32 v87, 16, v63
	v_and_b32_e32 v103, 0xffff0000, v63
	v_lshlrev_b32_e32 v88, 16, v64
	v_and_b32_e32 v89, 0xffff0000, v64
	v_lshlrev_b32_e32 v90, 16, v65
	v_and_b32_e32 v91, 0xffff0000, v65
	v_lshlrev_b32_e32 v92, 16, v66
	v_and_b32_e32 v93, 0xffff0000, v66
	v_lshlrev_b32_e32 v94, 16, v67
	v_and_b32_e32 v95, 0xffff0000, v67
	v_fmac_f32_e32 v80, v96, v18
	v_fmac_f32_e32 v81, v97, v19
	v_fmac_f32_e32 v82, v98, v20
	v_fmac_f32_e32 v83, v99, v21
	v_fmac_f32_e32 v84, v100, v22
	v_fmac_f32_e32 v85, v101, v23
	v_fmac_f32_e32 v86, v102, v24
	v_fmac_f32_e32 v87, v103, v25
	v_mul_f32_e32 v104, 0x3d372713, v88
	v_mul_f32_e32 v105, 0x3d372713, v89
	v_mul_f32_e32 v106, 0x3d372713, v90
	v_mul_f32_e32 v107, 0x3d372713, v91
	v_mul_f32_e32 v108, 0x3d372713, v92
	v_mul_f32_e32 v109, 0x3d372713, v93
	v_mul_f32_e32 v110, 0x3d372713, v94
	v_mul_f32_e32 v111, 0x3d372713, v95
	v_mul_f32_e32 v104, v104, v88
	v_mul_f32_e32 v105, v105, v89
	v_mul_f32_e32 v106, v106, v90
	v_mul_f32_e32 v107, v107, v91
; __device__ __forceinline__ u32x4 pack8(const float (&f)[8]) { u32x4 o; o.x = cvt_pk_bf16(f[0], f[1]); o.y = cvt_pk_bf16(f[2], f[3]); o.z = cvt_pk_bf16(f[4], f[5]); o.w = cvt_pk_bf16(f[6], f[7]); return o; }
; __device__ __forceinline__ float gelu_tanh(float x) { return x * sigmoidf_(1.5957691216057308f * (x + 0.044715f * x * x * x)); }
; __device__ __forceinline__ void fixup_phase(KP p, int l) {
;     ...
;         for (int i = 0; i < 16; ++i) {
;             const size_t m = (size_t)(m0 + i);
;             float hl[8], pc[8], gr[8], o[8], h[8];
;             unpack8(__builtin_nontemporal_load((const u32x4*)(HLOC + m * D + c0)), hl); unpack8(__builtin_nontemporal_load((const u32x4*)(PCUM + m * D + c0)), pc);
;             bf16_t* gp = P + m * DP + C_GR + c0; unpack8(*(const u32x4*)gp, gr);
; #pragma unroll
;             for (int e = 0; e < 8; ++e) { h[e] = hl[e] + pc[e] * carry[e]; o[e] = gelu_tanh(gr[e]) * h[e]; }
;             *(u32x4*)gp = pack8(o);
	v_mul_f32_e32 v108, v108, v92
	v_mul_f32_e32 v109, v109, v93
	v_mul_f32_e32 v110, v110, v94
	v_mul_f32_e32 v111, v111, v95
	v_fma_f32 v104, v104, v88, v88
	v_fma_f32 v105, v105, v89, v89
	v_fma_f32 v106, v106, v90, v90
	v_fma_f32 v107, v107, v91, v91
	v_fma_f32 v108, v108, v92, v92
	v_fma_f32 v109, v109, v93, v93
	v_fma_f32 v110, v110, v94, v94
	v_fma_f32 v111, v111, v95, v95
	v_mul_f32_e32 v104, 0x3fcc422a, v104
	v_mul_f32_e32 v105, 0x3fcc422a, v105
	v_mul_f32_e32 v106, 0x3fcc422a, v106
	v_mul_f32_e32 v107, 0x3fcc422a, v107
	v_mul_f32_e32 v108, 0x3fcc422a, v108
	v_mul_f32_e32 v109, 0x3fcc422a, v109
	v_mul_f32_e32 v110, 0x3fcc422a, v110
	v_mul_f32_e32 v111, 0x3fcc422a, v111
	v_mul_f32_e32 v104, 0xbfb8aa3b, v104
	v_mul_f32_e32 v105, 0xbfb8aa3b, v105
	v_mul_f32_e32 v106, 0xbfb8aa3b, v106
	v_mul_f32_e32 v107, 0xbfb8aa3b, v107
	v_mul_f32_e32 v108, 0xbfb8aa3b, v108
	v_mul_f32_e32 v109, 0xbfb8aa3b, v109
	v_mul_f32_e32 v110, 0xbfb8aa3b, v110
	v_mul_f32_e32 v111, 0xbfb8aa3b, v111
	v_exp_f32_e32 v104, v104
	v_exp_f32_e32 v105, v105
	v_exp_f32_e32 v106, v106
	v_exp_f32_e32 v107, v107
	v_exp_f32_e32 v108, v108
	v_exp_f32_e32 v109, v109
	v_exp_f32_e32 v110, v110
	v_exp_f32_e32 v111, v111
	v_add_f32_e32 v104, 1.0, v104
	v_add_f32_e32 v105, 1.0, v105
	v_add_f32_e32 v106, 1.0, v106
	v_add_f32_e32 v107, 1.0, v107
	v_add_f32_e32 v108, 1.0, v108
	v_add_f32_e32 v109, 1.0, v109
	v_add_f32_e32 v110, 1.0, v110
	v_add_f32_e32 v111, 1.0, v111
	v_rcp_f32_e32 v104, v104
	v_rcp_f32_e32 v105, v105
	v_rcp_f32_e32 v106, v106
	v_rcp_f32_e32 v107, v107
	v_rcp_f32_e32 v108, v108
	v_rcp_f32_e32 v109, v109
	v_rcp_f32_e32 v110, v110
	v_rcp_f32_e32 v111, v111
	v_mul_f32_e32 v104, v104, v88
	v_mul_f32_e32 v105, v105, v89
	v_mul_f32_e32 v106, v106, v90
	v_mul_f32_e32 v107, v107, v91
	v_mul_f32_e32 v108, v108, v92
	v_mul_f32_e32 v109, v109, v93
	v_mul_f32_e32 v110, v110, v94
	v_mul_f32_e32 v111, v111, v95
	v_mul_f32_e32 v104, v80, v104
	v_mul_f32_e32 v105, v81, v105
	v_mul_f32_e32 v106, v82, v106
	v_mul_f32_e32 v107, v83, v107
	v_mul_f32_e32 v108, v84, v108
	v_mul_f32_e32 v109, v85, v109
	v_mul_f32_e32 v110, v86, v110
	v_mul_f32_e32 v111, v87, v111
	v_cvt_pk_bf16_f32 v112, v104, v105
	v_cvt_pk_bf16_f32 v113, v106, v107
	v_cvt_pk_bf16_f32 v114, v108, v109
	v_cvt_pk_bf16_f32 v115, v110, v111
	global_store_dwordx4 v27, v[112:115], s[24:25]
	s_add_u32 s24, s24, 0x2800
	s_addc_u32 s25, s25, 0
	global_load_dwordx4 v[56:59], v31, s[12:13] nt
	global_load_dwordx4 v[60:63], v31, s[12:13] offset:16 nt
	global_load_dwordx4 v[64:67], v26, s[96:97] nt
	s_add_u32 s12, s12, 0x1000
	s_addc_u32 s13, s13, 0
	s_add_u32 s96, s96, 0x2800
	s_addc_u32 s97, s97, 0
	s_waitcnt vmcnt(12)
	v_lshlrev_b32_e32 v80, 16, v68
	v_and_b32_e32 v96, 0xffff0000, v68
	v_lshlrev_b32_e32 v81, 16, v69
	v_and_b32_e32 v97, 0xffff0000, v69
	v_lshlrev_b32_e32 v82, 16, v70
	v_and_b32_e32 v98, 0xffff0000, v70
	v_lshlrev_b32_e32 v83, 16, v71
	v_and_b32_e32 v99, 0xffff0000, v71
	v_lshlrev_b32_e32 v84, 16, v72
	v_and_b32_e32 v100, 0xffff0000, v72
	v_lshlrev_b32_e32 v85, 16, v73
	v_and_b32_e32 v101, 0xffff0000, v73
	v_lshlrev_b32_e32 v86, 16, v74
	v_and_b32_e32 v102, 0xffff0000, v74
	v_lshlrev_b32_e32 v87, 16, v75
	v_and_b32_e32 v103, 0xffff0000, v75
	v_lshlrev_b32_e32 v88, 16, v76
	v_and_b32_e32 v89, 0xffff0000, v76
	v_lshlrev_b32_e32 v90, 16, v77
	v_and_b32_e32 v91, 0xffff0000, v77
	v_lshlrev_b32_e32 v92, 16, v78
	v_and_b32_e32 v93, 0xffff0000, v78
	v_lshlrev_b32_e32 v94, 16, v79
	v_and_b32_e32 v95, 0xffff0000, v79
	v_fmac_f32_e32 v80, v96, v18
	v_fmac_f32_e32 v81, v97, v19
	v_fmac_f32_e32 v82, v98, v20
	v_fmac_f32_e32 v83, v99, v21
	v_fmac_f32_e32 v84, v100, v22
	v_fmac_f32_e32 v85, v101, v23
	v_fmac_f32_e32 v86, v102, v24
	v_fmac_f32_e32 v87, v103, v25
	v_mul_f32_e32 v104, 0x3d372713, v88
	v_mul_f32_e32 v105, 0x3d372713, v89
	v_mul_f32_e32 v106, 0x3d372713, v90
	v_mul_f32_e32 v107, 0x3d372713, v91
	v_mul_f32_e32 v108, 0x3d372713, v92
	v_mul_f32_e32 v109, 0x3d372713, v93
	v_mul_f32_e32 v110, 0x3d372713, v94
	v_mul_f32_e32 v111, 0x3d372713, v95
	v_mul_f32_e32 v104, v104, v88
	v_mul_f32_e32 v105, v105, v89
	v_mul_f32_e32 v106, v106, v90
	v_mul_f32_e32 v107, v107, v91
	v_mul_f32_e32 v108, v108, v92
	v_mul_f32_e32 v109, v109, v93
	v_mul_f32_e32 v110, v110, v94
	v_mul_f32_e32 v111, v111, v95
	v_fma_f32 v104, v104, v88, v88
	v_fma_f32 v105, v105, v89, v89
	v_fma_f32 v106, v106, v90, v90
	v_fma_f32 v107, v107, v91, v91
	v_fma_f32 v108, v108, v92, v92
	v_fma_f32 v109, v109, v93, v93
	v_fma_f32 v110, v110, v94, v94
	v_fma_f32 v111, v111, v95, v95
	v_mul_f32_e32 v104, 0x3fcc422a, v104
	v_mul_f32_e32 v105, 0x3fcc422a, v105
	v_mul_f32_e32 v106, 0x3fcc422a, v106
	v_mul_f32_e32 v107, 0x3fcc422a, v107
	v_mul_f32_e32 v108, 0x3fcc422a, v108
	v_mul_f32_e32 v109, 0x3fcc422a, v109
	v_mul_f32_e32 v110, 0x3fcc422a, v110
	v_mul_f32_e32 v111, 0x3fcc422a, v111
	v_mul_f32_e32 v104, 0xbfb8aa3b, v104
	v_mul_f32_e32 v105, 0xbfb8aa3b, v105
	v_mul_f32_e32 v106, 0xbfb8aa3b, v106
	v_mul_f32_e32 v107, 0xbfb8aa3b, v107
	v_mul_f32_e32 v108, 0xbfb8aa3b, v108
	v_mul_f32_e32 v109, 0xbfb8aa3b, v109
	v_mul_f32_e32 v110, 0xbfb8aa3b, v110
	v_mul_f32_e32 v111, 0xbfb8aa3b, v111
	v_exp_f32_e32 v104, v104
	v_exp_f32_e32 v105, v105
	v_exp_f32_e32 v106, v106
	v_exp_f32_e32 v107, v107
	v_exp_f32_e32 v108, v108
	v_exp_f32_e32 v109, v109
	v_exp_f32_e32 v110, v110
	v_exp_f32_e32 v111, v111
	v_add_f32_e32 v104, 1.0, v104
	v_add_f32_e32 v105, 1.0, v105
	v_add_f32_e32 v106, 1.0, v106
	v_add_f32_e32 v107, 1.0, v107
	v_add_f32_e32 v108, 1.0, v108
	v_add_f32_e32 v109, 1.0, v109
	v_add_f32_e32 v110, 1.0, v110
	v_add_f32_e32 v111, 1.0, v111
	v_rcp_f32_e32 v104, v104
	v_rcp_f32_e32 v105, v105
	v_rcp_f32_e32 v106, v106
	v_rcp_f32_e32 v107, v107
	v_rcp_f32_e32 v108, v108
	v_rcp_f32_e32 v109, v109
	v_rcp_f32_e32 v110, v110
	v_rcp_f32_e32 v111, v111
	v_mul_f32_e32 v104, v104, v88
	v_mul_f32_e32 v105, v105, v89
	v_mul_f32_e32 v106, v106, v90
	v_mul_f32_e32 v107, v107, v91
	v_mul_f32_e32 v108, v108, v92
	v_mul_f32_e32 v109, v109, v93
	v_mul_f32_e32 v110, v110, v94
	v_mul_f32_e32 v111, v111, v95
	v_mul_f32_e32 v104, v80, v104
	v_mul_f32_e32 v105, v81, v105
	v_mul_f32_e32 v106, v82, v106
	v_mul_f32_e32 v107, v83, v107
	v_mul_f32_e32 v108, v84, v108
	v_mul_f32_e32 v109, v85, v109
	v_mul_f32_e32 v110, v86, v110
	v_mul_f32_e32 v111, v87, v111
	v_cvt_pk_bf16_f32 v112, v104, v105
	v_cvt_pk_bf16_f32 v113, v106, v107
	v_cvt_pk_bf16_f32 v114, v108, v109
	v_cvt_pk_bf16_f32 v115, v110, v111
	global_store_dwordx4 v27, v[112:115], s[24:25]
	s_add_u32 s24, s24, 0x2800
	s_addc_u32 s25, s25, 0
	global_load_dwordx4 v[68:71], v31, s[12:13] nt
	global_load_dwordx4 v[72:75], v31, s[12:13] offset:16 nt
	global_load_dwordx4 v[76:79], v26, s[96:97] nt
	s_add_u32 s12, s12, 0x1000
	s_addc_u32 s13, s13, 0
	s_add_u32 s96, s96, 0x2800
	s_addc_u32 s97, s97, 0
	s_waitcnt vmcnt(12)
; __device__ __forceinline__ u32x4 pack8(const float (&f)[8]) { u32x4 o; o.x = cvt_pk_bf16(f[0], f[1]); o.y = cvt_pk_bf16(f[2], f[3]); o.z = cvt_pk_bf16(f[4], f[5]); o.w = cvt_pk_bf16(f[6], f[7]); return o; }
; __device__ __forceinline__ float gelu_tanh(float x) { return x * sigmoidf_(1.5957691216057308f * (x + 0.044715f * x * x * x)); }
; __device__ __forceinline__ void fixup_phase(KP p, int l) {
;     ...
;         for (int i = 0; i < 16; ++i) {
;             const size_t m = (size_t)(m0 + i);
;             float hl[8], pc[8], gr[8], o[8], h[8];
;             unpack8(__builtin_nontemporal_load((const u32x4*)(HLOC + m * D + c0)), hl); unpack8(__builtin_nontemporal_load((const u32x4*)(PCUM + m * D + c0)), pc);
;             bf16_t* gp = P + m * DP + C_GR + c0; unpack8(*(const u32x4*)gp, gr);
; #pragma unroll
;             for (int e = 0; e < 8; ++e) { h[e] = hl[e] + pc[e] * carry[e]; o[e] = gelu_tanh(gr[e]) * h[e]; }
;             *(u32x4*)gp = pack8(o);
	v_lshlrev_b32_e32 v80, 16, v32
	v_and_b32_e32 v96, 0xffff0000, v32
	v_lshlrev_b32_e32 v81, 16, v33
	v_and_b32_e32 v97, 0xffff0000, v33
	v_lshlrev_b32_e32 v82, 16, v34
	v_and_b32_e32 v98, 0xffff0000, v34
	v_lshlrev_b32_e32 v83, 16, v35
	v_and_b32_e32 v99, 0xffff0000, v35
	v_lshlrev_b32_e32 v84, 16, v36
	v_and_b32_e32 v100, 0xffff0000, v36
	v_lshlrev_b32_e32 v85, 16, v37
	v_and_b32_e32 v101, 0xffff0000, v37
	v_lshlrev_b32_e32 v86, 16, v38
	v_and_b32_e32 v102, 0xffff0000, v38
	v_lshlrev_b32_e32 v87, 16, v39
	v_and_b32_e32 v103, 0xffff0000, v39
	v_lshlrev_b32_e32 v88, 16, v40
	v_and_b32_e32 v89, 0xffff0000, v40
	v_lshlrev_b32_e32 v90, 16, v41
	v_and_b32_e32 v91, 0xffff0000, v41
	v_lshlrev_b32_e32 v92, 16, v42
	v_and_b32_e32 v93, 0xffff0000, v42
	v_lshlrev_b32_e32 v94, 16, v43
	v_and_b32_e32 v95, 0xffff0000, v43
	v_fmac_f32_e32 v80, v96, v18
	v_fmac_f32_e32 v81, v97, v19
	v_fmac_f32_e32 v82, v98, v20
	v_fmac_f32_e32 v83, v99, v21
	v_fmac_f32_e32 v84, v100, v22
	v_fmac_f32_e32 v85, v101, v23
	v_fmac_f32_e32 v86, v102, v24
	v_fmac_f32_e32 v87, v103, v25
	v_mul_f32_e32 v104, 0x3d372713, v88
	v_mul_f32_e32 v105, 0x3d372713, v89
	v_mul_f32_e32 v106, 0x3d372713, v90
	v_mul_f32_e32 v107, 0x3d372713, v91
	v_mul_f32_e32 v108, 0x3d372713, v92
	v_mul_f32_e32 v109, 0x3d372713, v93
	v_mul_f32_e32 v110, 0x3d372713, v94
	v_mul_f32_e32 v111, 0x3d372713, v95
	v_mul_f32_e32 v104, v104, v88
	v_mul_f32_e32 v105, v105, v89
	v_mul_f32_e32 v106, v106, v90
	v_mul_f32_e32 v107, v107, v91
	v_mul_f32_e32 v108, v108, v92
	v_mul_f32_e32 v109, v109, v93
	v_mul_f32_e32 v110, v110, v94
	v_mul_f32_e32 v111, v111, v95
	v_fma_f32 v104, v104, v88, v88
	v_fma_f32 v105, v105, v89, v89
	v_fma_f32 v106, v106, v90, v90
	v_fma_f32 v107, v107, v91, v91
	v_fma_f32 v108, v108, v92, v92
	v_fma_f32 v109, v109, v93, v93
	v_fma_f32 v110, v110, v94, v94
	v_fma_f32 v111, v111, v95, v95
	v_mul_f32_e32 v104, 0x3fcc422a, v104
	v_mul_f32_e32 v105, 0x3fcc422a, v105
	v_mul_f32_e32 v106, 0x3fcc422a, v106
	v_mul_f32_e32 v107, 0x3fcc422a, v107
	v_mul_f32_e32 v108, 0x3fcc422a, v108
	v_mul_f32_e32 v109, 0x3fcc422a, v109
	v_mul_f32_e32 v110, 0x3fcc422a, v110
	v_mul_f32_e32 v111, 0x3fcc422a, v111
	v_mul_f32_e32 v104, 0xbfb8aa3b, v104
	v_mul_f32_e32 v105, 0xbfb8aa3b, v105
	v_mul_f32_e32 v106, 0xbfb8aa3b, v106
	v_mul_f32_e32 v107, 0xbfb8aa3b, v107
	v_mul_f32_e32 v108, 0xbfb8aa3b, v108
	v_mul_f32_e32 v109, 0xbfb8aa3b, v109
	v_mul_f32_e32 v110, 0xbfb8aa3b, v110
	v_mul_f32_e32 v111, 0xbfb8aa3b, v111
	v_exp_f32_e32 v104, v104
	v_exp_f32_e32 v105, v105
	v_exp_f32_e32 v106, v106
	v_exp_f32_e32 v107, v107
	v_exp_f32_e32 v108, v108
	v_exp_f32_e32 v109, v109
	v_exp_f32_e32 v110, v110
	v_exp_f32_e32 v111, v111
	v_add_f32_e32 v104, 1.0, v104
	v_add_f32_e32 v105, 1.0, v105
	v_add_f32_e32 v106, 1.0, v106
	v_add_f32_e32 v107, 1.0, v107
	v_add_f32_e32 v108, 1.0, v108
	v_add_f32_e32 v109, 1.0, v109
	v_add_f32_e32 v110, 1.0, v110
	v_add_f32_e32 v111, 1.0, v111
	v_rcp_f32_e32 v104, v104
	v_rcp_f32_e32 v105, v105
	v_rcp_f32_e32 v106, v106
	v_rcp_f32_e32 v107, v107
	v_rcp_f32_e32 v108, v108
	v_rcp_f32_e32 v109, v109
	v_rcp_f32_e32 v110, v110
	v_rcp_f32_e32 v111, v111
	v_mul_f32_e32 v104, v104, v88
	v_mul_f32_e32 v105, v105, v89
	v_mul_f32_e32 v106, v106, v90
	v_mul_f32_e32 v107, v107, v91
	v_mul_f32_e32 v108, v108, v92
	v_mul_f32_e32 v109, v109, v93
	v_mul_f32_e32 v110, v110, v94
	v_mul_f32_e32 v111, v111, v95
	v_mul_f32_e32 v104, v80, v104
	v_mul_f32_e32 v105, v81, v105
	v_mul_f32_e32 v106, v82, v106
	v_mul_f32_e32 v107, v83, v107
	v_mul_f32_e32 v108, v84, v108
	v_mul_f32_e32 v109, v85, v109
	v_mul_f32_e32 v110, v86, v110
	v_mul_f32_e32 v111, v87, v111
	v_cvt_pk_bf16_f32 v112, v104, v105
	v_cvt_pk_bf16_f32 v113, v106, v107
	v_cvt_pk_bf16_f32 v114, v108, v109
	v_cvt_pk_bf16_f32 v115, v110, v111
	global_store_dwordx4 v27, v[112:115], s[24:25]
	s_add_u32 s24, s24, 0x2800
	s_addc_u32 s25, s25, 0
	global_load_dwordx4 v[32:35], v31, s[12:13] nt
	global_load_dwordx4 v[36:39], v31, s[12:13] offset:16 nt
	global_load_dwordx4 v[40:43], v26, s[96:97] nt
	s_add_u32 s12, s12, 0x1000
	s_addc_u32 s13, s13, 0
	s_add_u32 s96, s96, 0x2800
	s_addc_u32 s97, s97, 0
	s_waitcnt vmcnt(12)
	v_lshlrev_b32_e32 v80, 16, v44
	v_and_b32_e32 v96, 0xffff0000, v44
	v_lshlrev_b32_e32 v81, 16, v45
	v_and_b32_e32 v97, 0xffff0000, v45
	v_lshlrev_b32_e32 v82, 16, v46
	v_and_b32_e32 v98, 0xffff0000, v46
	v_lshlrev_b32_e32 v83, 16, v47
	v_and_b32_e32 v99, 0xffff0000, v47
	v_lshlrev_b32_e32 v84, 16, v48
	v_and_b32_e32 v100, 0xffff0000, v48
	v_lshlrev_b32_e32 v85, 16, v49
	v_and_b32_e32 v101, 0xffff0000, v49
	v_lshlrev_b32_e32 v86, 16, v50
	v_and_b32_e32 v102, 0xffff0000, v50
	v_lshlrev_b32_e32 v87, 16, v51
	v_and_b32_e32 v103, 0xffff0000, v51
	v_lshlrev_b32_e32 v88, 16, v52
	v_and_b32_e32 v89, 0xffff0000, v52
	v_lshlrev_b32_e32 v90, 16, v53
	v_and_b32_e32 v91, 0xffff0000, v53
	v_lshlrev_b32_e32 v92, 16, v54
	v_and_b32_e32 v93, 0xffff0000, v54
	v_lshlrev_b32_e32 v94, 16, v55
	v_and_b32_e32 v95, 0xffff0000, v55
	v_fmac_f32_e32 v80, v96, v18
	v_fmac_f32_e32 v81, v97, v19
	v_fmac_f32_e32 v82, v98, v20
	v_fmac_f32_e32 v83, v99, v21
	v_fmac_f32_e32 v84, v100, v22
	v_fmac_f32_e32 v85, v101, v23
	v_fmac_f32_e32 v86, v102, v24
	v_fmac_f32_e32 v87, v103, v25
	v_mul_f32_e32 v104, 0x3d372713, v88
	v_mul_f32_e32 v105, 0x3d372713, v89
	v_mul_f32_e32 v106, 0x3d372713, v90
	v_mul_f32_e32 v107, 0x3d372713, v91
	v_mul_f32_e32 v108, 0x3d372713, v92
	v_mul_f32_e32 v109, 0x3d372713, v93
	v_mul_f32_e32 v110, 0x3d372713, v94
	v_mul_f32_e32 v111, 0x3d372713, v95
	v_mul_f32_e32 v104, v104, v88
	v_mul_f32_e32 v105, v105, v89
	v_mul_f32_e32 v106, v106, v90
	v_mul_f32_e32 v107, v107, v91
; __device__ __forceinline__ u32x4 pack8(const float (&f)[8]) { u32x4 o; o.x = cvt_pk_bf16(f[0], f[1]); o.y = cvt_pk_bf16(f[2], f[3]); o.z = cvt_pk_bf16(f[4], f[5]); o.w = cvt_pk_bf16(f[6], f[7]); return o; }
; __device__ __forceinline__ float gelu_tanh(float x) { return x * sigmoidf_(1.5957691216057308f * (x + 0.044715f * x * x * x)); }
; __device__ __forceinline__ void fixup_phase(KP p, int l) {
;     ...
;         for (int i = 0; i < 16; ++i) {
;             const size_t m = (size_t)(m0 + i);
;             float hl[8], pc[8], gr[8], o[8], h[8];
;             unpack8(__builtin_nontemporal_load((const u32x4*)(HLOC + m * D + c0)), hl); unpack8(__builtin_nontemporal_load((const u32x4*)(PCUM + m * D + c0)), pc);
;             bf16_t* gp = P + m * DP + C_GR + c0; unpack8(*(const u32x4*)gp, gr);
; #pragma unroll
;             for (int e = 0; e < 8; ++e) { h[e] = hl[e] + pc[e] * carry[e]; o[e] = gelu_tanh(gr[e]) * h[e]; }
;             *(u32x4*)gp = pack8(o);
	v_mul_f32_e32 v108, v108, v92
	v_mul_f32_e32 v109, v109, v93
	v_mul_f32_e32 v110, v110, v94
	v_mul_f32_e32 v111, v111, v95
	v_fma_f32 v104, v104, v88, v88
	v_fma_f32 v105, v105, v89, v89
	v_fma_f32 v106, v106, v90, v90
	v_fma_f32 v107, v107, v91, v91
	v_fma_f32 v108, v108, v92, v92
	v_fma_f32 v109, v109, v93, v93
	v_fma_f32 v110, v110, v94, v94
	v_fma_f32 v111, v111, v95, v95
	v_mul_f32_e32 v104, 0x3fcc422a, v104
	v_mul_f32_e32 v105, 0x3fcc422a, v105
	v_mul_f32_e32 v106, 0x3fcc422a, v106
	v_mul_f32_e32 v107, 0x3fcc422a, v107
	v_mul_f32_e32 v108, 0x3fcc422a, v108
	v_mul_f32_e32 v109, 0x3fcc422a, v109
	v_mul_f32_e32 v110, 0x3fcc422a, v110
	v_mul_f32_e32 v111, 0x3fcc422a, v111
	v_mul_f32_e32 v104, 0xbfb8aa3b, v104
	v_mul_f32_e32 v105, 0xbfb8aa3b, v105
	v_mul_f32_e32 v106, 0xbfb8aa3b, v106
	v_mul_f32_e32 v107, 0xbfb8aa3b, v107
	v_mul_f32_e32 v108, 0xbfb8aa3b, v108
	v_mul_f32_e32 v109, 0xbfb8aa3b, v109
	v_mul_f32_e32 v110, 0xbfb8aa3b, v110
	v_mul_f32_e32 v111, 0xbfb8aa3b, v111
	v_exp_f32_e32 v104, v104
	v_exp_f32_e32 v105, v105
	v_exp_f32_e32 v106, v106
	v_exp_f32_e32 v107, v107
	v_exp_f32_e32 v108, v108
	v_exp_f32_e32 v109, v109
	v_exp_f32_e32 v110, v110
	v_exp_f32_e32 v111, v111
	v_add_f32_e32 v104, 1.0, v104
	v_add_f32_e32 v105, 1.0, v105
	v_add_f32_e32 v106, 1.0, v106
	v_add_f32_e32 v107, 1.0, v107
	v_add_f32_e32 v108, 1.0, v108
	v_add_f32_e32 v109, 1.0, v109
	v_add_f32_e32 v110, 1.0, v110
	v_add_f32_e32 v111, 1.0, v111
	v_rcp_f32_e32 v104, v104
	v_rcp_f32_e32 v105, v105
	v_rcp_f32_e32 v106, v106
	v_rcp_f32_e32 v107, v107
	v_rcp_f32_e32 v108, v108
	v_rcp_f32_e32 v109, v109
	v_rcp_f32_e32 v110, v110
	v_rcp_f32_e32 v111, v111
	v_mul_f32_e32 v104, v104, v88
	v_mul_f32_e32 v105, v105, v89
	v_mul_f32_e32 v106, v106, v90
	v_mul_f32_e32 v107, v107, v91
	v_mul_f32_e32 v108, v108, v92
	v_mul_f32_e32 v109, v109, v93
	v_mul_f32_e32 v110, v110, v94
	v_mul_f32_e32 v111, v111, v95
	v_mul_f32_e32 v104, v80, v104
	v_mul_f32_e32 v105, v81, v105
	v_mul_f32_e32 v106, v82, v106
	v_mul_f32_e32 v107, v83, v107
	v_mul_f32_e32 v108, v84, v108
	v_mul_f32_e32 v109, v85, v109
	v_mul_f32_e32 v110, v86, v110
	v_mul_f32_e32 v111, v87, v111
	v_cvt_pk_bf16_f32 v112, v104, v105
	v_cvt_pk_bf16_f32 v113, v106, v107
	v_cvt_pk_bf16_f32 v114, v108, v109
	v_cvt_pk_bf16_f32 v115, v110, v111
	global_store_dwordx4 v27, v[112:115], s[24:25]
	s_add_u32 s24, s24, 0x2800
	s_addc_u32 s25, s25, 0
	global_load_dwordx4 v[44:47], v31, s[12:13] nt
	global_load_dwordx4 v[48:51], v31, s[12:13] offset:16 nt
	global_load_dwordx4 v[52:55], v26, s[96:97] nt
	s_add_u32 s12, s12, 0x1000
	s_addc_u32 s13, s13, 0
	s_add_u32 s96, s96, 0x2800
	s_addc_u32 s97, s97, 0
	s_waitcnt vmcnt(12)
	v_lshlrev_b32_e32 v80, 16, v56
	v_and_b32_e32 v96, 0xffff0000, v56
	v_lshlrev_b32_e32 v81, 16, v57
	v_and_b32_e32 v97, 0xffff0000, v57
	v_lshlrev_b32_e32 v82, 16, v58
	v_and_b32_e32 v98, 0xffff0000, v58
	v_lshlrev_b32_e32 v83, 16, v59
	v_and_b32_e32 v99, 0xffff0000, v59
	v_lshlrev_b32_e32 v84, 16, v60
	v_and_b32_e32 v100, 0xffff0000, v60
	v_lshlrev_b32_e32 v85, 16, v61
	v_and_b32_e32 v101, 0xffff0000, v61
	v_lshlrev_b32_e32 v86, 16, v62
	v_and_b32_e32 v102, 0xffff0000, v62
	v_lshlrev_b32_e32 v87, 16, v63
	v_and_b32_e32 v103, 0xffff0000, v63
	v_lshlrev_b32_e32 v88, 16, v64
	v_and_b32_e32 v89, 0xffff0000, v64
	v_lshlrev_b32_e32 v90, 16, v65
	v_and_b32_e32 v91, 0xffff0000, v65
	v_lshlrev_b32_e32 v92, 16, v66
	v_and_b32_e32 v93, 0xffff0000, v66
	v_lshlrev_b32_e32 v94, 16, v67
	v_and_b32_e32 v95, 0xffff0000, v67
	v_fmac_f32_e32 v80, v96, v18
	v_fmac_f32_e32 v81, v97, v19
	v_fmac_f32_e32 v82, v98, v20
	v_fmac_f32_e32 v83, v99, v21
	v_fmac_f32_e32 v84, v100, v22
	v_fmac_f32_e32 v85, v101, v23
	v_fmac_f32_e32 v86, v102, v24
	v_fmac_f32_e32 v87, v103, v25
	v_mul_f32_e32 v104, 0x3d372713, v88
	v_mul_f32_e32 v105, 0x3d372713, v89
	v_mul_f32_e32 v106, 0x3d372713, v90
	v_mul_f32_e32 v107, 0x3d372713, v91
	v_mul_f32_e32 v108, 0x3d372713, v92
	v_mul_f32_e32 v109, 0x3d372713, v93
	v_mul_f32_e32 v110, 0x3d372713, v94
	v_mul_f32_e32 v111, 0x3d372713, v95
	v_mul_f32_e32 v104, v104, v88
	v_mul_f32_e32 v105, v105, v89
	v_mul_f32_e32 v106, v106, v90
	v_mul_f32_e32 v107, v107, v91
	v_mul_f32_e32 v108, v108, v92
	v_mul_f32_e32 v109, v109, v93
	v_mul_f32_e32 v110, v110, v94
	v_mul_f32_e32 v111, v111, v95
	v_fma_f32 v104, v104, v88, v88
	v_fma_f32 v105, v105, v89, v89
	v_fma_f32 v106, v106, v90, v90
	v_fma_f32 v107, v107, v91, v91
	v_fma_f32 v108, v108, v92, v92
	v_fma_f32 v109, v109, v93, v93
	v_fma_f32 v110, v110, v94, v94
	v_fma_f32 v111, v111, v95, v95
	v_mul_f32_e32 v104, 0x3fcc422a, v104
	v_mul_f32_e32 v105, 0x3fcc422a, v105
	v_mul_f32_e32 v106, 0x3fcc422a, v106
	v_mul_f32_e32 v107, 0x3fcc422a, v107
	v_mul_f32_e32 v108, 0x3fcc422a, v108
	v_mul_f32_e32 v109, 0x3fcc422a, v109
	v_mul_f32_e32 v110, 0x3fcc422a, v110
	v_mul_f32_e32 v111, 0x3fcc422a, v111
	v_mul_f32_e32 v104, 0xbfb8aa3b, v104
	v_mul_f32_e32 v105, 0xbfb8aa3b, v105
	v_mul_f32_e32 v106, 0xbfb8aa3b, v106
	v_mul_f32_e32 v107, 0xbfb8aa3b, v107
	v_mul_f32_e32 v108, 0xbfb8aa3b, v108
	v_mul_f32_e32 v109, 0xbfb8aa3b, v109
	v_mul_f32_e32 v110, 0xbfb8aa3b, v110
	v_mul_f32_e32 v111, 0xbfb8aa3b, v111
	v_exp_f32_e32 v104, v104
	v_exp_f32_e32 v105, v105
	v_exp_f32_e32 v106, v106
	v_exp_f32_e32 v107, v107
	v_exp_f32_e32 v108, v108
	v_exp_f32_e32 v109, v109
	v_exp_f32_e32 v110, v110
	v_exp_f32_e32 v111, v111
	v_add_f32_e32 v104, 1.0, v104
	v_add_f32_e32 v105, 1.0, v105
	v_add_f32_e32 v106, 1.0, v106
	v_add_f32_e32 v107, 1.0, v107
	v_add_f32_e32 v108, 1.0, v108
	v_add_f32_e32 v109, 1.0, v109
	v_add_f32_e32 v110, 1.0, v110
	v_add_f32_e32 v111, 1.0, v111
	v_rcp_f32_e32 v104, v104
	v_rcp_f32_e32 v105, v105
	v_rcp_f32_e32 v106, v106
	v_rcp_f32_e32 v107, v107
	v_rcp_f32_e32 v108, v108
	v_rcp_f32_e32 v109, v109
	v_rcp_f32_e32 v110, v110
	v_rcp_f32_e32 v111, v111
	v_mul_f32_e32 v104, v104, v88
	v_mul_f32_e32 v105, v105, v89
	v_mul_f32_e32 v106, v106, v90
	v_mul_f32_e32 v107, v107, v91
	v_mul_f32_e32 v108, v108, v92
	v_mul_f32_e32 v109, v109, v93
	v_mul_f32_e32 v110, v110, v94
	v_mul_f32_e32 v111, v111, v95
	v_mul_f32_e32 v104, v80, v104
	v_mul_f32_e32 v105, v81, v105
	v_mul_f32_e32 v106, v82, v106
	v_mul_f32_e32 v107, v83, v107
	v_mul_f32_e32 v108, v84, v108
	v_mul_f32_e32 v109, v85, v109
	v_mul_f32_e32 v110, v86, v110
	v_mul_f32_e32 v111, v87, v111
	v_cvt_pk_bf16_f32 v112, v104, v105
	v_cvt_pk_bf16_f32 v113, v106, v107
	v_cvt_pk_bf16_f32 v114, v108, v109
	v_cvt_pk_bf16_f32 v115, v110, v111
	global_store_dwordx4 v27, v[112:115], s[24:25]
	s_add_u32 s24, s24, 0x2800
	s_addc_u32 s25, s25, 0
	global_load_dwordx4 v[56:59], v31, s[12:13] nt
	global_load_dwordx4 v[60:63], v31, s[12:13] offset:16 nt
	global_load_dwordx4 v[64:67], v26, s[96:97] nt
	s_add_u32 s12, s12, 0x1000
	s_addc_u32 s13, s13, 0
	s_add_u32 s96, s96, 0x2800
	s_addc_u32 s97, s97, 0
	s_waitcnt vmcnt(12)
; __device__ __forceinline__ u32x4 pack8(const float (&f)[8]) { u32x4 o; o.x = cvt_pk_bf16(f[0], f[1]); o.y = cvt_pk_bf16(f[2], f[3]); o.z = cvt_pk_bf16(f[4], f[5]); o.w = cvt_pk_bf16(f[6], f[7]); return o; }
; __device__ __forceinline__ float gelu_tanh(float x) { return x * sigmoidf_(1.5957691216057308f * (x + 0.044715f * x * x * x)); }
; __device__ __forceinline__ void fixup_phase(KP p, int l) {
;     ...
;         for (int i = 0; i < 16; ++i) {
;             const size_t m = (size_t)(m0 + i);
;             float hl[8], pc[8], gr[8], o[8], h[8];
;             unpack8(__builtin_nontemporal_load((const u32x4*)(HLOC + m * D + c0)), hl); unpack8(__builtin_nontemporal_load((const u32x4*)(PCUM + m * D + c0)), pc);
;             bf16_t* gp = P + m * DP + C_GR + c0; unpack8(*(const u32x4*)gp, gr);
; #pragma unroll
;             for (int e = 0; e < 8; ++e) { h[e] = hl[e] + pc[e] * carry[e]; o[e] = gelu_tanh(gr[e]) * h[e]; }
;             *(u32x4*)gp = pack8(o);
	v_lshlrev_b32_e32 v80, 16, v68
	v_and_b32_e32 v96, 0xffff0000, v68
	v_lshlrev_b32_e32 v81, 16, v69
	v_and_b32_e32 v97, 0xffff0000, v69
	v_lshlrev_b32_e32 v82, 16, v70
	v_and_b32_e32 v98, 0xffff0000, v70
	v_lshlrev_b32_e32 v83, 16, v71
	v_and_b32_e32 v99, 0xffff0000, v71
	v_lshlrev_b32_e32 v84, 16, v72
	v_and_b32_e32 v100, 0xffff0000, v72
	v_lshlrev_b32_e32 v85, 16, v73
	v_and_b32_e32 v101, 0xffff0000, v73
	v_lshlrev_b32_e32 v86, 16, v74
	v_and_b32_e32 v102, 0xffff0000, v74
	v_lshlrev_b32_e32 v87, 16, v75
	v_and_b32_e32 v103, 0xffff0000, v75
	v_lshlrev_b32_e32 v88, 16, v76
	v_and_b32_e32 v89, 0xffff0000, v76
	v_lshlrev_b32_e32 v90, 16, v77
	v_and_b32_e32 v91, 0xffff0000, v77
	v_lshlrev_b32_e32 v92, 16, v78
	v_and_b32_e32 v93, 0xffff0000, v78
	v_lshlrev_b32_e32 v94, 16, v79
	v_and_b32_e32 v95, 0xffff0000, v79
	v_fmac_f32_e32 v80, v96, v18
	v_fmac_f32_e32 v81, v97, v19
	v_fmac_f32_e32 v82, v98, v20
	v_fmac_f32_e32 v83, v99, v21
	v_fmac_f32_e32 v84, v100, v22
	v_fmac_f32_e32 v85, v101, v23
	v_fmac_f32_e32 v86, v102, v24
	v_fmac_f32_e32 v87, v103, v25
	v_mul_f32_e32 v104, 0x3d372713, v88
	v_mul_f32_e32 v105, 0x3d372713, v89
	v_mul_f32_e32 v106, 0x3d372713, v90
	v_mul_f32_e32 v107, 0x3d372713, v91
	v_mul_f32_e32 v108, 0x3d372713, v92
	v_mul_f32_e32 v109, 0x3d372713, v93
	v_mul_f32_e32 v110, 0x3d372713, v94
	v_mul_f32_e32 v111, 0x3d372713, v95
	v_mul_f32_e32 v104, v104, v88
	v_mul_f32_e32 v105, v105, v89
	v_mul_f32_e32 v106, v106, v90
	v_mul_f32_e32 v107, v107, v91
	v_mul_f32_e32 v108, v108, v92
	v_mul_f32_e32 v109, v109, v93
	v_mul_f32_e32 v110, v110, v94
	v_mul_f32_e32 v111, v111, v95
	v_fma_f32 v104, v104, v88, v88
	v_fma_f32 v105, v105, v89, v89
	v_fma_f32 v106, v106, v90, v90
	v_fma_f32 v107, v107, v91, v91
	v_fma_f32 v108, v108, v92, v92
	v_fma_f32 v109, v109, v93, v93
	v_fma_f32 v110, v110, v94, v94
	v_fma_f32 v111, v111, v95, v95
	v_mul_f32_e32 v104, 0x3fcc422a, v104
	v_mul_f32_e32 v105, 0x3fcc422a, v105
	v_mul_f32_e32 v106, 0x3fcc422a, v106
	v_mul_f32_e32 v107, 0x3fcc422a, v107
	v_mul_f32_e32 v108, 0x3fcc422a, v108
	v_mul_f32_e32 v109, 0x3fcc422a, v109
	v_mul_f32_e32 v110, 0x3fcc422a, v110
	v_mul_f32_e32 v111, 0x3fcc422a, v111
	v_mul_f32_e32 v104, 0xbfb8aa3b, v104
	v_mul_f32_e32 v105, 0xbfb8aa3b, v105
	v_mul_f32_e32 v106, 0xbfb8aa3b, v106
	v_mul_f32_e32 v107, 0xbfb8aa3b, v107
	v_mul_f32_e32 v108, 0xbfb8aa3b, v108
	v_mul_f32_e32 v109, 0xbfb8aa3b, v109
	v_mul_f32_e32 v110, 0xbfb8aa3b, v110
	v_mul_f32_e32 v111, 0xbfb8aa3b, v111
	v_exp_f32_e32 v104, v104
	v_exp_f32_e32 v105, v105
	v_exp_f32_e32 v106, v106
	v_exp_f32_e32 v107, v107
	v_exp_f32_e32 v108, v108
	v_exp_f32_e32 v109, v109
	v_exp_f32_e32 v110, v110
	v_exp_f32_e32 v111, v111
	v_add_f32_e32 v104, 1.0, v104
	v_add_f32_e32 v105, 1.0, v105
	v_add_f32_e32 v106, 1.0, v106
	v_add_f32_e32 v107, 1.0, v107
	v_add_f32_e32 v108, 1.0, v108
	v_add_f32_e32 v109, 1.0, v109
	v_add_f32_e32 v110, 1.0, v110
	v_add_f32_e32 v111, 1.0, v111
	v_rcp_f32_e32 v104, v104
	v_rcp_f32_e32 v105, v105
	v_rcp_f32_e32 v106, v106
	v_rcp_f32_e32 v107, v107
	v_rcp_f32_e32 v108, v108
	v_rcp_f32_e32 v109, v109
	v_rcp_f32_e32 v110, v110
	v_rcp_f32_e32 v111, v111
	v_mul_f32_e32 v104, v104, v88
	v_mul_f32_e32 v105, v105, v89
	v_mul_f32_e32 v106, v106, v90
	v_mul_f32_e32 v107, v107, v91
	v_mul_f32_e32 v108, v108, v92
	v_mul_f32_e32 v109, v109, v93
	v_mul_f32_e32 v110, v110, v94
	v_mul_f32_e32 v111, v111, v95
	v_mul_f32_e32 v104, v80, v104
	v_mul_f32_e32 v105, v81, v105
	v_mul_f32_e32 v106, v82, v106
	v_mul_f32_e32 v107, v83, v107
	v_mul_f32_e32 v108, v84, v108
	v_mul_f32_e32 v109, v85, v109
	v_mul_f32_e32 v110, v86, v110
	v_mul_f32_e32 v111, v87, v111
	v_cvt_pk_bf16_f32 v112, v104, v105
	v_cvt_pk_bf16_f32 v113, v106, v107
	v_cvt_pk_bf16_f32 v114, v108, v109
	v_cvt_pk_bf16_f32 v115, v110, v111
	global_store_dwordx4 v27, v[112:115], s[24:25]
	s_add_u32 s24, s24, 0x2800
	s_addc_u32 s25, s25, 0
	global_load_dwordx4 v[68:71], v31, s[12:13] nt
	global_load_dwordx4 v[72:75], v31, s[12:13] offset:16 nt
	global_load_dwordx4 v[76:79], v26, s[96:97] nt
	s_add_u32 s12, s12, 0x1000
	s_addc_u32 s13, s13, 0
	s_add_u32 s96, s96, 0x2800
	s_addc_u32 s97, s97, 0
	s_waitcnt vmcnt(12)
	v_lshlrev_b32_e32 v80, 16, v32
	v_and_b32_e32 v96, 0xffff0000, v32
	v_lshlrev_b32_e32 v81, 16, v33
	v_and_b32_e32 v97, 0xffff0000, v33
	v_lshlrev_b32_e32 v82, 16, v34
	v_and_b32_e32 v98, 0xffff0000, v34
	v_lshlrev_b32_e32 v83, 16, v35
	v_and_b32_e32 v99, 0xffff0000, v35
	v_lshlrev_b32_e32 v84, 16, v36
	v_and_b32_e32 v100, 0xffff0000, v36
	v_lshlrev_b32_e32 v85, 16, v37
	v_and_b32_e32 v101, 0xffff0000, v37
	v_lshlrev_b32_e32 v86, 16, v38
	v_and_b32_e32 v102, 0xffff0000, v38
	v_lshlrev_b32_e32 v87, 16, v39
	v_and_b32_e32 v103, 0xffff0000, v39
	v_lshlrev_b32_e32 v88, 16, v40
	v_and_b32_e32 v89, 0xffff0000, v40
	v_lshlrev_b32_e32 v90, 16, v41
	v_and_b32_e32 v91, 0xffff0000, v41
	v_lshlrev_b32_e32 v92, 16, v42
	v_and_b32_e32 v93, 0xffff0000, v42
	v_lshlrev_b32_e32 v94, 16, v43
	v_and_b32_e32 v95, 0xffff0000, v43
	v_fmac_f32_e32 v80, v96, v18
	v_fmac_f32_e32 v81, v97, v19
	v_fmac_f32_e32 v82, v98, v20
	v_fmac_f32_e32 v83, v99, v21
	v_fmac_f32_e32 v84, v100, v22
	v_fmac_f32_e32 v85, v101, v23
	v_fmac_f32_e32 v86, v102, v24
	v_fmac_f32_e32 v87, v103, v25
	v_mul_f32_e32 v104, 0x3d372713, v88
	v_mul_f32_e32 v105, 0x3d372713, v89
	v_mul_f32_e32 v106, 0x3d372713, v90
	v_mul_f32_e32 v107, 0x3d372713, v91
	v_mul_f32_e32 v108, 0x3d372713, v92
	v_mul_f32_e32 v109, 0x3d372713, v93
	v_mul_f32_e32 v110, 0x3d372713, v94
	v_mul_f32_e32 v111, 0x3d372713, v95
	v_mul_f32_e32 v104, v104, v88
	v_mul_f32_e32 v105, v105, v89
	v_mul_f32_e32 v106, v106, v90
	v_mul_f32_e32 v107, v107, v91
; __device__ __forceinline__ u32x4 pack8(const float (&f)[8]) { u32x4 o; o.x = cvt_pk_bf16(f[0], f[1]); o.y = cvt_pk_bf16(f[2], f[3]); o.z = cvt_pk_bf16(f[4], f[5]); o.w = cvt_pk_bf16(f[6], f[7]); return o; }
; __device__ __forceinline__ float gelu_tanh(float x) { return x * sigmoidf_(1.5957691216057308f * (x + 0.044715f * x * x * x)); }
; __device__ __forceinline__ void fixup_phase(KP p, int l) {
;     ...
;         for (int i = 0; i < 16; ++i) {
;             const size_t m = (size_t)(m0 + i);
;             float hl[8], pc[8], gr[8], o[8], h[8];
;             unpack8(__builtin_nontemporal_load((const u32x4*)(HLOC + m * D + c0)), hl); unpack8(__builtin_nontemporal_load((const u32x4*)(PCUM + m * D + c0)), pc);
;             bf16_t* gp = P + m * DP + C_GR + c0; unpack8(*(const u32x4*)gp, gr);
; #pragma unroll
;             for (int e = 0; e < 8; ++e) { h[e] = hl[e] + pc[e] * carry[e]; o[e] = gelu_tanh(gr[e]) * h[e]; }
;             *(u32x4*)gp = pack8(o);
	v_mul_f32_e32 v108, v108, v92
	v_mul_f32_e32 v109, v109, v93
	v_mul_f32_e32 v110, v110, v94
	v_mul_f32_e32 v111, v111, v95
	v_fma_f32 v104, v104, v88, v88
	v_fma_f32 v105, v105, v89, v89
	v_fma_f32 v106, v106, v90, v90
	v_fma_f32 v107, v107, v91, v91
	v_fma_f32 v108, v108, v92, v92
	v_fma_f32 v109, v109, v93, v93
	v_fma_f32 v110, v110, v94, v94
	v_fma_f32 v111, v111, v95, v95
	v_mul_f32_e32 v104, 0x3fcc422a, v104
	v_mul_f32_e32 v105, 0x3fcc422a, v105
	v_mul_f32_e32 v106, 0x3fcc422a, v106
	v_mul_f32_e32 v107, 0x3fcc422a, v107
	v_mul_f32_e32 v108, 0x3fcc422a, v108
	v_mul_f32_e32 v109, 0x3fcc422a, v109
	v_mul_f32_e32 v110, 0x3fcc422a, v110
	v_mul_f32_e32 v111, 0x3fcc422a, v111
	v_mul_f32_e32 v104, 0xbfb8aa3b, v104
	v_mul_f32_e32 v105, 0xbfb8aa3b, v105
	v_mul_f32_e32 v106, 0xbfb8aa3b, v106
	v_mul_f32_e32 v107, 0xbfb8aa3b, v107
	v_mul_f32_e32 v108, 0xbfb8aa3b, v108
	v_mul_f32_e32 v109, 0xbfb8aa3b, v109
	v_mul_f32_e32 v110, 0xbfb8aa3b, v110
	v_mul_f32_e32 v111, 0xbfb8aa3b, v111
	v_exp_f32_e32 v104, v104
	v_exp_f32_e32 v105, v105
	v_exp_f32_e32 v106, v106
	v_exp_f32_e32 v107, v107
	v_exp_f32_e32 v108, v108
	v_exp_f32_e32 v109, v109
	v_exp_f32_e32 v110, v110
	v_exp_f32_e32 v111, v111
	v_add_f32_e32 v104, 1.0, v104
	v_add_f32_e32 v105, 1.0, v105
	v_add_f32_e32 v106, 1.0, v106
	v_add_f32_e32 v107, 1.0, v107
	v_add_f32_e32 v108, 1.0, v108
	v_add_f32_e32 v109, 1.0, v109
	v_add_f32_e32 v110, 1.0, v110
	v_add_f32_e32 v111, 1.0, v111
	v_rcp_f32_e32 v104, v104
	v_rcp_f32_e32 v105, v105
	v_rcp_f32_e32 v106, v106
	v_rcp_f32_e32 v107, v107
	v_rcp_f32_e32 v108, v108
	v_rcp_f32_e32 v109, v109
	v_rcp_f32_e32 v110, v110
	v_rcp_f32_e32 v111, v111
	v_mul_f32_e32 v104, v104, v88
	v_mul_f32_e32 v105, v105, v89
	v_mul_f32_e32 v106, v106, v90
	v_mul_f32_e32 v107, v107, v91
	v_mul_f32_e32 v108, v108, v92
	v_mul_f32_e32 v109, v109, v93
	v_mul_f32_e32 v110, v110, v94
	v_mul_f32_e32 v111, v111, v95
	v_mul_f32_e32 v104, v80, v104
	v_mul_f32_e32 v105, v81, v105
	v_mul_f32_e32 v106, v82, v106
	v_mul_f32_e32 v107, v83, v107
	v_mul_f32_e32 v108, v84, v108
	v_mul_f32_e32 v109, v85, v109
	v_mul_f32_e32 v110, v86, v110
	v_mul_f32_e32 v111, v87, v111
	v_cvt_pk_bf16_f32 v112, v104, v105
	v_cvt_pk_bf16_f32 v113, v106, v107
	v_cvt_pk_bf16_f32 v114, v108, v109
	v_cvt_pk_bf16_f32 v115, v110, v111
	global_store_dwordx4 v27, v[112:115], s[24:25]
	s_add_u32 s24, s24, 0x2800
	s_addc_u32 s25, s25, 0
	global_load_dwordx4 v[32:35], v31, s[12:13] nt
	global_load_dwordx4 v[36:39], v31, s[12:13] offset:16 nt
	global_load_dwordx4 v[40:43], v26, s[96:97] nt
	s_add_u32 s12, s12, 0x1000
	s_addc_u32 s13, s13, 0
	s_add_u32 s96, s96, 0x2800
	s_addc_u32 s97, s97, 0
	s_waitcnt vmcnt(12)
	v_lshlrev_b32_e32 v80, 16, v44
	v_and_b32_e32 v96, 0xffff0000, v44
	v_lshlrev_b32_e32 v81, 16, v45
	v_and_b32_e32 v97, 0xffff0000, v45
	v_lshlrev_b32_e32 v82, 16, v46
	v_and_b32_e32 v98, 0xffff0000, v46
	v_lshlrev_b32_e32 v83, 16, v47
	v_and_b32_e32 v99, 0xffff0000, v47
	v_lshlrev_b32_e32 v84, 16, v48
	v_and_b32_e32 v100, 0xffff0000, v48
	v_lshlrev_b32_e32 v85, 16, v49
	v_and_b32_e32 v101, 0xffff0000, v49
	v_lshlrev_b32_e32 v86, 16, v50
	v_and_b32_e32 v102, 0xffff0000, v50
	v_lshlrev_b32_e32 v87, 16, v51
	v_and_b32_e32 v103, 0xffff0000, v51
	v_lshlrev_b32_e32 v88, 16, v52
	v_and_b32_e32 v89, 0xffff0000, v52
	v_lshlrev_b32_e32 v90, 16, v53
	v_and_b32_e32 v91, 0xffff0000, v53
	v_lshlrev_b32_e32 v92, 16, v54
	v_and_b32_e32 v93, 0xffff0000, v54
	v_lshlrev_b32_e32 v94, 16, v55
	v_and_b32_e32 v95, 0xffff0000, v55
	v_fmac_f32_e32 v80, v96, v18
	v_fmac_f32_e32 v81, v97, v19
	v_fmac_f32_e32 v82, v98, v20
	v_fmac_f32_e32 v83, v99, v21
	v_fmac_f32_e32 v84, v100, v22
	v_fmac_f32_e32 v85, v101, v23
	v_fmac_f32_e32 v86, v102, v24
	v_fmac_f32_e32 v87, v103, v25
	v_mul_f32_e32 v104, 0x3d372713, v88
	v_mul_f32_e32 v105, 0x3d372713, v89
	v_mul_f32_e32 v106, 0x3d372713, v90
	v_mul_f32_e32 v107, 0x3d372713, v91
	v_mul_f32_e32 v108, 0x3d372713, v92
	v_mul_f32_e32 v109, 0x3d372713, v93
	v_mul_f32_e32 v110, 0x3d372713, v94
	v_mul_f32_e32 v111, 0x3d372713, v95
	v_mul_f32_e32 v104, v104, v88
	v_mul_f32_e32 v105, v105, v89
	v_mul_f32_e32 v106, v106, v90
	v_mul_f32_e32 v107, v107, v91
	v_mul_f32_e32 v108, v108, v92
	v_mul_f32_e32 v109, v109, v93
	v_mul_f32_e32 v110, v110, v94
	v_mul_f32_e32 v111, v111, v95
	v_fma_f32 v104, v104, v88, v88
	v_fma_f32 v105, v105, v89, v89
	v_fma_f32 v106, v106, v90, v90
	v_fma_f32 v107, v107, v91, v91
	v_fma_f32 v108, v108, v92, v92
	v_fma_f32 v109, v109, v93, v93
	v_fma_f32 v110, v110, v94, v94
	v_fma_f32 v111, v111, v95, v95
	v_mul_f32_e32 v104, 0x3fcc422a, v104
	v_mul_f32_e32 v105, 0x3fcc422a, v105
	v_mul_f32_e32 v106, 0x3fcc422a, v106
	v_mul_f32_e32 v107, 0x3fcc422a, v107
	v_mul_f32_e32 v108, 0x3fcc422a, v108
	v_mul_f32_e32 v109, 0x3fcc422a, v109
	v_mul_f32_e32 v110, 0x3fcc422a, v110
	v_mul_f32_e32 v111, 0x3fcc422a, v111
	v_mul_f32_e32 v104, 0xbfb8aa3b, v104
	v_mul_f32_e32 v105, 0xbfb8aa3b, v105
	v_mul_f32_e32 v106, 0xbfb8aa3b, v106
	v_mul_f32_e32 v107, 0xbfb8aa3b, v107
	v_mul_f32_e32 v108, 0xbfb8aa3b, v108
	v_mul_f32_e32 v109, 0xbfb8aa3b, v109
	v_mul_f32_e32 v110, 0xbfb8aa3b, v110
	v_mul_f32_e32 v111, 0xbfb8aa3b, v111
	v_exp_f32_e32 v104, v104
	v_exp_f32_e32 v105, v105
	v_exp_f32_e32 v106, v106
	v_exp_f32_e32 v107, v107
	v_exp_f32_e32 v108, v108
	v_exp_f32_e32 v109, v109
	v_exp_f32_e32 v110, v110
	v_exp_f32_e32 v111, v111
	v_add_f32_e32 v104, 1.0, v104
	v_add_f32_e32 v105, 1.0, v105
	v_add_f32_e32 v106, 1.0, v106
	v_add_f32_e32 v107, 1.0, v107
	v_add_f32_e32 v108, 1.0, v108
	v_add_f32_e32 v109, 1.0, v109
	v_add_f32_e32 v110, 1.0, v110
	v_add_f32_e32 v111, 1.0, v111
	v_rcp_f32_e32 v104, v104
	v_rcp_f32_e32 v105, v105
	v_rcp_f32_e32 v106, v106
	v_rcp_f32_e32 v107, v107
	v_rcp_f32_e32 v108, v108
	v_rcp_f32_e32 v109, v109
	v_rcp_f32_e32 v110, v110
	v_rcp_f32_e32 v111, v111
	v_mul_f32_e32 v104, v104, v88
	v_mul_f32_e32 v105, v105, v89
	v_mul_f32_e32 v106, v106, v90
	v_mul_f32_e32 v107, v107, v91
	v_mul_f32_e32 v108, v108, v92
	v_mul_f32_e32 v109, v109, v93
	v_mul_f32_e32 v110, v110, v94
	v_mul_f32_e32 v111, v111, v95
	v_mul_f32_e32 v104, v80, v104
	v_mul_f32_e32 v105, v81, v105
	v_mul_f32_e32 v106, v82, v106
	v_mul_f32_e32 v107, v83, v107
	v_mul_f32_e32 v108, v84, v108
	v_mul_f32_e32 v109, v85, v109
	v_mul_f32_e32 v110, v86, v110
	v_mul_f32_e32 v111, v87, v111
	v_cvt_pk_bf16_f32 v112, v104, v105
	v_cvt_pk_bf16_f32 v113, v106, v107
	v_cvt_pk_bf16_f32 v114, v108, v109
	v_cvt_pk_bf16_f32 v115, v110, v111
	global_store_dwordx4 v27, v[112:115], s[24:25]
	s_add_u32 s24, s24, 0x2800
	s_addc_u32 s25, s25, 0
	global_load_dwordx4 v[44:47], v31, s[12:13] nt
	global_load_dwordx4 v[48:51], v31, s[12:13] offset:16 nt
	global_load_dwordx4 v[52:55], v26, s[96:97] nt
	s_add_u32 s12, s12, 0x1000
	s_addc_u32 s13, s13, 0
	s_add_u32 s96, s96, 0x2800
	s_addc_u32 s97, s97, 0
	s_waitcnt vmcnt(12)
; __device__ __forceinline__ u32x4 pack8(const float (&f)[8]) { u32x4 o; o.x = cvt_pk_bf16(f[0], f[1]); o.y = cvt_pk_bf16(f[2], f[3]); o.z = cvt_pk_bf16(f[4], f[5]); o.w = cvt_pk_bf16(f[6], f[7]); return o; }
; __device__ __forceinline__ float gelu_tanh(float x) { return x * sigmoidf_(1.5957691216057308f * (x + 0.044715f * x * x * x)); }
; __device__ __forceinline__ void fixup_phase(KP p, int l) {
;     ...
;         for (int i = 0; i < 16; ++i) {
;             const size_t m = (size_t)(m0 + i);
;             float hl[8], pc[8], gr[8], o[8], h[8];
;             unpack8(__builtin_nontemporal_load((const u32x4*)(HLOC + m * D + c0)), hl); unpack8(__builtin_nontemporal_load((const u32x4*)(PCUM + m * D + c0)), pc);
;             bf16_t* gp = P + m * DP + C_GR + c0; unpack8(*(const u32x4*)gp, gr);
; #pragma unroll
;             for (int e = 0; e < 8; ++e) { h[e] = hl[e] + pc[e] * carry[e]; o[e] = gelu_tanh(gr[e]) * h[e]; }
;             *(u32x4*)gp = pack8(o);
	v_lshlrev_b32_e32 v80, 16, v56
	v_and_b32_e32 v96, 0xffff0000, v56
	v_lshlrev_b32_e32 v81, 16, v57
	v_and_b32_e32 v97, 0xffff0000, v57
	v_lshlrev_b32_e32 v82, 16, v58
	v_and_b32_e32 v98, 0xffff0000, v58
	v_lshlrev_b32_e32 v83, 16, v59
	v_and_b32_e32 v99, 0xffff0000, v59
	v_lshlrev_b32_e32 v84, 16, v60
	v_and_b32_e32 v100, 0xffff0000, v60
	v_lshlrev_b32_e32 v85, 16, v61
	v_and_b32_e32 v101, 0xffff0000, v61
	v_lshlrev_b32_e32 v86, 16, v62
	v_and_b32_e32 v102, 0xffff0000, v62
	v_lshlrev_b32_e32 v87, 16, v63
	v_and_b32_e32 v103, 0xffff0000, v63
	v_lshlrev_b32_e32 v88, 16, v64
	v_and_b32_e32 v89, 0xffff0000, v64
	v_lshlrev_b32_e32 v90, 16, v65
	v_and_b32_e32 v91, 0xffff0000, v65
	v_lshlrev_b32_e32 v92, 16, v66
	v_and_b32_e32 v93, 0xffff0000, v66
	v_lshlrev_b32_e32 v94, 16, v67
	v_and_b32_e32 v95, 0xffff0000, v67
	v_fmac_f32_e32 v80, v96, v18
	v_fmac_f32_e32 v81, v97, v19
	v_fmac_f32_e32 v82, v98, v20
	v_fmac_f32_e32 v83, v99, v21
	v_fmac_f32_e32 v84, v100, v22
	v_fmac_f32_e32 v85, v101, v23
	v_fmac_f32_e32 v86, v102, v24
	v_fmac_f32_e32 v87, v103, v25
	v_mul_f32_e32 v104, 0x3d372713, v88
	v_mul_f32_e32 v105, 0x3d372713, v89
	v_mul_f32_e32 v106, 0x3d372713, v90
	v_mul_f32_e32 v107, 0x3d372713, v91
	v_mul_f32_e32 v108, 0x3d372713, v92
	v_mul_f32_e32 v109, 0x3d372713, v93
	v_mul_f32_e32 v110, 0x3d372713, v94
	v_mul_f32_e32 v111, 0x3d372713, v95
	v_mul_f32_e32 v104, v104, v88
	v_mul_f32_e32 v105, v105, v89
	v_mul_f32_e32 v106, v106, v90
	v_mul_f32_e32 v107, v107, v91
	v_mul_f32_e32 v108, v108, v92
	v_mul_f32_e32 v109, v109, v93
	v_mul_f32_e32 v110, v110, v94
	v_mul_f32_e32 v111, v111, v95
	v_fma_f32 v104, v104, v88, v88
	v_fma_f32 v105, v105, v89, v89
	v_fma_f32 v106, v106, v90, v90
	v_fma_f32 v107, v107, v91, v91
	v_fma_f32 v108, v108, v92, v92
	v_fma_f32 v109, v109, v93, v93
	v_fma_f32 v110, v110, v94, v94
	v_fma_f32 v111, v111, v95, v95
	v_mul_f32_e32 v104, 0x3fcc422a, v104
	v_mul_f32_e32 v105, 0x3fcc422a, v105
	v_mul_f32_e32 v106, 0x3fcc422a, v106
	v_mul_f32_e32 v107, 0x3fcc422a, v107
	v_mul_f32_e32 v108, 0x3fcc422a, v108
	v_mul_f32_e32 v109, 0x3fcc422a, v109
	v_mul_f32_e32 v110, 0x3fcc422a, v110
	v_mul_f32_e32 v111, 0x3fcc422a, v111
	v_mul_f32_e32 v104, 0xbfb8aa3b, v104
	v_mul_f32_e32 v105, 0xbfb8aa3b, v105
	v_mul_f32_e32 v106, 0xbfb8aa3b, v106
	v_mul_f32_e32 v107, 0xbfb8aa3b, v107
	v_mul_f32_e32 v108, 0xbfb8aa3b, v108
	v_mul_f32_e32 v109, 0xbfb8aa3b, v109
	v_mul_f32_e32 v110, 0xbfb8aa3b, v110
	v_mul_f32_e32 v111, 0xbfb8aa3b, v111
	v_exp_f32_e32 v104, v104
	v_exp_f32_e32 v105, v105
	v_exp_f32_e32 v106, v106
	v_exp_f32_e32 v107, v107
	v_exp_f32_e32 v108, v108
	v_exp_f32_e32 v109, v109
	v_exp_f32_e32 v110, v110
	v_exp_f32_e32 v111, v111
	v_add_f32_e32 v104, 1.0, v104
	v_add_f32_e32 v105, 1.0, v105
	v_add_f32_e32 v106, 1.0, v106
	v_add_f32_e32 v107, 1.0, v107
	v_add_f32_e32 v108, 1.0, v108
	v_add_f32_e32 v109, 1.0, v109
	v_add_f32_e32 v110, 1.0, v110
	v_add_f32_e32 v111, 1.0, v111
	v_rcp_f32_e32 v104, v104
	v_rcp_f32_e32 v105, v105
	v_rcp_f32_e32 v106, v106
	v_rcp_f32_e32 v107, v107
	v_rcp_f32_e32 v108, v108
	v_rcp_f32_e32 v109, v109
	v_rcp_f32_e32 v110, v110
	v_rcp_f32_e32 v111, v111
	v_mul_f32_e32 v104, v104, v88
	v_mul_f32_e32 v105, v105, v89
	v_mul_f32_e32 v106, v106, v90
	v_mul_f32_e32 v107, v107, v91
	v_mul_f32_e32 v108, v108, v92
	v_mul_f32_e32 v109, v109, v93
	v_mul_f32_e32 v110, v110, v94
	v_mul_f32_e32 v111, v111, v95
	v_mul_f32_e32 v104, v80, v104
	v_mul_f32_e32 v105, v81, v105
	v_mul_f32_e32 v106, v82, v106
	v_mul_f32_e32 v107, v83, v107
	v_mul_f32_e32 v108, v84, v108
	v_mul_f32_e32 v109, v85, v109
	v_mul_f32_e32 v110, v86, v110
	v_mul_f32_e32 v111, v87, v111
	v_cvt_pk_bf16_f32 v112, v104, v105
	v_cvt_pk_bf16_f32 v113, v106, v107
	v_cvt_pk_bf16_f32 v114, v108, v109
	v_cvt_pk_bf16_f32 v115, v110, v111
	global_store_dwordx4 v27, v[112:115], s[24:25]
	s_add_u32 s24, s24, 0x2800
	s_addc_u32 s25, s25, 0
	global_load_dwordx4 v[56:59], v31, s[12:13] nt
	global_load_dwordx4 v[60:63], v31, s[12:13] offset:16 nt
	global_load_dwordx4 v[64:67], v26, s[96:97] nt
	s_add_u32 s12, s12, 0x1000
	s_addc_u32 s13, s13, 0
	s_add_u32 s96, s96, 0x2800
	s_addc_u32 s97, s97, 0
	s_waitcnt vmcnt(12)
	v_lshlrev_b32_e32 v80, 16, v68
	v_and_b32_e32 v96, 0xffff0000, v68
	v_lshlrev_b32_e32 v81, 16, v69
	v_and_b32_e32 v97, 0xffff0000, v69
	v_lshlrev_b32_e32 v82, 16, v70
	v_and_b32_e32 v98, 0xffff0000, v70
	v_lshlrev_b32_e32 v83, 16, v71
	v_and_b32_e32 v99, 0xffff0000, v71
	v_lshlrev_b32_e32 v84, 16, v72
	v_and_b32_e32 v100, 0xffff0000, v72
	v_lshlrev_b32_e32 v85, 16, v73
	v_and_b32_e32 v101, 0xffff0000, v73
	v_lshlrev_b32_e32 v86, 16, v74
	v_and_b32_e32 v102, 0xffff0000, v74
	v_lshlrev_b32_e32 v87, 16, v75
	v_and_b32_e32 v103, 0xffff0000, v75
	v_lshlrev_b32_e32 v88, 16, v76
	v_and_b32_e32 v89, 0xffff0000, v76
	v_lshlrev_b32_e32 v90, 16, v77
	v_and_b32_e32 v91, 0xffff0000, v77
	v_lshlrev_b32_e32 v92, 16, v78
	v_and_b32_e32 v93, 0xffff0000, v78
	v_lshlrev_b32_e32 v94, 16, v79
	v_and_b32_e32 v95, 0xffff0000, v79
	v_fmac_f32_e32 v80, v96, v18
	v_fmac_f32_e32 v81, v97, v19
	v_fmac_f32_e32 v82, v98, v20
	v_fmac_f32_e32 v83, v99, v21
	v_fmac_f32_e32 v84, v100, v22
	v_fmac_f32_e32 v85, v101, v23
	v_fmac_f32_e32 v86, v102, v24
	v_fmac_f32_e32 v87, v103, v25
	v_mul_f32_e32 v104, 0x3d372713, v88
	v_mul_f32_e32 v105, 0x3d372713, v89
	v_mul_f32_e32 v106, 0x3d372713, v90
	v_mul_f32_e32 v107, 0x3d372713, v91
	v_mul_f32_e32 v108, 0x3d372713, v92
	v_mul_f32_e32 v109, 0x3d372713, v93
	v_mul_f32_e32 v110, 0x3d372713, v94
	v_mul_f32_e32 v111, 0x3d372713, v95
	v_mul_f32_e32 v104, v104, v88
	v_mul_f32_e32 v105, v105, v89
	v_mul_f32_e32 v106, v106, v90
	v_mul_f32_e32 v107, v107, v91
; __device__ __forceinline__ u32x4 pack8(const float (&f)[8]) { u32x4 o; o.x = cvt_pk_bf16(f[0], f[1]); o.y = cvt_pk_bf16(f[2], f[3]); o.z = cvt_pk_bf16(f[4], f[5]); o.w = cvt_pk_bf16(f[6], f[7]); return o; }
; __device__ __forceinline__ float gelu_tanh(float x) { return x * sigmoidf_(1.5957691216057308f * (x + 0.044715f * x * x * x)); }
; __device__ __forceinline__ void fixup_phase(KP p, int l) {
;     ...
;         for (int i = 0; i < 16; ++i) {
;             const size_t m = (size_t)(m0 + i);
;             float hl[8], pc[8], gr[8], o[8], h[8];
;             unpack8(__builtin_nontemporal_load((const u32x4*)(HLOC + m * D + c0)), hl); unpack8(__builtin_nontemporal_load((const u32x4*)(PCUM + m * D + c0)), pc);
;             bf16_t* gp = P + m * DP + C_GR + c0; unpack8(*(const u32x4*)gp, gr);
; #pragma unroll
;             for (int e = 0; e < 8; ++e) { h[e] = hl[e] + pc[e] * carry[e]; o[e] = gelu_tanh(gr[e]) * h[e]; }
;             *(u32x4*)gp = pack8(o);
	v_mul_f32_e32 v108, v108, v92
	v_mul_f32_e32 v109, v109, v93
	v_mul_f32_e32 v110, v110, v94
	v_mul_f32_e32 v111, v111, v95
	v_fma_f32 v104, v104, v88, v88
	v_fma_f32 v105, v105, v89, v89
	v_fma_f32 v106, v106, v90, v90
	v_fma_f32 v107, v107, v91, v91
	v_fma_f32 v108, v108, v92, v92
	v_fma_f32 v109, v109, v93, v93
	v_fma_f32 v110, v110, v94, v94
	v_fma_f32 v111, v111, v95, v95
	v_mul_f32_e32 v104, 0x3fcc422a, v104
	v_mul_f32_e32 v105, 0x3fcc422a, v105
	v_mul_f32_e32 v106, 0x3fcc422a, v106
	v_mul_f32_e32 v107, 0x3fcc422a, v107
	v_mul_f32_e32 v108, 0x3fcc422a, v108
	v_mul_f32_e32 v109, 0x3fcc422a, v109
	v_mul_f32_e32 v110, 0x3fcc422a, v110
	v_mul_f32_e32 v111, 0x3fcc422a, v111
	v_mul_f32_e32 v104, 0xbfb8aa3b, v104
	v_mul_f32_e32 v105, 0xbfb8aa3b, v105
	v_mul_f32_e32 v106, 0xbfb8aa3b, v106
	v_mul_f32_e32 v107, 0xbfb8aa3b, v107
	v_mul_f32_e32 v108, 0xbfb8aa3b, v108
	v_mul_f32_e32 v109, 0xbfb8aa3b, v109
	v_mul_f32_e32 v110, 0xbfb8aa3b, v110
	v_mul_f32_e32 v111, 0xbfb8aa3b, v111
	v_exp_f32_e32 v104, v104
	v_exp_f32_e32 v105, v105
	v_exp_f32_e32 v106, v106
	v_exp_f32_e32 v107, v107
	v_exp_f32_e32 v108, v108
	v_exp_f32_e32 v109, v109
	v_exp_f32_e32 v110, v110
	v_exp_f32_e32 v111, v111
	v_add_f32_e32 v104, 1.0, v104
	v_add_f32_e32 v105, 1.0, v105
	v_add_f32_e32 v106, 1.0, v106
	v_add_f32_e32 v107, 1.0, v107
	v_add_f32_e32 v108, 1.0, v108
	v_add_f32_e32 v109, 1.0, v109
	v_add_f32_e32 v110, 1.0, v110
	v_add_f32_e32 v111, 1.0, v111
	v_rcp_f32_e32 v104, v104
	v_rcp_f32_e32 v105, v105
	v_rcp_f32_e32 v106, v106
	v_rcp_f32_e32 v107, v107
	v_rcp_f32_e32 v108, v108
	v_rcp_f32_e32 v109, v109
	v_rcp_f32_e32 v110, v110
	v_rcp_f32_e32 v111, v111
	v_mul_f32_e32 v104, v104, v88
	v_mul_f32_e32 v105, v105, v89
	v_mul_f32_e32 v106, v106, v90
	v_mul_f32_e32 v107, v107, v91
	v_mul_f32_e32 v108, v108, v92
	v_mul_f32_e32 v109, v109, v93
	v_mul_f32_e32 v110, v110, v94
	v_mul_f32_e32 v111, v111, v95
	v_mul_f32_e32 v104, v80, v104
	v_mul_f32_e32 v105, v81, v105
	v_mul_f32_e32 v106, v82, v106
	v_mul_f32_e32 v107, v83, v107
	v_mul_f32_e32 v108, v84, v108
	v_mul_f32_e32 v109, v85, v109
	v_mul_f32_e32 v110, v86, v110
	v_mul_f32_e32 v111, v87, v111
	v_cvt_pk_bf16_f32 v112, v104, v105
	v_cvt_pk_bf16_f32 v113, v106, v107
	v_cvt_pk_bf16_f32 v114, v108, v109
	v_cvt_pk_bf16_f32 v115, v110, v111
	global_store_dwordx4 v27, v[112:115], s[24:25]
	s_add_u32 s24, s24, 0x2800
	s_addc_u32 s25, s25, 0
	global_load_dwordx4 v[68:71], v31, s[12:13] nt
	global_load_dwordx4 v[72:75], v31, s[12:13] offset:16 nt
	global_load_dwordx4 v[76:79], v26, s[96:97] nt
	s_add_u32 s12, s12, 0x1000
	s_addc_u32 s13, s13, 0
	s_add_u32 s96, s96, 0x2800
	s_addc_u32 s97, s97, 0
	s_waitcnt vmcnt(12)
	v_lshlrev_b32_e32 v80, 16, v32
	v_and_b32_e32 v96, 0xffff0000, v32
	v_lshlrev_b32_e32 v81, 16, v33
	v_and_b32_e32 v97, 0xffff0000, v33
	v_lshlrev_b32_e32 v82, 16, v34
	v_and_b32_e32 v98, 0xffff0000, v34
	v_lshlrev_b32_e32 v83, 16, v35
	v_and_b32_e32 v99, 0xffff0000, v35
	v_lshlrev_b32_e32 v84, 16, v36
	v_and_b32_e32 v100, 0xffff0000, v36
	v_lshlrev_b32_e32 v85, 16, v37
	v_and_b32_e32 v101, 0xffff0000, v37
	v_lshlrev_b32_e32 v86, 16, v38
	v_and_b32_e32 v102, 0xffff0000, v38
	v_lshlrev_b32_e32 v87, 16, v39
	v_and_b32_e32 v103, 0xffff0000, v39
	v_lshlrev_b32_e32 v88, 16, v40
	v_and_b32_e32 v89, 0xffff0000, v40
	v_lshlrev_b32_e32 v90, 16, v41
	v_and_b32_e32 v91, 0xffff0000, v41
	v_lshlrev_b32_e32 v92, 16, v42
	v_and_b32_e32 v93, 0xffff0000, v42
	v_lshlrev_b32_e32 v94, 16, v43
	v_and_b32_e32 v95, 0xffff0000, v43
	v_fmac_f32_e32 v80, v96, v18
	v_fmac_f32_e32 v81, v97, v19
	v_fmac_f32_e32 v82, v98, v20
	v_fmac_f32_e32 v83, v99, v21
	v_fmac_f32_e32 v84, v100, v22
	v_fmac_f32_e32 v85, v101, v23
	v_fmac_f32_e32 v86, v102, v24
	v_fmac_f32_e32 v87, v103, v25
	v_mul_f32_e32 v104, 0x3d372713, v88
	v_mul_f32_e32 v105, 0x3d372713, v89
	v_mul_f32_e32 v106, 0x3d372713, v90
	v_mul_f32_e32 v107, 0x3d372713, v91
	v_mul_f32_e32 v108, 0x3d372713, v92
	v_mul_f32_e32 v109, 0x3d372713, v93
	v_mul_f32_e32 v110, 0x3d372713, v94
	v_mul_f32_e32 v111, 0x3d372713, v95
	v_mul_f32_e32 v104, v104, v88
	v_mul_f32_e32 v105, v105, v89
	v_mul_f32_e32 v106, v106, v90
	v_mul_f32_e32 v107, v107, v91
	v_mul_f32_e32 v108, v108, v92
	v_mul_f32_e32 v109, v109, v93
	v_mul_f32_e32 v110, v110, v94
	v_mul_f32_e32 v111, v111, v95
	v_fma_f32 v104, v104, v88, v88
	v_fma_f32 v105, v105, v89, v89
	v_fma_f32 v106, v106, v90, v90
	v_fma_f32 v107, v107, v91, v91
	v_fma_f32 v108, v108, v92, v92
	v_fma_f32 v109, v109, v93, v93
	v_fma_f32 v110, v110, v94, v94
	v_fma_f32 v111, v111, v95, v95
	v_mul_f32_e32 v104, 0x3fcc422a, v104
	v_mul_f32_e32 v105, 0x3fcc422a, v105
	v_mul_f32_e32 v106, 0x3fcc422a, v106
	v_mul_f32_e32 v107, 0x3fcc422a, v107
	v_mul_f32_e32 v108, 0x3fcc422a, v108
	v_mul_f32_e32 v109, 0x3fcc422a, v109
	v_mul_f32_e32 v110, 0x3fcc422a, v110
	v_mul_f32_e32 v111, 0x3fcc422a, v111
	v_mul_f32_e32 v104, 0xbfb8aa3b, v104
	v_mul_f32_e32 v105, 0xbfb8aa3b, v105
	v_mul_f32_e32 v106, 0xbfb8aa3b, v106
	v_mul_f32_e32 v107, 0xbfb8aa3b, v107
	v_mul_f32_e32 v108, 0xbfb8aa3b, v108
	v_mul_f32_e32 v109, 0xbfb8aa3b, v109
	v_mul_f32_e32 v110, 0xbfb8aa3b, v110
	v_mul_f32_e32 v111, 0xbfb8aa3b, v111
	v_exp_f32_e32 v104, v104
	v_exp_f32_e32 v105, v105
	v_exp_f32_e32 v106, v106
	v_exp_f32_e32 v107, v107
	v_exp_f32_e32 v108, v108
	v_exp_f32_e32 v109, v109
	v_exp_f32_e32 v110, v110
	v_exp_f32_e32 v111, v111
	v_add_f32_e32 v104, 1.0, v104
	v_add_f32_e32 v105, 1.0, v105
	v_add_f32_e32 v106, 1.0, v106
	v_add_f32_e32 v107, 1.0, v107
	v_add_f32_e32 v108, 1.0, v108
	v_add_f32_e32 v109, 1.0, v109
	v_add_f32_e32 v110, 1.0, v110
	v_add_f32_e32 v111, 1.0, v111
	v_rcp_f32_e32 v104, v104
	v_rcp_f32_e32 v105, v105
	v_rcp_f32_e32 v106, v106
	v_rcp_f32_e32 v107, v107
	v_rcp_f32_e32 v108, v108
	v_rcp_f32_e32 v109, v109
	v_rcp_f32_e32 v110, v110
	v_rcp_f32_e32 v111, v111
	v_mul_f32_e32 v104, v104, v88
	v_mul_f32_e32 v105, v105, v89
	v_mul_f32_e32 v106, v106, v90
	v_mul_f32_e32 v107, v107, v91
	v_mul_f32_e32 v108, v108, v92
	v_mul_f32_e32 v109, v109, v93
	v_mul_f32_e32 v110, v110, v94
	v_mul_f32_e32 v111, v111, v95
	v_mul_f32_e32 v104, v80, v104
	v_mul_f32_e32 v105, v81, v105
	v_mul_f32_e32 v106, v82, v106
	v_mul_f32_e32 v107, v83, v107
	v_mul_f32_e32 v108, v84, v108
	v_mul_f32_e32 v109, v85, v109
	v_mul_f32_e32 v110, v86, v110
	v_mul_f32_e32 v111, v87, v111
	v_cvt_pk_bf16_f32 v112, v104, v105
	v_cvt_pk_bf16_f32 v113, v106, v107
	v_cvt_pk_bf16_f32 v114, v108, v109
	v_cvt_pk_bf16_f32 v115, v110, v111
	global_store_dwordx4 v27, v[112:115], s[24:25]
	s_add_u32 s24, s24, 0x2800
	s_addc_u32 s25, s25, 0
	s_waitcnt vmcnt(9)
; __device__ __forceinline__ u32x4 pack8(const float (&f)[8]) { u32x4 o; o.x = cvt_pk_bf16(f[0], f[1]); o.y = cvt_pk_bf16(f[2], f[3]); o.z = cvt_pk_bf16(f[4], f[5]); o.w = cvt_pk_bf16(f[6], f[7]); return o; }
; __device__ __forceinline__ float gelu_tanh(float x) { return x * sigmoidf_(1.5957691216057308f * (x + 0.044715f * x * x * x)); }
; __device__ __forceinline__ void fixup_phase(KP p, int l) {
;     ...
;         for (int i = 0; i < 16; ++i) {
;             const size_t m = (size_t)(m0 + i);
;             float hl[8], pc[8], gr[8], o[8], h[8];
;             unpack8(__builtin_nontemporal_load((const u32x4*)(HLOC + m * D + c0)), hl); unpack8(__builtin_nontemporal_load((const u32x4*)(PCUM + m * D + c0)), pc);
;             bf16_t* gp = P + m * DP + C_GR + c0; unpack8(*(const u32x4*)gp, gr);
; #pragma unroll
;             for (int e = 0; e < 8; ++e) { h[e] = hl[e] + pc[e] * carry[e]; o[e] = gelu_tanh(gr[e]) * h[e]; }
;             *(u32x4*)gp = pack8(o);
	v_lshlrev_b32_e32 v80, 16, v44
	v_and_b32_e32 v96, 0xffff0000, v44
	v_lshlrev_b32_e32 v81, 16, v45
	v_and_b32_e32 v97, 0xffff0000, v45
	v_lshlrev_b32_e32 v82, 16, v46
	v_and_b32_e32 v98, 0xffff0000, v46
	v_lshlrev_b32_e32 v83, 16, v47
	v_and_b32_e32 v99, 0xffff0000, v47
	v_lshlrev_b32_e32 v84, 16, v48
	v_and_b32_e32 v100, 0xffff0000, v48
	v_lshlrev_b32_e32 v85, 16, v49
	v_and_b32_e32 v101, 0xffff0000, v49
	v_lshlrev_b32_e32 v86, 16, v50
	v_and_b32_e32 v102, 0xffff0000, v50
	v_lshlrev_b32_e32 v87, 16, v51
	v_and_b32_e32 v103, 0xffff0000, v51
	v_lshlrev_b32_e32 v88, 16, v52
	v_and_b32_e32 v89, 0xffff0000, v52
	v_lshlrev_b32_e32 v90, 16, v53
	v_and_b32_e32 v91, 0xffff0000, v53
	v_lshlrev_b32_e32 v92, 16, v54
	v_and_b32_e32 v93, 0xffff0000, v54
	v_lshlrev_b32_e32 v94, 16, v55
	v_and_b32_e32 v95, 0xffff0000, v55
	v_fmac_f32_e32 v80, v96, v18
	v_fmac_f32_e32 v81, v97, v19
	v_fmac_f32_e32 v82, v98, v20
	v_fmac_f32_e32 v83, v99, v21
	v_fmac_f32_e32 v84, v100, v22
	v_fmac_f32_e32 v85, v101, v23
	v_fmac_f32_e32 v86, v102, v24
	v_fmac_f32_e32 v87, v103, v25
	v_mul_f32_e32 v104, 0x3d372713, v88
	v_mul_f32_e32 v105, 0x3d372713, v89
	v_mul_f32_e32 v106, 0x3d372713, v90
	v_mul_f32_e32 v107, 0x3d372713, v91
	v_mul_f32_e32 v108, 0x3d372713, v92
	v_mul_f32_e32 v109, 0x3d372713, v93
	v_mul_f32_e32 v110, 0x3d372713, v94
	v_mul_f32_e32 v111, 0x3d372713, v95
	v_mul_f32_e32 v104, v104, v88
	v_mul_f32_e32 v105, v105, v89
	v_mul_f32_e32 v106, v106, v90
	v_mul_f32_e32 v107, v107, v91
	v_mul_f32_e32 v108, v108, v92
	v_mul_f32_e32 v109, v109, v93
	v_mul_f32_e32 v110, v110, v94
	v_mul_f32_e32 v111, v111, v95
	v_fma_f32 v104, v104, v88, v88
	v_fma_f32 v105, v105, v89, v89
	v_fma_f32 v106, v106, v90, v90
	v_fma_f32 v107, v107, v91, v91
	v_fma_f32 v108, v108, v92, v92
	v_fma_f32 v109, v109, v93, v93
	v_fma_f32 v110, v110, v94, v94
	v_fma_f32 v111, v111, v95, v95
	v_mul_f32_e32 v104, 0x3fcc422a, v104
	v_mul_f32_e32 v105, 0x3fcc422a, v105
	v_mul_f32_e32 v106, 0x3fcc422a, v106
	v_mul_f32_e32 v107, 0x3fcc422a, v107
	v_mul_f32_e32 v108, 0x3fcc422a, v108
	v_mul_f32_e32 v109, 0x3fcc422a, v109
	v_mul_f32_e32 v110, 0x3fcc422a, v110
	v_mul_f32_e32 v111, 0x3fcc422a, v111
	v_mul_f32_e32 v104, 0xbfb8aa3b, v104
	v_mul_f32_e32 v105, 0xbfb8aa3b, v105
	v_mul_f32_e32 v106, 0xbfb8aa3b, v106
	v_mul_f32_e32 v107, 0xbfb8aa3b, v107
	v_mul_f32_e32 v108, 0xbfb8aa3b, v108
	v_mul_f32_e32 v109, 0xbfb8aa3b, v109
	v_mul_f32_e32 v110, 0xbfb8aa3b, v110
	v_mul_f32_e32 v111, 0xbfb8aa3b, v111
	v_exp_f32_e32 v104, v104
	v_exp_f32_e32 v105, v105
	v_exp_f32_e32 v106, v106
	v_exp_f32_e32 v107, v107
	v_exp_f32_e32 v108, v108
	v_exp_f32_e32 v109, v109
	v_exp_f32_e32 v110, v110
	v_exp_f32_e32 v111, v111
	v_add_f32_e32 v104, 1.0, v104
	v_add_f32_e32 v105, 1.0, v105
	v_add_f32_e32 v106, 1.0, v106
	v_add_f32_e32 v107, 1.0, v107
	v_add_f32_e32 v108, 1.0, v108
	v_add_f32_e32 v109, 1.0, v109
	v_add_f32_e32 v110, 1.0, v110
	v_add_f32_e32 v111, 1.0, v111
	v_rcp_f32_e32 v104, v104
	v_rcp_f32_e32 v105, v105
	v_rcp_f32_e32 v106, v106
	v_rcp_f32_e32 v107, v107
	v_rcp_f32_e32 v108, v108
	v_rcp_f32_e32 v109, v109
	v_rcp_f32_e32 v110, v110
	v_rcp_f32_e32 v111, v111
	v_mul_f32_e32 v104, v104, v88
	v_mul_f32_e32 v105, v105, v89
	v_mul_f32_e32 v106, v106, v90
	v_mul_f32_e32 v107, v107, v91
	v_mul_f32_e32 v108, v108, v92
	v_mul_f32_e32 v109, v109, v93
	v_mul_f32_e32 v110, v110, v94
	v_mul_f32_e32 v111, v111, v95
	v_mul_f32_e32 v104, v80, v104
	v_mul_f32_e32 v105, v81, v105
	v_mul_f32_e32 v106, v82, v106
	v_mul_f32_e32 v107, v83, v107
	v_mul_f32_e32 v108, v84, v108
	v_mul_f32_e32 v109, v85, v109
	v_mul_f32_e32 v110, v86, v110
	v_mul_f32_e32 v111, v87, v111
	v_cvt_pk_bf16_f32 v112, v104, v105
	v_cvt_pk_bf16_f32 v113, v106, v107
	v_cvt_pk_bf16_f32 v114, v108, v109
	v_cvt_pk_bf16_f32 v115, v110, v111
	global_store_dwordx4 v27, v[112:115], s[24:25]
	s_add_u32 s24, s24, 0x2800
	s_addc_u32 s25, s25, 0
	s_waitcnt vmcnt(6)
	v_lshlrev_b32_e32 v80, 16, v56
	v_and_b32_e32 v96, 0xffff0000, v56
	v_lshlrev_b32_e32 v81, 16, v57
	v_and_b32_e32 v97, 0xffff0000, v57
	v_lshlrev_b32_e32 v82, 16, v58
	v_and_b32_e32 v98, 0xffff0000, v58
	v_lshlrev_b32_e32 v83, 16, v59
	v_and_b32_e32 v99, 0xffff0000, v59
	v_lshlrev_b32_e32 v84, 16, v60
	v_and_b32_e32 v100, 0xffff0000, v60
	v_lshlrev_b32_e32 v85, 16, v61
	v_and_b32_e32 v101, 0xffff0000, v61
	v_lshlrev_b32_e32 v86, 16, v62
	v_and_b32_e32 v102, 0xffff0000, v62
	v_lshlrev_b32_e32 v87, 16, v63
	v_and_b32_e32 v103, 0xffff0000, v63
	v_lshlrev_b32_e32 v88, 16, v64
	v_and_b32_e32 v89, 0xffff0000, v64
	v_lshlrev_b32_e32 v90, 16, v65
	v_and_b32_e32 v91, 0xffff0000, v65
	v_lshlrev_b32_e32 v92, 16, v66
	v_and_b32_e32 v93, 0xffff0000, v66
	v_lshlrev_b32_e32 v94, 16, v67
	v_and_b32_e32 v95, 0xffff0000, v67
	v_fmac_f32_e32 v80, v96, v18
	v_fmac_f32_e32 v81, v97, v19
	v_fmac_f32_e32 v82, v98, v20
	v_fmac_f32_e32 v83, v99, v21
	v_fmac_f32_e32 v84, v100, v22
	v_fmac_f32_e32 v85, v101, v23
	v_fmac_f32_e32 v86, v102, v24
	v_fmac_f32_e32 v87, v103, v25
	v_mul_f32_e32 v104, 0x3d372713, v88
	v_mul_f32_e32 v105, 0x3d372713, v89
	v_mul_f32_e32 v106, 0x3d372713, v90
	v_mul_f32_e32 v107, 0x3d372713, v91
	v_mul_f32_e32 v108, 0x3d372713, v92
	v_mul_f32_e32 v109, 0x3d372713, v93
	v_mul_f32_e32 v110, 0x3d372713, v94
	v_mul_f32_e32 v111, 0x3d372713, v95
	v_mul_f32_e32 v104, v104, v88
	v_mul_f32_e32 v105, v105, v89
	v_mul_f32_e32 v106, v106, v90
	v_mul_f32_e32 v107, v107, v91
	v_mul_f32_e32 v108, v108, v92
	v_mul_f32_e32 v109, v109, v93
	v_mul_f32_e32 v110, v110, v94
	v_mul_f32_e32 v111, v111, v95
	v_fma_f32 v104, v104, v88, v88
	v_fma_f32 v105, v105, v89, v89
	v_fma_f32 v106, v106, v90, v90
	v_fma_f32 v107, v107, v91, v91
; __device__ __forceinline__ u32x4 pack8(const float (&f)[8]) { u32x4 o; o.x = cvt_pk_bf16(f[0], f[1]); o.y = cvt_pk_bf16(f[2], f[3]); o.z = cvt_pk_bf16(f[4], f[5]); o.w = cvt_pk_bf16(f[6], f[7]); return o; }
; __device__ __forceinline__ float gelu_tanh(float x) { return x * sigmoidf_(1.5957691216057308f * (x + 0.044715f * x * x * x)); }
; __device__ __forceinline__ void fixup_phase(KP p, int l) {
;     ...
;         for (int i = 0; i < 16; ++i) {
;             const size_t m = (size_t)(m0 + i);
;             float hl[8], pc[8], gr[8], o[8], h[8];
;             unpack8(__builtin_nontemporal_load((const u32x4*)(HLOC + m * D + c0)), hl); unpack8(__builtin_nontemporal_load((const u32x4*)(PCUM + m * D + c0)), pc);
;             bf16_t* gp = P + m * DP + C_GR + c0; unpack8(*(const u32x4*)gp, gr);
; #pragma unroll
;             for (int e = 0; e < 8; ++e) { h[e] = hl[e] + pc[e] * carry[e]; o[e] = gelu_tanh(gr[e]) * h[e]; }
;             *(u32x4*)gp = pack8(o);
;             if (tile < 1032 && t0 + i == TP - 1) store8f(p->out + O_PRG + (size_t)(l * NB + b) * D + c0, h);
	v_fma_f32 v108, v108, v92, v92
	v_fma_f32 v109, v109, v93, v93
	v_fma_f32 v110, v110, v94, v94
	v_fma_f32 v111, v111, v95, v95
	v_mul_f32_e32 v104, 0x3fcc422a, v104
	v_mul_f32_e32 v105, 0x3fcc422a, v105
	v_mul_f32_e32 v106, 0x3fcc422a, v106
	v_mul_f32_e32 v107, 0x3fcc422a, v107
	v_mul_f32_e32 v108, 0x3fcc422a, v108
	v_mul_f32_e32 v109, 0x3fcc422a, v109
	v_mul_f32_e32 v110, 0x3fcc422a, v110
	v_mul_f32_e32 v111, 0x3fcc422a, v111
	v_mul_f32_e32 v104, 0xbfb8aa3b, v104
	v_mul_f32_e32 v105, 0xbfb8aa3b, v105
	v_mul_f32_e32 v106, 0xbfb8aa3b, v106
	v_mul_f32_e32 v107, 0xbfb8aa3b, v107
	v_mul_f32_e32 v108, 0xbfb8aa3b, v108
	v_mul_f32_e32 v109, 0xbfb8aa3b, v109
	v_mul_f32_e32 v110, 0xbfb8aa3b, v110
	v_mul_f32_e32 v111, 0xbfb8aa3b, v111
	v_exp_f32_e32 v104, v104
	v_exp_f32_e32 v105, v105
	v_exp_f32_e32 v106, v106
	v_exp_f32_e32 v107, v107
	v_exp_f32_e32 v108, v108
	v_exp_f32_e32 v109, v109
	v_exp_f32_e32 v110, v110
	v_exp_f32_e32 v111, v111
	v_add_f32_e32 v104, 1.0, v104
	v_add_f32_e32 v105, 1.0, v105
	v_add_f32_e32 v106, 1.0, v106
	v_add_f32_e32 v107, 1.0, v107
	v_add_f32_e32 v108, 1.0, v108
	v_add_f32_e32 v109, 1.0, v109
	v_add_f32_e32 v110, 1.0, v110
	v_add_f32_e32 v111, 1.0, v111
	v_rcp_f32_e32 v104, v104
	v_rcp_f32_e32 v105, v105
	v_rcp_f32_e32 v106, v106
	v_rcp_f32_e32 v107, v107
	v_rcp_f32_e32 v108, v108
	v_rcp_f32_e32 v109, v109
	v_rcp_f32_e32 v110, v110
	v_rcp_f32_e32 v111, v111
	v_mul_f32_e32 v104, v104, v88
	v_mul_f32_e32 v105, v105, v89
	v_mul_f32_e32 v106, v106, v90
	v_mul_f32_e32 v107, v107, v91
	v_mul_f32_e32 v108, v108, v92
	v_mul_f32_e32 v109, v109, v93
	v_mul_f32_e32 v110, v110, v94
	v_mul_f32_e32 v111, v111, v95
	v_mul_f32_e32 v104, v80, v104
	v_mul_f32_e32 v105, v81, v105
	v_mul_f32_e32 v106, v82, v106
	v_mul_f32_e32 v107, v83, v107
	v_mul_f32_e32 v108, v84, v108
	v_mul_f32_e32 v109, v85, v109
	v_mul_f32_e32 v110, v86, v110
	v_mul_f32_e32 v111, v87, v111
	v_cvt_pk_bf16_f32 v112, v104, v105
	v_cvt_pk_bf16_f32 v113, v106, v107
	v_cvt_pk_bf16_f32 v114, v108, v109
	v_cvt_pk_bf16_f32 v115, v110, v111
	global_store_dwordx4 v27, v[112:115], s[24:25]
	s_add_u32 s24, s24, 0x2800
	s_addc_u32 s25, s25, 0
	s_waitcnt vmcnt(3)
	v_lshlrev_b32_e32 v80, 16, v68
	v_and_b32_e32 v96, 0xffff0000, v68
	v_lshlrev_b32_e32 v81, 16, v69
	v_and_b32_e32 v97, 0xffff0000, v69
	v_lshlrev_b32_e32 v82, 16, v70
	v_and_b32_e32 v98, 0xffff0000, v70
	v_lshlrev_b32_e32 v83, 16, v71
	v_and_b32_e32 v99, 0xffff0000, v71
	v_lshlrev_b32_e32 v84, 16, v72
	v_and_b32_e32 v100, 0xffff0000, v72
	v_lshlrev_b32_e32 v85, 16, v73
	v_and_b32_e32 v101, 0xffff0000, v73
	v_lshlrev_b32_e32 v86, 16, v74
	v_and_b32_e32 v102, 0xffff0000, v74
	v_lshlrev_b32_e32 v87, 16, v75
	v_and_b32_e32 v103, 0xffff0000, v75
	v_lshlrev_b32_e32 v88, 16, v76
	v_and_b32_e32 v89, 0xffff0000, v76
	v_lshlrev_b32_e32 v90, 16, v77
	v_and_b32_e32 v91, 0xffff0000, v77
	v_lshlrev_b32_e32 v92, 16, v78
	v_and_b32_e32 v93, 0xffff0000, v78
	v_lshlrev_b32_e32 v94, 16, v79
	v_and_b32_e32 v95, 0xffff0000, v79
	v_fmac_f32_e32 v80, v96, v18
	v_fmac_f32_e32 v81, v97, v19
	v_fmac_f32_e32 v82, v98, v20
	v_fmac_f32_e32 v83, v99, v21
	v_fmac_f32_e32 v84, v100, v22
	v_fmac_f32_e32 v85, v101, v23
	v_fmac_f32_e32 v86, v102, v24
	v_fmac_f32_e32 v87, v103, v25
	v_mul_f32_e32 v104, 0x3d372713, v88
	v_mul_f32_e32 v105, 0x3d372713, v89
	v_mul_f32_e32 v106, 0x3d372713, v90
	v_mul_f32_e32 v107, 0x3d372713, v91
	v_mul_f32_e32 v108, 0x3d372713, v92
	v_mul_f32_e32 v109, 0x3d372713, v93
	v_mul_f32_e32 v110, 0x3d372713, v94
	v_mul_f32_e32 v111, 0x3d372713, v95
	v_mul_f32_e32 v104, v104, v88
	v_mul_f32_e32 v105, v105, v89
	v_mul_f32_e32 v106, v106, v90
	v_mul_f32_e32 v107, v107, v91
	v_mul_f32_e32 v108, v108, v92
	v_mul_f32_e32 v109, v109, v93
	v_mul_f32_e32 v110, v110, v94
	v_mul_f32_e32 v111, v111, v95
	v_fma_f32 v104, v104, v88, v88
	v_fma_f32 v105, v105, v89, v89
	v_fma_f32 v106, v106, v90, v90
	v_fma_f32 v107, v107, v91, v91
	v_fma_f32 v108, v108, v92, v92
	v_fma_f32 v109, v109, v93, v93
	v_fma_f32 v110, v110, v94, v94
	v_fma_f32 v111, v111, v95, v95
	v_mul_f32_e32 v104, 0x3fcc422a, v104
	v_mul_f32_e32 v105, 0x3fcc422a, v105
	v_mul_f32_e32 v106, 0x3fcc422a, v106
	v_mul_f32_e32 v107, 0x3fcc422a, v107
	v_mul_f32_e32 v108, 0x3fcc422a, v108
	v_mul_f32_e32 v109, 0x3fcc422a, v109
	v_mul_f32_e32 v110, 0x3fcc422a, v110
	v_mul_f32_e32 v111, 0x3fcc422a, v111
	v_mul_f32_e32 v104, 0xbfb8aa3b, v104
	v_mul_f32_e32 v105, 0xbfb8aa3b, v105
	v_mul_f32_e32 v106, 0xbfb8aa3b, v106
	v_mul_f32_e32 v107, 0xbfb8aa3b, v107
	v_mul_f32_e32 v108, 0xbfb8aa3b, v108
	v_mul_f32_e32 v109, 0xbfb8aa3b, v109
	v_mul_f32_e32 v110, 0xbfb8aa3b, v110
	v_mul_f32_e32 v111, 0xbfb8aa3b, v111
	v_exp_f32_e32 v104, v104
	v_exp_f32_e32 v105, v105
	v_exp_f32_e32 v106, v106
	v_exp_f32_e32 v107, v107
	v_exp_f32_e32 v108, v108
	v_exp_f32_e32 v109, v109
	v_exp_f32_e32 v110, v110
	v_exp_f32_e32 v111, v111
	v_add_f32_e32 v104, 1.0, v104
	v_add_f32_e32 v105, 1.0, v105
	v_add_f32_e32 v106, 1.0, v106
	v_add_f32_e32 v107, 1.0, v107
	v_add_f32_e32 v108, 1.0, v108
	v_add_f32_e32 v109, 1.0, v109
	v_add_f32_e32 v110, 1.0, v110
	v_add_f32_e32 v111, 1.0, v111
	v_rcp_f32_e32 v104, v104
	v_rcp_f32_e32 v105, v105
	v_rcp_f32_e32 v106, v106
	v_rcp_f32_e32 v107, v107
	v_rcp_f32_e32 v108, v108
	v_rcp_f32_e32 v109, v109
	v_rcp_f32_e32 v110, v110
	v_rcp_f32_e32 v111, v111
	v_mul_f32_e32 v104, v104, v88
	v_mul_f32_e32 v105, v105, v89
	v_mul_f32_e32 v106, v106, v90
	v_mul_f32_e32 v107, v107, v91
	v_mul_f32_e32 v108, v108, v92
	v_mul_f32_e32 v109, v109, v93
	v_mul_f32_e32 v110, v110, v94
	v_mul_f32_e32 v111, v111, v95
	v_mul_f32_e32 v104, v80, v104
	v_mul_f32_e32 v105, v81, v105
	v_mul_f32_e32 v106, v82, v106
	v_mul_f32_e32 v107, v83, v107
	v_mul_f32_e32 v108, v84, v108
	v_mul_f32_e32 v109, v85, v109
	v_mul_f32_e32 v110, v86, v110
	v_mul_f32_e32 v111, v87, v111
	v_cvt_pk_bf16_f32 v112, v104, v105
	v_cvt_pk_bf16_f32 v113, v106, v107
	v_cvt_pk_bf16_f32 v114, v108, v109
	v_cvt_pk_bf16_f32 v115, v110, v111
	global_store_dwordx4 v27, v[112:115], s[24:25]
	s_cmp_eq_u32 s43, 0
	s_cbranch_scc1 .Lfx_noprg
	s_lshl_b32 s44, s18, 12
	s_lshl_b32 s23, s10, 12
	s_add_i32 s44, s44, s23
	s_add_u32 s98, s72, 0x4120000
	s_addc_u32 s99, s73, 0
	s_add_u32 s98, s98, s44
	s_addc_u32 s99, s99, 0
	global_store_dwordx4 v31, v[80:83], s[98:99]
	global_store_dwordx4 v31, v[84:87], s[98:99] offset:16
